# trailing wave half re-staggers after computing the next unit coordinates (barrier moved from the unit loop back edge to the end of the unit header) in G1 G6 G3a G3b; on top of v37
# baseline (speedup 1.0000x reference)
; #define PG8_STAGEX(rs, bufoff, soff, voff) do { _Pragma("unroll") for (int _i = 0; _i < 2; ++_i) \
;         __builtin_amdgcn_raw_ptr_buffer_load_lds(rs, (LAS unsigned*)(lds + (bufoff) + ldsw + _i * 8192), 16, (voff)[_i], (soff), 0, 0); } while (0)
; #define PG8_LDA(dst, b, h) do { _Pragma("unroll") for (int m = 0; m < 4; ++m) _Pragma("unroll") for (int k = 0; k < 2; ++k) dst[m][k] = *(const LAS bf16x8*)(lds + PG8_SA(b, h) + aoff + m * 2048 + k * 1024); } while (0)
; #define PG8_LDB(dst, b, h) do { _Pragma("unroll") for (int n = 0; n < 2; ++n) _Pragma("unroll") for (int k = 0; k < 2; ++k) dst[n][k] = *(const LAS bf16x8*)(lds + PG8_SB(b, h) + boff + n * 2048 + k * 1024); } while (0)
; #define PG8_WAIT_V(n) asm volatile("s_waitcnt vmcnt(" #n ")" ::: "memory")
; #define PG8_WAIT_L(n) asm volatile("s_waitcnt lgkmcnt(" #n ")" ::: "memory")
; #define PG8_BAR __builtin_amdgcn_s_barrier()
;     ...
;         bool has_next; if constexpr (QV == 2) has_next = S.next_tail(ui + 1, nxt); else has_next = S.next(ui + 1, nxt);
;         const unsigned nA = has_next ? (unsigned)nxt.pm * tstepA + nxt.aoff : cA, nB = has_next ? (unsigned)nxt.pn * tstepB + nxt.boff : cB;
;         if constexpr (QV == 0) {
; #pragma nounroll
;         for (int t = 0; t < nt; t += 2) {
;             const bool last = (t == nt - 2);
;             const unsigned a1 = cA + (unsigned)(t + 1) * kstep;
;             const unsigned a2 = last ? nA : cA + (unsigned)(t + 2) * kstep, b2 = last ? nB : cB + (unsigned)(t + 2) * kstep;
;             const unsigned a3 = a2 + kstep, b3 = b2 + kstep;
;             PG8_LDB(B0, 0, 0); PG8_LDB(B1, 0, 1); PG8_SCHED; PG8_LDA(At, 0, 0); PG8_STAGEX(rsA, PG8_SA(1, 1), a1 + hstepA, voffA);
;             PG8_WAIT_V(8); PG8_WAIT_L(0); PG8_BAR; PG8_MMA(0, 0, At, B0); PG8_MMA(0, 1, At, B1); PG8_BAR; PG8_SCHED;
;     ...
;         if (!cur.keep) {
; #pragma unroll
;             for (int a = 0; a < 2; ++a)
; #pragma unroll
;                 for (int b = 0; b < 2; ++b)
; #pragma unroll
;                     for (int m = 0; m < 4; ++m)
; #pragma unroll
;                         for (int n = 0; n < 2; ++n) { f32x2 z0, z1; asm("v_mov_b64 %0, 0\n\tv_mov_b64 %1, 0" : "=v"(z0), "=v"(z1));
;                     acc[a][b][m][n] = __builtin_shufflevector(z0, z1, 0, 1, 2, 3); }
;         }
;         cur = nxt; cA = nA; cB = nB; ++ui;
;         if (wr == 1) PG8_BAR;
.LBB0_222:
	s_lshl_b32 s28, s27, 20
	s_and_b64 s[30:31], s[38:39], exec
	s_cselect_b32 s30, s28, s50
	s_lshl_b32 s29, s26, 20
	s_and_b64 s[52:53], s[38:39], exec
	v_mov_b64_e32 v[12:13], v[4:5]
	v_mov_b64_e32 v[20:21], v[4:5]
	s_waitcnt vmcnt(15)
	v_mov_b64_e32 v[28:29], v[4:5]
	v_mov_b64_e32 v[36:37], v[4:5]
	v_mov_b64_e32 v[44:45], v[4:5]
	v_mov_b64_e32 v[52:53], v[4:5]
	v_mov_b64_e32 v[60:61], v[4:5]
	v_mov_b64_e32 v[8:9], v[4:5]
	v_mov_b64_e32 v[16:17], v[4:5]
	v_mov_b64_e32 v[24:25], v[4:5]
	v_mov_b64_e32 v[32:33], v[4:5]
	v_mov_b64_e32 v[40:41], v[4:5]
	v_mov_b64_e32 v[48:49], v[4:5]
	v_mov_b64_e32 v[56:57], v[4:5]
	v_mov_b64_e32 v[64:65], v[4:5]
	v_mov_b64_e32 v[68:69], v[4:5]
	v_mov_b64_e32 v[76:77], v[4:5]
	v_mov_b64_e32 v[92:93], v[4:5]
	v_mov_b64_e32 v[108:109], v[4:5]
	v_mov_b64_e32 v[116:117], v[4:5]
	v_mov_b64_e32 v[124:125], v[4:5]
	v_mov_b64_e32 v[132:133], v[4:5]
	v_mov_b64_e32 v[140:141], v[4:5]
	v_mov_b64_e32 v[72:73], v[4:5]
	v_mov_b64_e32 v[80:81], v[4:5]
	v_mov_b64_e32 v[96:97], v[4:5]
	v_mov_b64_e32 v[112:113], v[4:5]
	v_mov_b64_e32 v[120:121], v[4:5]
	v_mov_b64_e32 v[128:129], v[4:5]
	v_mov_b64_e32 v[136:137], v[4:5]
	v_mov_b64_e32 v[144:145], v[4:5]
	s_cselect_b32 s31, s29, s42
	s_add_i32 s50, s50, 0x80080
	s_add_i32 s51, s42, 0x100
	s_mov_b32 s52, -2
	v_mov_b64_e32 v[10:11], v[2:3]
	v_mov_b64_e32 v[18:19], v[2:3]
	v_mov_b64_e32 v[26:27], v[2:3]
	v_mov_b64_e32 v[34:35], v[2:3]
	v_mov_b64_e32 v[42:43], v[2:3]
	v_mov_b64_e32 v[50:51], v[2:3]
	v_mov_b64_e32 v[58:59], v[2:3]
	v_mov_b64_e32 v[6:7], v[2:3]
	v_mov_b64_e32 v[14:15], v[2:3]
	v_mov_b64_e32 v[22:23], v[2:3]
	v_mov_b64_e32 v[30:31], v[2:3]
	v_mov_b64_e32 v[38:39], v[2:3]
	v_mov_b64_e32 v[46:47], v[2:3]
	v_mov_b64_e32 v[54:55], v[2:3]
	v_mov_b64_e32 v[62:63], v[2:3]
	v_mov_b64_e32 v[66:67], v[2:3]
	v_mov_b64_e32 v[74:75], v[2:3]
	v_mov_b64_e32 v[90:91], v[2:3]
	v_mov_b64_e32 v[106:107], v[2:3]
	v_mov_b64_e32 v[114:115], v[2:3]
	v_mov_b64_e32 v[122:123], v[2:3]
	v_mov_b64_e32 v[130:131], v[2:3]
	v_mov_b64_e32 v[138:139], v[2:3]
	v_mov_b64_e32 v[70:71], v[2:3]
	v_mov_b64_e32 v[78:79], v[2:3]
	v_mov_b64_e32 v[94:95], v[2:3]
	v_mov_b64_e32 v[110:111], v[2:3]
	v_mov_b64_e32 v[118:119], v[2:3]
	v_mov_b64_e32 v[126:127], v[2:3]
	v_mov_b64_e32 v[134:135], v[2:3]
	v_mov_b64_e32 v[142:143], v[2:3]
	s_cmp_eq_u32 s25, 1
	s_cbranch_scc1 .Lrst_skip_223
	s_andn2_b64 vcc, exec, s[44:45]
	s_cbranch_vccnz .Lrst_skip_223
	s_barrier
.Lrst_skip_223:
.LBB0_223:
	v_add_u32_e32 v102, 0x10000, v172
	v_add_u32_e32 v146, 0x14000, v172
	ds_read_b128 v[82:85], v102
	ds_read_b128 v[86:89], v102 offset:1024
	ds_read_b128 v[98:101], v102 offset:2048
	ds_read_b128 v[102:105], v102 offset:3072
	ds_read_b128 v[150:153], v146
	ds_read_b128 v[154:157], v146 offset:1024
	ds_read_b128 v[182:185], v146 offset:2048
	ds_read_b128 v[186:189], v146 offset:3072
	s_add_i32 s42, s50, 0xfff80080
	s_cmp_eq_u32 s52, 28
	s_cselect_b32 s55, s30, s42
	s_cselect_b32 s54, s31, s51
	s_or_b32 s53, s55, 0x80
	s_mov_b32 m0, s22
	ds_read_b128 v[190:193], v173
	ds_read_b128 v[194:197], v173 offset:1024
	ds_read_b128 v[198:201], v173 offset:2048
	ds_read_b128 v[202:205], v173 offset:3072
	ds_read_b128 v[206:209], v173 offset:4096
	ds_read_b128 v[210:213], v173 offset:5120
	ds_read_b128 v[214:217], v173 offset:6144
	ds_read_b128 v[218:221], v173 offset:7168
	buffer_load_dwordx4 v159, s[76:79], s50 offen lds
	s_mov_b32 m0, s23
	s_nop 0
	buffer_load_dwordx4 v163, s[76:79], s50 offen lds
	s_waitcnt vmcnt(8)
	s_waitcnt lgkmcnt(0)
	s_setprio 1
	s_barrier
	v_mfma_f32_16x16x32_bf16 v[142:145], v[82:85], v[190:193], v[142:145]
	v_mfma_f32_16x16x32_bf16 v[134:137], v[98:101], v[190:193], v[134:137]
	v_mfma_f32_16x16x32_bf16 v[126:129], v[82:85], v[198:201], v[126:129]
	v_mfma_f32_16x16x32_bf16 v[118:121], v[98:101], v[198:201], v[118:121]
	v_mfma_f32_16x16x32_bf16 v[110:113], v[82:85], v[206:209], v[110:113]
	v_mfma_f32_16x16x32_bf16 v[94:97], v[98:101], v[206:209], v[94:97]
	v_mfma_f32_16x16x32_bf16 v[78:81], v[82:85], v[214:217], v[78:81]
	v_mfma_f32_16x16x32_bf16 v[70:73], v[98:101], v[214:217], v[70:73]
	v_mfma_f32_16x16x32_bf16 v[142:145], v[86:89], v[194:197], v[142:145]
	v_mfma_f32_16x16x32_bf16 v[134:137], v[102:105], v[194:197], v[134:137]
	v_mfma_f32_16x16x32_bf16 v[126:129], v[86:89], v[202:205], v[126:129]
	v_mfma_f32_16x16x32_bf16 v[118:121], v[102:105], v[202:205], v[118:121]
	v_mfma_f32_16x16x32_bf16 v[110:113], v[86:89], v[210:213], v[110:113]
	v_mfma_f32_16x16x32_bf16 v[94:97], v[102:105], v[210:213], v[94:97]
	v_mfma_f32_16x16x32_bf16 v[78:81], v[86:89], v[218:221], v[78:81]
	v_mfma_f32_16x16x32_bf16 v[70:73], v[102:105], v[218:221], v[70:73]
	v_mfma_f32_16x16x32_bf16 v[138:141], v[150:153], v[190:193], v[138:141]
	v_mfma_f32_16x16x32_bf16 v[130:133], v[182:185], v[190:193], v[130:133]
	v_mfma_f32_16x16x32_bf16 v[122:125], v[150:153], v[198:201], v[122:125]
	v_mfma_f32_16x16x32_bf16 v[114:117], v[182:185], v[198:201], v[114:117]
	v_mfma_f32_16x16x32_bf16 v[106:109], v[150:153], v[206:209], v[106:109]
	v_mfma_f32_16x16x32_bf16 v[90:93], v[182:185], v[206:209], v[90:93]
	v_mfma_f32_16x16x32_bf16 v[74:77], v[150:153], v[214:217], v[74:77]
	v_mfma_f32_16x16x32_bf16 v[66:69], v[182:185], v[214:217], v[66:69]
	v_mfma_f32_16x16x32_bf16 v[138:141], v[154:157], v[194:197], v[138:141]
	v_mfma_f32_16x16x32_bf16 v[130:133], v[186:189], v[194:197], v[130:133]
	v_mfma_f32_16x16x32_bf16 v[122:125], v[154:157], v[202:205], v[122:125]
	v_mfma_f32_16x16x32_bf16 v[114:117], v[186:189], v[202:205], v[114:117]
	v_mfma_f32_16x16x32_bf16 v[106:109], v[154:157], v[210:213], v[106:109]
	v_mfma_f32_16x16x32_bf16 v[90:93], v[186:189], v[210:213], v[90:93]
	v_mfma_f32_16x16x32_bf16 v[74:77], v[154:157], v[218:221], v[74:77]
	v_mfma_f32_16x16x32_bf16 v[66:69], v[186:189], v[218:221], v[66:69]
	s_barrier
; #define PG8_STAGEX(rs, bufoff, soff, voff) do { _Pragma("unroll") for (int _i = 0; _i < 2; ++_i) \
;         __builtin_amdgcn_raw_ptr_buffer_load_lds(rs, (LAS unsigned*)(lds + (bufoff) + ldsw + _i * 8192), 16, (voff)[_i], (soff), 0, 0); } while (0)
; #define PG8_LDA(dst, b, h) do { _Pragma("unroll") for (int m = 0; m < 4; ++m) _Pragma("unroll") for (int k = 0; k < 2; ++k) dst[m][k] = *(const LAS bf16x8*)(lds + PG8_SA(b, h) + aoff + m * 2048 + k * 1024); } while (0)
; #define PG8_LDB(dst, b, h) do { _Pragma("unroll") for (int n = 0; n < 2; ++n) _Pragma("unroll") for (int k = 0; k < 2; ++k) dst[n][k] = *(const LAS bf16x8*)(lds + PG8_SB(b, h) + boff + n * 2048 + k * 1024); } while (0)
; #define PG8_WAIT_V(n) asm volatile("s_waitcnt vmcnt(" #n ")" ::: "memory")
; #define PG8_WAIT_L(n) asm volatile("s_waitcnt lgkmcnt(" #n ")" ::: "memory")
; #define PG8_BAR __builtin_amdgcn_s_barrier()
; #define PG8_SCHED __builtin_amdgcn_sched_barrier(0)
;     ...
;             PG8_LDB(B0, 0, 0); PG8_LDB(B1, 0, 1); PG8_SCHED; PG8_LDA(At, 0, 0); PG8_STAGEX(rsA, PG8_SA(1, 1), a1 + hstepA, voffA);
;             PG8_WAIT_V(8); PG8_WAIT_L(0); PG8_BAR; PG8_MMA(0, 0, At, B0); PG8_MMA(0, 1, At, B1); PG8_BAR; PG8_SCHED;
;             PG8_LDA(At, 0, 1); PG8_STAGEX(rsB, PG8_SB(0, 0), b2, voffB); PG8_STAGEX(rsB, PG8_SB(0, 1), b2 + hstepB, voffB); PG8_STAGEX(rsA, PG8_SA(0, 0), a2, voffA);
;             PG8_WAIT_V(8); PG8_WAIT_L(0); PG8_BAR; PG8_MMA(1, 0, At, B0); PG8_MMA(1, 1, At, B1); PG8_BAR; PG8_SCHED;
;             PG8_LDB(B0, 1, 0); PG8_LDB(B1, 1, 1); PG8_SCHED; PG8_LDA(At, 1, 0); PG8_STAGEX(rsA, PG8_SA(0, 1), a2 + hstepA, voffA);
;             PG8_WAIT_V(8); PG8_WAIT_L(0); PG8_BAR; PG8_MMA(0, 0, At, B0); PG8_MMA(0, 1, At, B1); PG8_BAR; PG8_SCHED;
;             PG8_LDA(At, 1, 1); PG8_STAGEX(rsB, PG8_SB(1, 0), b3, voffB); PG8_STAGEX(rsB, PG8_SB(1, 1), b3 + hstepB, voffB); PG8_STAGEX(rsA, PG8_SA(1, 0), a3, voffA);
;             PG8_WAIT_V(8); PG8_WAIT_L(0); PG8_BAR; PG8_MMA(1, 0, At, B0); PG8_MMA(1, 1, At, B1); PG8_BAR; PG8_SCHED;
	s_setprio 0
	s_mov_b32 m0, s9
	s_mov_b32 s42, s78
	s_mov_b32 s43, s79
	ds_read_b128 v[190:193], v173 offset:16384
	ds_read_b128 v[194:197], v173 offset:17408
	ds_read_b128 v[198:201], v173 offset:18432
	ds_read_b128 v[202:205], v173 offset:19456
	ds_read_b128 v[206:209], v173 offset:20480
	ds_read_b128 v[210:213], v173 offset:21504
	ds_read_b128 v[214:217], v173 offset:22528
	ds_read_b128 v[218:221], v173 offset:23552
	buffer_load_dwordx4 v161, s[40:43], s54 offen lds
	s_mov_b32 m0, s10
	s_add_i32 s56, s54, 0x80000
	buffer_load_dwordx4 v165, s[40:43], s54 offen lds
	s_mov_b32 m0, s11
	s_nop 0
	buffer_load_dwordx4 v161, s[40:43], s56 offen lds
	s_mov_b32 m0, s12
	s_nop 0
	buffer_load_dwordx4 v165, s[40:43], s56 offen lds
	s_mov_b32 m0, s8
	s_nop 0
	buffer_load_dwordx4 v159, s[76:79], s55 offen lds
	s_mov_b32 m0, s13
	s_nop 0
	buffer_load_dwordx4 v163, s[76:79], s55 offen lds
	s_waitcnt vmcnt(8)
	s_waitcnt lgkmcnt(0)
	s_setprio 1
	s_barrier
	v_mfma_f32_16x16x32_bf16 v[62:65], v[82:85], v[190:193], v[62:65]
	v_mfma_f32_16x16x32_bf16 v[54:57], v[98:101], v[190:193], v[54:57]
	v_mfma_f32_16x16x32_bf16 v[46:49], v[82:85], v[198:201], v[46:49]
	v_mfma_f32_16x16x32_bf16 v[38:41], v[98:101], v[198:201], v[38:41]
	v_mfma_f32_16x16x32_bf16 v[30:33], v[82:85], v[206:209], v[30:33]
	v_mfma_f32_16x16x32_bf16 v[22:25], v[98:101], v[206:209], v[22:25]
	v_mfma_f32_16x16x32_bf16 v[14:17], v[82:85], v[214:217], v[14:17]
	v_mfma_f32_16x16x32_bf16 v[6:9], v[98:101], v[214:217], v[6:9]
	v_mfma_f32_16x16x32_bf16 v[62:65], v[86:89], v[194:197], v[62:65]
	v_mfma_f32_16x16x32_bf16 v[54:57], v[102:105], v[194:197], v[54:57]
	v_mfma_f32_16x16x32_bf16 v[46:49], v[86:89], v[202:205], v[46:49]
	v_mfma_f32_16x16x32_bf16 v[38:41], v[102:105], v[202:205], v[38:41]
	v_mfma_f32_16x16x32_bf16 v[30:33], v[86:89], v[210:213], v[30:33]
	v_mfma_f32_16x16x32_bf16 v[22:25], v[102:105], v[210:213], v[22:25]
	v_mfma_f32_16x16x32_bf16 v[14:17], v[86:89], v[218:221], v[14:17]
	v_mfma_f32_16x16x32_bf16 v[6:9], v[102:105], v[218:221], v[6:9]
	v_mfma_f32_16x16x32_bf16 v[58:61], v[150:153], v[190:193], v[58:61]
	v_mfma_f32_16x16x32_bf16 v[50:53], v[182:185], v[190:193], v[50:53]
	v_mfma_f32_16x16x32_bf16 v[42:45], v[150:153], v[198:201], v[42:45]
	v_mfma_f32_16x16x32_bf16 v[34:37], v[182:185], v[198:201], v[34:37]
	v_mfma_f32_16x16x32_bf16 v[26:29], v[150:153], v[206:209], v[26:29]
	v_mfma_f32_16x16x32_bf16 v[18:21], v[182:185], v[206:209], v[18:21]
	v_mfma_f32_16x16x32_bf16 v[10:13], v[150:153], v[214:217], v[10:13]
	v_mfma_f32_16x16x32_bf16 v[2:5], v[182:185], v[214:217], v[2:5]
	v_mfma_f32_16x16x32_bf16 v[58:61], v[154:157], v[194:197], v[58:61]
	v_mfma_f32_16x16x32_bf16 v[50:53], v[186:189], v[194:197], v[50:53]
	v_mfma_f32_16x16x32_bf16 v[42:45], v[154:157], v[202:205], v[42:45]
	v_mfma_f32_16x16x32_bf16 v[34:37], v[186:189], v[202:205], v[34:37]
	v_mfma_f32_16x16x32_bf16 v[26:29], v[154:157], v[210:213], v[26:29]
	v_mfma_f32_16x16x32_bf16 v[18:21], v[186:189], v[210:213], v[18:21]
	v_mfma_f32_16x16x32_bf16 v[10:13], v[154:157], v[218:221], v[10:13]
	v_mfma_f32_16x16x32_bf16 v[2:5], v[186:189], v[218:221], v[2:5]
	s_barrier
	s_setprio 0
	v_add_u32_e32 v102, 0x18000, v172
	v_add_u32_e32 v146, 0x1c000, v172
	ds_read_b128 v[82:85], v102
	ds_read_b128 v[86:89], v102 offset:1024
	ds_read_b128 v[98:101], v102 offset:2048
	ds_read_b128 v[102:105], v102 offset:3072
	ds_read_b128 v[150:153], v146
	ds_read_b128 v[154:157], v146 offset:1024
	ds_read_b128 v[182:185], v146 offset:2048
	ds_read_b128 v[186:189], v146 offset:3072
	s_add_i32 s55, s55, 0x80000
	s_mov_b32 m0, s14
	ds_read_b128 v[190:193], v173 offset:32768
	ds_read_b128 v[194:197], v173 offset:33792
	ds_read_b128 v[198:201], v173 offset:34816
	ds_read_b128 v[202:205], v173 offset:35840
	ds_read_b128 v[206:209], v173 offset:36864
	ds_read_b128 v[210:213], v173 offset:37888
	ds_read_b128 v[214:217], v173 offset:38912
	ds_read_b128 v[218:221], v173 offset:39936
	buffer_load_dwordx4 v159, s[76:79], s55 offen lds
	s_mov_b32 m0, s15
	s_nop 0
	buffer_load_dwordx4 v163, s[76:79], s55 offen lds
	s_waitcnt vmcnt(8)
	s_waitcnt lgkmcnt(0)
	s_setprio 1
	s_barrier
; #define PG8_STAGEX(rs, bufoff, soff, voff) do { _Pragma("unroll") for (int _i = 0; _i < 2; ++_i) \
;         __builtin_amdgcn_raw_ptr_buffer_load_lds(rs, (LAS unsigned*)(lds + (bufoff) + ldsw + _i * 8192), 16, (voff)[_i], (soff), 0, 0); } while (0)
; #define PG8_LDA(dst, b, h) do { _Pragma("unroll") for (int m = 0; m < 4; ++m) _Pragma("unroll") for (int k = 0; k < 2; ++k) dst[m][k] = *(const LAS bf16x8*)(lds + PG8_SA(b, h) + aoff + m * 2048 + k * 1024); } while (0)
; #define PG8_LDB(dst, b, h) do { _Pragma("unroll") for (int n = 0; n < 2; ++n) _Pragma("unroll") for (int k = 0; k < 2; ++k) dst[n][k] = *(const LAS bf16x8*)(lds + PG8_SB(b, h) + boff + n * 2048 + k * 1024); } while (0)
; #define PG8_WAIT_V(n) asm volatile("s_waitcnt vmcnt(" #n ")" ::: "memory")
; #define PG8_WAIT_L(n) asm volatile("s_waitcnt lgkmcnt(" #n ")" ::: "memory")
; #define PG8_BAR __builtin_amdgcn_s_barrier()
; #define PG8_SCHED __builtin_amdgcn_sched_barrier(0)
;     ...
;             PG8_LDB(B0, 1, 0); PG8_LDB(B1, 1, 1); PG8_SCHED; PG8_LDA(At, 1, 0); PG8_STAGEX(rsA, PG8_SA(0, 1), a2 + hstepA, voffA);
;             PG8_WAIT_V(8); PG8_WAIT_L(0); PG8_BAR; PG8_MMA(0, 0, At, B0); PG8_MMA(0, 1, At, B1); PG8_BAR; PG8_SCHED;
;             PG8_LDA(At, 1, 1); PG8_STAGEX(rsB, PG8_SB(1, 0), b3, voffB); PG8_STAGEX(rsB, PG8_SB(1, 1), b3 + hstepB, voffB); PG8_STAGEX(rsA, PG8_SA(1, 0), a3, voffA);
;             PG8_WAIT_V(8); PG8_WAIT_L(0); PG8_BAR; PG8_MMA(1, 0, At, B0); PG8_MMA(1, 1, At, B1); PG8_BAR; PG8_SCHED;
;     ...
;         if (wr == 0) PG8_BAR;
	v_mfma_f32_16x16x32_bf16 v[142:145], v[82:85], v[190:193], v[142:145]
	v_mfma_f32_16x16x32_bf16 v[134:137], v[98:101], v[190:193], v[134:137]
	v_mfma_f32_16x16x32_bf16 v[126:129], v[82:85], v[198:201], v[126:129]
	v_mfma_f32_16x16x32_bf16 v[118:121], v[98:101], v[198:201], v[118:121]
	v_mfma_f32_16x16x32_bf16 v[110:113], v[82:85], v[206:209], v[110:113]
	v_mfma_f32_16x16x32_bf16 v[94:97], v[98:101], v[206:209], v[94:97]
	v_mfma_f32_16x16x32_bf16 v[78:81], v[82:85], v[214:217], v[78:81]
	v_mfma_f32_16x16x32_bf16 v[70:73], v[98:101], v[214:217], v[70:73]
	v_mfma_f32_16x16x32_bf16 v[142:145], v[86:89], v[194:197], v[142:145]
	v_mfma_f32_16x16x32_bf16 v[134:137], v[102:105], v[194:197], v[134:137]
	v_mfma_f32_16x16x32_bf16 v[126:129], v[86:89], v[202:205], v[126:129]
	v_mfma_f32_16x16x32_bf16 v[118:121], v[102:105], v[202:205], v[118:121]
	v_mfma_f32_16x16x32_bf16 v[110:113], v[86:89], v[210:213], v[110:113]
	v_mfma_f32_16x16x32_bf16 v[94:97], v[102:105], v[210:213], v[94:97]
	v_mfma_f32_16x16x32_bf16 v[78:81], v[86:89], v[218:221], v[78:81]
	v_mfma_f32_16x16x32_bf16 v[70:73], v[102:105], v[218:221], v[70:73]
	v_mfma_f32_16x16x32_bf16 v[138:141], v[150:153], v[190:193], v[138:141]
	v_mfma_f32_16x16x32_bf16 v[130:133], v[182:185], v[190:193], v[130:133]
	v_mfma_f32_16x16x32_bf16 v[122:125], v[150:153], v[198:201], v[122:125]
	v_mfma_f32_16x16x32_bf16 v[114:117], v[182:185], v[198:201], v[114:117]
	v_mfma_f32_16x16x32_bf16 v[106:109], v[150:153], v[206:209], v[106:109]
	v_mfma_f32_16x16x32_bf16 v[90:93], v[182:185], v[206:209], v[90:93]
	v_mfma_f32_16x16x32_bf16 v[74:77], v[150:153], v[214:217], v[74:77]
	v_mfma_f32_16x16x32_bf16 v[66:69], v[182:185], v[214:217], v[66:69]
	v_mfma_f32_16x16x32_bf16 v[138:141], v[154:157], v[194:197], v[138:141]
	v_mfma_f32_16x16x32_bf16 v[130:133], v[186:189], v[194:197], v[130:133]
	v_mfma_f32_16x16x32_bf16 v[122:125], v[154:157], v[202:205], v[122:125]
	v_mfma_f32_16x16x32_bf16 v[114:117], v[186:189], v[202:205], v[114:117]
	v_mfma_f32_16x16x32_bf16 v[106:109], v[154:157], v[210:213], v[106:109]
	v_mfma_f32_16x16x32_bf16 v[90:93], v[186:189], v[210:213], v[90:93]
	v_mfma_f32_16x16x32_bf16 v[74:77], v[154:157], v[218:221], v[74:77]
	v_mfma_f32_16x16x32_bf16 v[66:69], v[186:189], v[218:221], v[66:69]
	s_barrier
	s_setprio 0
	s_mov_b32 m0, s16
	s_or_b32 s55, s54, 0x80
	ds_read_b128 v[190:193], v173 offset:49152
	ds_read_b128 v[194:197], v173 offset:50176
	ds_read_b128 v[198:201], v173 offset:51200
	ds_read_b128 v[202:205], v173 offset:52224
	ds_read_b128 v[206:209], v173 offset:53248
	ds_read_b128 v[210:213], v173 offset:54272
	ds_read_b128 v[214:217], v173 offset:55296
	ds_read_b128 v[218:221], v173 offset:56320
	buffer_load_dwordx4 v161, s[40:43], s55 offen lds
	s_mov_b32 m0, s17
	s_add_i32 s54, s54, 0x80080
	buffer_load_dwordx4 v165, s[40:43], s55 offen lds
	s_mov_b32 m0, s20
	s_nop 0
	buffer_load_dwordx4 v161, s[40:43], s54 offen lds
	s_mov_b32 m0, s21
	s_nop 0
	buffer_load_dwordx4 v165, s[40:43], s54 offen lds
	s_mov_b32 m0, s18
	s_nop 0
	buffer_load_dwordx4 v159, s[76:79], s53 offen lds
	s_mov_b32 m0, s19
	s_nop 0
	buffer_load_dwordx4 v163, s[76:79], s53 offen lds
	s_waitcnt vmcnt(8)
	s_waitcnt lgkmcnt(0)
	s_setprio 1
	s_barrier
	v_mfma_f32_16x16x32_bf16 v[62:65], v[82:85], v[190:193], v[62:65]
	v_mfma_f32_16x16x32_bf16 v[54:57], v[98:101], v[190:193], v[54:57]
	v_mfma_f32_16x16x32_bf16 v[46:49], v[82:85], v[198:201], v[46:49]
	v_mfma_f32_16x16x32_bf16 v[38:41], v[98:101], v[198:201], v[38:41]
	v_mfma_f32_16x16x32_bf16 v[30:33], v[82:85], v[206:209], v[30:33]
	v_mfma_f32_16x16x32_bf16 v[22:25], v[98:101], v[206:209], v[22:25]
	v_mfma_f32_16x16x32_bf16 v[14:17], v[82:85], v[214:217], v[14:17]
	v_mfma_f32_16x16x32_bf16 v[6:9], v[98:101], v[214:217], v[6:9]
	v_mfma_f32_16x16x32_bf16 v[62:65], v[86:89], v[194:197], v[62:65]
	v_mfma_f32_16x16x32_bf16 v[54:57], v[102:105], v[194:197], v[54:57]
	v_mfma_f32_16x16x32_bf16 v[46:49], v[86:89], v[202:205], v[46:49]
	v_mfma_f32_16x16x32_bf16 v[38:41], v[102:105], v[202:205], v[38:41]
	v_mfma_f32_16x16x32_bf16 v[30:33], v[86:89], v[210:213], v[30:33]
	v_mfma_f32_16x16x32_bf16 v[22:25], v[102:105], v[210:213], v[22:25]
	v_mfma_f32_16x16x32_bf16 v[14:17], v[86:89], v[218:221], v[14:17]
	v_mfma_f32_16x16x32_bf16 v[6:9], v[102:105], v[218:221], v[6:9]
	v_mfma_f32_16x16x32_bf16 v[58:61], v[150:153], v[190:193], v[58:61]
	v_mfma_f32_16x16x32_bf16 v[50:53], v[182:185], v[190:193], v[50:53]
	v_mfma_f32_16x16x32_bf16 v[42:45], v[150:153], v[198:201], v[42:45]
	v_mfma_f32_16x16x32_bf16 v[34:37], v[182:185], v[198:201], v[34:37]
	v_mfma_f32_16x16x32_bf16 v[26:29], v[150:153], v[206:209], v[26:29]
	v_mfma_f32_16x16x32_bf16 v[18:21], v[182:185], v[206:209], v[18:21]
	v_mfma_f32_16x16x32_bf16 v[10:13], v[150:153], v[214:217], v[10:13]
	v_mfma_f32_16x16x32_bf16 v[2:5], v[182:185], v[214:217], v[2:5]
	v_mfma_f32_16x16x32_bf16 v[58:61], v[154:157], v[194:197], v[58:61]
	v_mfma_f32_16x16x32_bf16 v[50:53], v[186:189], v[194:197], v[50:53]
	v_mfma_f32_16x16x32_bf16 v[42:45], v[154:157], v[202:205], v[42:45]
	v_mfma_f32_16x16x32_bf16 v[34:37], v[186:189], v[202:205], v[34:37]
	v_mfma_f32_16x16x32_bf16 v[26:29], v[154:157], v[210:213], v[26:29]
	v_mfma_f32_16x16x32_bf16 v[18:21], v[186:189], v[210:213], v[18:21]
	v_mfma_f32_16x16x32_bf16 v[10:13], v[154:157], v[218:221], v[10:13]
	v_mfma_f32_16x16x32_bf16 v[2:5], v[186:189], v[218:221], v[2:5]
	s_barrier
	s_setprio 0
	s_add_i32 s52, s52, 2
	s_addk_i32 s50, 0x100
	s_addk_i32 s51, 0x100
	s_cmp_gt_u32 s52, 29
	s_cbranch_scc0 .LBB0_223
	s_and_b64 vcc, exec, s[46:47]
	s_cbranch_vccz .LBB0_226
	s_barrier

; __device__ __forceinline__ void row_rstd(const unsigned long long* ssq, int row0, float (&rs)[2][4]) {
;     unsigned long long q[2][4];
; #pragma unroll
;     for (int ai = 0; ai < 2; ++ai)
; #pragma unroll
;         for (int m = 0; m < 4; ++m) q[ai][m] = ssq[row0 + ai * HALF + m * 16];
;     asm volatile("" : "+v"(q[0][0]), "+v"(q[0][1]), "+v"(q[0][2]), "+v"(q[0][3]), "+v"(q[1][0]), "+v"(q[1][1]), "+v"(q[1][2]), "+v"(q[1][3]));
; #pragma unroll
;     for (int ai = 0; ai < 2; ++ai)
; #pragma unroll
;         for (int m = 0; m < 4; ++m) {
;             const float qf = __builtin_fmaf((float)(unsigned)(q[ai][m] >> 32), 4294967296.0f, (float)(unsigned)q[ai][m]);
;             rs[ai][m] = __builtin_amdgcn_rsqf(__builtin_fmaf(qf, 1.0f / (SSQ_SCALE * DM), EPS)); }
; }
;     template <int QVV> __device__ __forceinline__ void run(f32x4 (&acc)[2][2][4][2], const Unit& u, int wr, int wc, int fr, int fq) const {
;         constexpr int nai = (QVV == 2) ? 1 : 2; const int r0 = u.pm * BM + (QVV == 2 ? (u.seg - 1) * HALF : 0);
;         char* tb = (char*)(O + (size_t)r0 * DFF + u.pn * HALF);
;         const int v = u.pm < 4 ? 4 : ((u.pm - 4) >> 5);
;         const char* swb = (const char*)(sw + (size_t)v * SWLD + u.pn * BM);
;         unsigned lo = (unsigned)((wr * 64 + fr) * DFF + wc * 32 + 8 * fq) * 2u;
;         unsigned co = (unsigned)(wc * 32 + 8 * fq) * 4u;
;         asm volatile("" : "+v"(lo), "+v"(co));
;         float rs[2][4]; row_rstd(ssq, r0 + wr * 64 + fr, rs);
;         f32x4 sg[2], su[2], sgn[2];
; #pragma unroll
;         for (int n = 0; n < 2; ++n) { sg[n] = *(const f32x4*)(swb + co + n * 16); su[n] = *(const f32x4*)(swb + co + HALF * 4 + n * 16); sgn[n] = sg[n] * (-LOG2E); }
.LBB0_228:
	s_lshl_b32 s30, s49, 8
	v_add_u32_e32 v82, s30, v169
	v_ashrrev_i32_e32 v83, 31, v82
	v_mov_b32_e32 v166, v170
	v_mov_b32_e32 v98, v171
	v_lshl_add_u64 v[82:83], v[82:83], 3, s[34:35]
	global_load_dwordx2 v[150:151], v[82:83], off
	global_load_dwordx2 v[152:153], v[82:83], off offset:128
	global_load_dwordx2 v[154:155], v[82:83], off offset:256
	global_load_dwordx2 v[156:157], v[82:83], off offset:384
	global_load_dwordx2 v[178:179], v[82:83], off offset:1024
	global_load_dwordx2 v[180:181], v[82:83], off offset:1152
	global_load_dwordx2 v[182:183], v[82:83], off offset:1280
	global_load_dwordx2 v[184:185], v[82:83], off offset:1408
	s_mul_i32 s31, s49, 0x2b0000
	s_mul_hi_i32 s30, s30, 0x2b00
	s_add_u32 s49, s5, s31
	s_addc_u32 s50, s7, s30
	s_lshl_b32 s30, s48, 7
	s_ashr_i32 s31, s30, 31
	s_lshl_b64 s[30:31], s[30:31], 1
	s_add_u32 s30, s49, s30
	s_addc_u32 s31, s50, s31
	s_lshl_b64 s[42:43], s[42:43], 2
	s_add_u32 s49, s2, s42
	s_addc_u32 s50, s3, s43
	s_lshl_b32 s42, s48, 8
	s_ashr_i32 s43, s42, 31
	s_lshl_b64 s[42:43], s[42:43], 2
	s_add_u32 s42, s49, s42
	s_addc_u32 s43, s50, s43
	s_flbit_i32_b32 s48, 0
	s_min_u32 s48, s48, 32
	s_sub_i32 s49, 32, s48
	v_mov_b32_e32 v167, v175
	v_lshl_add_u64 v[146:147], s[30:31], 0, v[166:167]
	s_waitcnt vmcnt(0)
	global_load_dwordx4 v[86:89], v98, s[42:43] offset:16
	global_load_dwordx4 v[102:105], v98, s[42:43]
	global_load_dwordx4 v[82:85], v98, s[42:43] offset:528
	s_nop 0
	global_load_dwordx4 v[98:101], v98, s[42:43] offset:512
	v_mov_b32_e32 v174, v151
	v_cvt_f32_u32_e32 v148, v150
	v_lshlrev_b64 v[150:151], s48, v[174:175]
	v_mov_b32_e32 v174, v153
	v_cvt_f32_u32_e32 v158, v152
	v_min_u32_e32 v150, 1, v150
	v_lshlrev_b64 v[152:153], s48, v[174:175]
	v_mov_b32_e32 v174, v155
	v_or_b32_e32 v155, v151, v150
	v_min_u32_e32 v152, 1, v152
	v_lshlrev_b64 v[150:151], s48, v[174:175]
	v_mov_b32_e32 v174, v157
	v_cvt_f32_u32_e32 v155, v155
	v_or_b32_e32 v157, v153, v152
	v_min_u32_e32 v150, 1, v150
	v_lshlrev_b64 v[152:153], s48, v[174:175]
	v_mov_b32_e32 v174, v179
	v_cvt_f32_u32_e32 v157, v157
	v_or_b32_e32 v162, v151, v150
	v_min_u32_e32 v152, 1, v152
	v_lshlrev_b64 v[150:151], s48, v[174:175]
	v_mov_b32_e32 v174, v181
	v_cvt_f32_u32_e32 v162, v162
	v_or_b32_e32 v164, v153, v152
	v_min_u32_e32 v150, 1, v150
	v_lshlrev_b64 v[152:153], s48, v[174:175]
	v_mov_b32_e32 v174, v183
	v_cvt_f32_u32_e32 v154, v154
	v_cvt_f32_u32_e32 v164, v164
	v_or_b32_e32 v168, v151, v150
	v_lshlrev_b64 v[150:151], s48, v[174:175]
	v_cvt_f32_u32_e32 v156, v156
	v_min_u32_e32 v152, 1, v152
	v_mov_b32_e32 v174, v185
	v_ldexp_f32 v155, v155, s49
	v_cvt_f32_u32_e32 v168, v168
	v_min_u32_e32 v150, 1, v150
	v_cvt_f32_u32_e32 v160, v178
	v_or_b32_e32 v178, v153, v152
	v_lshlrev_b64 v[152:153], s48, v[174:175]
	v_fmac_f32_e32 v148, 0x4f800000, v155
	v_ldexp_f32 v155, v157, s49
	v_or_b32_e32 v150, v151, v150
	v_cvt_f32_u32_e32 v157, v178
	v_min_u32_e32 v151, 1, v152
	v_fmamk_f32 v148, v148, 0x30000000, v231
	v_fmac_f32_e32 v158, 0x4f800000, v155
	v_ldexp_f32 v152, v162, s49
	v_cvt_f32_u32_e32 v150, v150
	v_cvt_f32_u32_e32 v167, v180
	v_cvt_f32_u32_e32 v177, v182
	v_or_b32_e32 v151, v153, v151
	v_rsq_f32_e32 v174, v148
	v_fmamk_f32 v148, v158, 0x30000000, v231
	v_fmac_f32_e32 v154, 0x4f800000, v152
	v_ldexp_f32 v152, v164, s49
	v_cvt_f32_u32_e32 v151, v151
	v_rsq_f32_e32 v178, v148
	v_fmamk_f32 v148, v154, 0x30000000, v231
	v_fmac_f32_e32 v156, 0x4f800000, v152
	v_ldexp_f32 v152, v168, s49
	v_cvt_f32_u32_e32 v188, v184
	v_rsq_f32_e32 v168, v148
	v_fmamk_f32 v148, v156, 0x30000000, v231
	v_fmac_f32_e32 v160, 0x4f800000, v152
	v_ldexp_f32 v152, v157, s49
	v_rsq_f32_e32 v164, v148
	v_fmamk_f32 v148, v160, 0x30000000, v231
	v_ldexp_f32 v150, v150, s49
	v_fmac_f32_e32 v167, 0x4f800000, v152
	v_rsq_f32_e32 v162, v148
	v_fmac_f32_e32 v177, 0x4f800000, v150
	v_mul_f32_e32 v148, 0xbfb8aa3b, v174
	s_mov_b32 s42, 0xbfb8aa3b
	v_fmamk_f32 v152, v167, 0x30000000, v231
	v_ldexp_f32 v150, v151, s49
	v_fmamk_f32 v151, v177, 0x30000000, v231
	v_pk_mul_f32 v[182:183], v[142:143], v[148:149] op_sel_hi:[1,0]
	s_waitcnt vmcnt(2)
	v_pk_mul_f32 v[156:157], v[102:103], s[42:43] op_sel_hi:[1,0]
	v_rsq_f32_e32 v160, v152
	v_fmac_f32_e32 v188, 0x4f800000, v150
	v_pk_mul_f32 v[180:181], v[144:145], v[148:149] op_sel_hi:[1,0]
	v_pk_mul_f32 v[184:185], v[136:137], v[148:149] op_sel_hi:[1,0]
	v_pk_mul_f32 v[186:187], v[134:135], v[148:149] op_sel_hi:[1,0]
	v_rsq_f32_e32 v158, v151
	v_pk_mul_f32 v[154:155], v[104:105], s[42:43] op_sel_hi:[1,0]
	v_pk_mul_f32 v[150:151], v[88:89], s[42:43] op_sel_hi:[1,0]
	v_pk_mul_f32 v[152:153], v[86:87], s[42:43] op_sel_hi:[1,0]
	v_pk_fma_f32 v[144:145], v[144:145], v[174:175], v[104:105] op_sel_hi:[1,0,1]
	v_pk_fma_f32 v[142:143], v[142:143], v[174:175], v[102:103] op_sel_hi:[1,0,1]
	s_waitcnt vmcnt(0)
;     template <int QVV> __device__ __forceinline__ void run(f32x4 (&acc)[2][2][4][2], const Unit& u, int wr, int wc, int fr, int fq) const {
;     ...
; #pragma unroll
;         for (int ai = 0; ai < 2; ++ai)
; #pragma unroll
;             for (int m = 0; m < 4; ++m) { if (ai >= nai) continue;
;                 const float r = rs[ai][m], rn = r * (-LOG2E);
;                 f32x4 o[2];
; #pragma unroll
;                 for (int n = 0; n < 2; ++n) {
;                     const f32x4 gt = acc[ai][0][m][n] * r + sg[n], up = acc[ai][1][m][n] * r + su[n], ex = acc[ai][0][m][n] * rn + sgn[n];
;                     f32x4 den, rc;
; #pragma unroll
;                     for (int i = 0; i < 4; ++i) den[i] = __builtin_amdgcn_exp2f(ex[i]);
;                     den = den + 1.0f;
; #pragma unroll
;                     for (int i = 0; i < 4; ++i) rc[i] = __builtin_amdgcn_rcpf(den[i]);
;                     o[n] = (gt * up) * rc; }
;                 u32x4 w; w.x = pk2(o[0][0], o[0][1]); w.y = pk2(o[0][2], o[0][3]); w.z = pk2(o[1][0], o[1][1]); w.w = pk2(o[1][2], o[1][3]);
;                 *(u32x4*)(tb + lo + (unsigned)(ai * HALF + m * 16) * (DFF * 2)) = w; }
	v_pk_fma_f32 v[140:141], v[140:141], v[174:175], v[100:101] op_sel_hi:[1,0,1]
	v_pk_fma_f32 v[138:139], v[138:139], v[174:175], v[98:99] op_sel_hi:[1,0,1]
	v_pk_fma_f32 v[136:137], v[136:137], v[174:175], v[88:89] op_sel_hi:[1,0,1]
	v_pk_fma_f32 v[134:135], v[134:135], v[174:175], v[86:87] op_sel_hi:[1,0,1]
	v_pk_fma_f32 v[132:133], v[132:133], v[174:175], v[84:85] op_sel_hi:[1,0,1]
	v_pk_fma_f32 v[130:131], v[130:131], v[174:175], v[82:83] op_sel_hi:[1,0,1]
	v_add_f32_e32 v167, v156, v182
	v_add_f32_e32 v174, v157, v183
	v_add_f32_e32 v177, v154, v180
	v_add_f32_e32 v179, v155, v181
	v_pk_mul_f32 v[138:139], v[142:143], v[138:139]
	v_pk_mul_f32 v[140:141], v[144:145], v[140:141]
	v_add_f32_e32 v142, v152, v186
	v_add_f32_e32 v143, v153, v187
	v_add_f32_e32 v144, v150, v184
	v_add_f32_e32 v145, v151, v185
	v_pk_mul_f32 v[130:131], v[134:135], v[130:131]
	v_exp_f32_e32 v134, v167
	v_exp_f32_e32 v135, v174
	v_pk_mul_f32 v[132:133], v[136:137], v[132:133]
	v_exp_f32_e32 v136, v177
	v_exp_f32_e32 v137, v179
	v_exp_f32_e32 v142, v142
	v_exp_f32_e32 v144, v144
	v_exp_f32_e32 v145, v145
	v_exp_f32_e32 v143, v143
	v_pk_add_f32 v[134:135], v[134:135], 1.0 op_sel_hi:[1,0]
	v_pk_add_f32 v[136:137], v[136:137], 1.0 op_sel_hi:[1,0]
	v_pk_add_f32 v[144:145], v[144:145], 1.0 op_sel_hi:[1,0]
	v_pk_add_f32 v[142:143], v[142:143], 1.0 op_sel_hi:[1,0]
	v_rcp_f32_e32 v134, v134
	v_rcp_f32_e32 v135, v135
	v_rcp_f32_e32 v136, v136
	v_rcp_f32_e32 v137, v137
	v_rcp_f32_e32 v142, v142
	v_rcp_f32_e32 v144, v144
	v_rcp_f32_e32 v145, v145
	v_rcp_f32_e32 v143, v143
	v_pk_mul_f32 v[134:135], v[138:139], v[134:135]
	v_pk_mul_f32 v[136:137], v[140:141], v[136:137]
	v_pk_mul_f32 v[138:139], v[132:133], v[144:145]
	v_pk_mul_f32 v[132:133], v[130:131], v[142:143]
	v_cvt_pk_bf16_f32 v130, v134, v135
	v_mul_f32_e32 v134, 0xbfb8aa3b, v178
	v_cvt_pk_bf16_f32 v131, v136, v137
	v_pk_mul_f32 v[136:137], v[128:129], v[134:135] op_sel_hi:[1,0]
	v_pk_mul_f32 v[140:141], v[126:127], v[134:135] op_sel_hi:[1,0]
	v_add_f32_e32 v135, v154, v136
	v_exp_f32_e32 v136, v135
	v_add_f32_e32 v135, v155, v137
	v_pk_fma_f32 v[128:129], v[128:129], v[178:179], v[104:105] op_sel_hi:[1,0,1]
	v_pk_fma_f32 v[126:127], v[126:127], v[178:179], v[102:103] op_sel_hi:[1,0,1]
	v_pk_fma_f32 v[124:125], v[124:125], v[178:179], v[100:101] op_sel_hi:[1,0,1]
	v_pk_fma_f32 v[122:123], v[122:123], v[178:179], v[98:99] op_sel_hi:[1,0,1]
	v_pk_mul_f32 v[124:125], v[128:129], v[124:125]
	v_pk_mul_f32 v[122:123], v[126:127], v[122:123]
	v_pk_mul_f32 v[126:127], v[120:121], v[134:135] op_sel_hi:[1,0]
	v_pk_mul_f32 v[128:129], v[118:119], v[134:135] op_sel_hi:[1,0]
	v_cvt_pk_bf16_f32 v132, v132, v133
	v_add_f32_e32 v133, v156, v140
	v_add_f32_e32 v128, v152, v128
	v_add_f32_e32 v129, v153, v129
	v_add_f32_e32 v126, v150, v126
	v_add_f32_e32 v127, v151, v127
	v_exp_f32_e32 v140, v133
	v_add_f32_e32 v133, v157, v141
	v_exp_f32_e32 v128, v128
	v_exp_f32_e32 v126, v126
	v_exp_f32_e32 v127, v127
	v_exp_f32_e32 v129, v129
	v_exp_f32_e32 v141, v133
	v_cvt_pk_bf16_f32 v133, v138, v139
	v_pk_add_f32 v[126:127], v[126:127], 1.0 op_sel_hi:[1,0]
	v_pk_add_f32 v[128:129], v[128:129], 1.0 op_sel_hi:[1,0]
	global_store_dwordx4 v166, v[130:133], s[30:31]
	v_rcp_f32_e32 v128, v128
	v_rcp_f32_e32 v129, v129
	v_pk_add_f32 v[132:133], v[140:141], 1.0 op_sel_hi:[1,0]
	v_rcp_f32_e32 v126, v126
	v_rcp_f32_e32 v127, v127
	v_rcp_f32_e32 v132, v132
	v_rcp_f32_e32 v133, v133
	v_pk_fma_f32 v[120:121], v[120:121], v[178:179], v[88:89] op_sel_hi:[1,0,1]
	v_pk_fma_f32 v[118:119], v[118:119], v[178:179], v[86:87] op_sel_hi:[1,0,1]
	v_pk_fma_f32 v[116:117], v[116:117], v[178:179], v[84:85] op_sel_hi:[1,0,1]
	v_pk_fma_f32 v[114:115], v[114:115], v[178:179], v[82:83] op_sel_hi:[1,0,1]
	v_pk_mul_f32 v[116:117], v[120:121], v[116:117]
	v_pk_mul_f32 v[114:115], v[118:119], v[114:115]
	v_pk_mul_f32 v[118:119], v[116:117], v[126:127]
	v_pk_mul_f32 v[116:117], v[114:115], v[128:129]
	v_pk_mul_f32 v[122:123], v[122:123], v[132:133]
	v_cvt_pk_bf16_f32 v116, v116, v117
	v_cvt_pk_bf16_f32 v117, v118, v119
	v_mul_f32_e32 v118, 0xbfb8aa3b, v168
	v_exp_f32_e32 v137, v135
	v_cvt_pk_bf16_f32 v114, v122, v123
	v_pk_mul_f32 v[122:123], v[110:111], v[118:119] op_sel_hi:[1,0]
	v_pk_mul_f32 v[120:121], v[112:113], v[118:119] op_sel_hi:[1,0]
	v_add_f32_e32 v119, v156, v122
	v_exp_f32_e32 v122, v119
	v_add_f32_e32 v119, v157, v123
	v_exp_f32_e32 v123, v119
	v_add_f32_e32 v119, v154, v120
	v_pk_add_f32 v[130:131], v[136:137], 1.0 op_sel_hi:[1,0]
	v_exp_f32_e32 v120, v119
	v_add_f32_e32 v119, v155, v121
	v_pk_fma_f32 v[112:113], v[112:113], v[168:169], v[104:105] op_sel_hi:[1,0,1]
	v_pk_fma_f32 v[110:111], v[110:111], v[168:169], v[102:103] op_sel_hi:[1,0,1]
	v_pk_fma_f32 v[108:109], v[108:109], v[168:169], v[100:101] op_sel_hi:[1,0,1]
	v_pk_fma_f32 v[106:107], v[106:107], v[168:169], v[98:99] op_sel_hi:[1,0,1]
	v_rcp_f32_e32 v130, v130
	v_rcp_f32_e32 v131, v131
	v_pk_mul_f32 v[106:107], v[110:111], v[106:107]
	v_pk_mul_f32 v[108:109], v[112:113], v[108:109]
	v_pk_mul_f32 v[110:111], v[96:97], v[118:119] op_sel_hi:[1,0]
	v_pk_mul_f32 v[112:113], v[94:95], v[118:119] op_sel_hi:[1,0]
	v_add_f32_e32 v110, v150, v110
	v_add_f32_e32 v112, v152, v112
	v_add_f32_e32 v113, v153, v113
	v_add_f32_e32 v111, v151, v111
	v_exp_f32_e32 v112, v112
	v_exp_f32_e32 v110, v110
	v_exp_f32_e32 v111, v111
	v_exp_f32_e32 v113, v113
	v_pk_mul_f32 v[124:125], v[124:125], v[130:131]
	s_mov_b32 s30, 0x2b000
	v_cvt_pk_bf16_f32 v115, v124, v125
	v_add_co_u32_e32 v124, vcc, s30, v146
	v_pk_add_f32 v[110:111], v[110:111], 1.0 op_sel_hi:[1,0]
	s_nop 0
	v_addc_co_u32_e32 v125, vcc, 0, v147, vcc
;     template <int QVV> __device__ __forceinline__ void run(f32x4 (&acc)[2][2][4][2], const Unit& u, int wr, int wc, int fr, int fq) const {
;     ...
; #pragma unroll
;         for (int ai = 0; ai < 2; ++ai)
; #pragma unroll
;             for (int m = 0; m < 4; ++m) { if (ai >= nai) continue;
;                 const float r = rs[ai][m], rn = r * (-LOG2E);
;                 f32x4 o[2];
; #pragma unroll
;                 for (int n = 0; n < 2; ++n) {
;                     const f32x4 gt = acc[ai][0][m][n] * r + sg[n], up = acc[ai][1][m][n] * r + su[n], ex = acc[ai][0][m][n] * rn + sgn[n];
;                     f32x4 den, rc;
; #pragma unroll
;                     for (int i = 0; i < 4; ++i) den[i] = __builtin_amdgcn_exp2f(ex[i]);
;                     den = den + 1.0f;
; #pragma unroll
;                     for (int i = 0; i < 4; ++i) rc[i] = __builtin_amdgcn_rcpf(den[i]);
;                     o[n] = (gt * up) * rc; }
;                 u32x4 w; w.x = pk2(o[0][0], o[0][1]); w.y = pk2(o[0][2], o[0][3]); w.z = pk2(o[1][0], o[1][1]); w.w = pk2(o[1][2], o[1][3]);
;                 *(u32x4*)(tb + lo + (unsigned)(ai * HALF + m * 16) * (DFF * 2)) = w; }
	v_pk_add_f32 v[112:113], v[112:113], 1.0 op_sel_hi:[1,0]
	global_store_dwordx4 v[124:125], v[114:117], off
	v_rcp_f32_e32 v112, v112
	v_rcp_f32_e32 v113, v113
	v_pk_add_f32 v[116:117], v[122:123], 1.0 op_sel_hi:[1,0]
	v_rcp_f32_e32 v110, v110
	v_rcp_f32_e32 v111, v111
	v_rcp_f32_e32 v116, v116
	v_rcp_f32_e32 v117, v117
	v_pk_fma_f32 v[96:97], v[96:97], v[168:169], v[88:89] op_sel_hi:[1,0,1]
	v_pk_fma_f32 v[94:95], v[94:95], v[168:169], v[86:87] op_sel_hi:[1,0,1]
	v_pk_fma_f32 v[92:93], v[92:93], v[168:169], v[84:85] op_sel_hi:[1,0,1]
	v_pk_fma_f32 v[90:91], v[90:91], v[168:169], v[82:83] op_sel_hi:[1,0,1]
	v_pk_mul_f32 v[92:93], v[96:97], v[92:93]
	v_pk_mul_f32 v[90:91], v[94:95], v[90:91]
	v_pk_mul_f32 v[94:95], v[92:93], v[110:111]
	v_pk_mul_f32 v[92:93], v[90:91], v[112:113]
	v_pk_mul_f32 v[106:107], v[106:107], v[116:117]
	v_cvt_pk_bf16_f32 v92, v92, v93
	v_cvt_pk_bf16_f32 v93, v94, v95
	v_mul_f32_e32 v94, 0xbfb8aa3b, v164
	v_exp_f32_e32 v121, v119
	v_cvt_pk_bf16_f32 v90, v106, v107
	v_pk_mul_f32 v[106:107], v[78:79], v[94:95] op_sel_hi:[1,0]
	v_pk_mul_f32 v[96:97], v[80:81], v[94:95] op_sel_hi:[1,0]
	v_add_f32_e32 v95, v156, v106
	v_exp_f32_e32 v106, v95
	v_add_f32_e32 v95, v157, v107
	v_exp_f32_e32 v107, v95
	v_add_f32_e32 v95, v154, v96
	v_pk_add_f32 v[114:115], v[120:121], 1.0 op_sel_hi:[1,0]
	v_exp_f32_e32 v96, v95
	v_add_f32_e32 v95, v155, v97
	v_pk_fma_f32 v[80:81], v[80:81], v[164:165], v[104:105] op_sel_hi:[1,0,1]
	v_pk_fma_f32 v[78:79], v[78:79], v[164:165], v[102:103] op_sel_hi:[1,0,1]
	v_pk_fma_f32 v[76:77], v[76:77], v[164:165], v[100:101] op_sel_hi:[1,0,1]
	v_pk_fma_f32 v[74:75], v[74:75], v[164:165], v[98:99] op_sel_hi:[1,0,1]
	v_rcp_f32_e32 v114, v114
	v_rcp_f32_e32 v115, v115
	v_pk_mul_f32 v[74:75], v[78:79], v[74:75]
	v_pk_mul_f32 v[76:77], v[80:81], v[76:77]
	v_pk_mul_f32 v[78:79], v[72:73], v[94:95] op_sel_hi:[1,0]
	v_pk_mul_f32 v[80:81], v[70:71], v[94:95] op_sel_hi:[1,0]
	v_add_f32_e32 v78, v150, v78
	v_add_f32_e32 v80, v152, v80
	v_add_f32_e32 v81, v153, v81
	v_add_f32_e32 v79, v151, v79
	v_exp_f32_e32 v80, v80
	v_exp_f32_e32 v78, v78
	v_exp_f32_e32 v79, v79
	v_exp_f32_e32 v81, v81
	v_pk_mul_f32 v[108:109], v[108:109], v[114:115]
	s_mov_b32 s30, 0x56000
	v_cvt_pk_bf16_f32 v91, v108, v109
	v_add_co_u32_e32 v108, vcc, s30, v146
	v_pk_add_f32 v[78:79], v[78:79], 1.0 op_sel_hi:[1,0]
	s_nop 0
	v_addc_co_u32_e32 v109, vcc, 0, v147, vcc
	v_pk_add_f32 v[80:81], v[80:81], 1.0 op_sel_hi:[1,0]
	global_store_dwordx4 v[108:109], v[90:93], off
	v_rcp_f32_e32 v80, v80
	v_rcp_f32_e32 v81, v81
	v_pk_add_f32 v[92:93], v[106:107], 1.0 op_sel_hi:[1,0]
	v_rcp_f32_e32 v78, v78
	v_rcp_f32_e32 v79, v79
	v_rcp_f32_e32 v92, v92
	v_rcp_f32_e32 v93, v93
	v_pk_fma_f32 v[72:73], v[72:73], v[164:165], v[88:89] op_sel_hi:[1,0,1]
	v_pk_fma_f32 v[70:71], v[70:71], v[164:165], v[86:87] op_sel_hi:[1,0,1]
	v_pk_fma_f32 v[68:69], v[68:69], v[164:165], v[84:85] op_sel_hi:[1,0,1]
	v_pk_fma_f32 v[66:67], v[66:67], v[164:165], v[82:83] op_sel_hi:[1,0,1]
	v_pk_mul_f32 v[68:69], v[72:73], v[68:69]
	v_pk_mul_f32 v[66:67], v[70:71], v[66:67]
	v_pk_mul_f32 v[70:71], v[68:69], v[78:79]
	v_pk_mul_f32 v[68:69], v[66:67], v[80:81]
	v_pk_mul_f32 v[74:75], v[74:75], v[92:93]
	v_cvt_pk_bf16_f32 v68, v68, v69
	v_cvt_pk_bf16_f32 v69, v70, v71
	v_mul_f32_e32 v70, 0xbfb8aa3b, v162
	v_exp_f32_e32 v97, v95
	v_cvt_pk_bf16_f32 v66, v74, v75
	v_pk_mul_f32 v[74:75], v[62:63], v[70:71] op_sel_hi:[1,0]
	v_pk_mul_f32 v[72:73], v[64:65], v[70:71] op_sel_hi:[1,0]
	v_add_f32_e32 v71, v156, v74
	v_exp_f32_e32 v74, v71
	v_add_f32_e32 v71, v157, v75
	v_exp_f32_e32 v75, v71
	v_add_f32_e32 v71, v154, v72
	v_pk_add_f32 v[90:91], v[96:97], 1.0 op_sel_hi:[1,0]
	v_exp_f32_e32 v72, v71
	v_add_f32_e32 v71, v155, v73
	v_pk_fma_f32 v[64:65], v[64:65], v[162:163], v[104:105] op_sel_hi:[1,0,1]
	v_pk_fma_f32 v[62:63], v[62:63], v[162:163], v[102:103] op_sel_hi:[1,0,1]
	v_pk_fma_f32 v[60:61], v[60:61], v[162:163], v[100:101] op_sel_hi:[1,0,1]
	v_pk_fma_f32 v[58:59], v[58:59], v[162:163], v[98:99] op_sel_hi:[1,0,1]
	v_rcp_f32_e32 v90, v90
	v_rcp_f32_e32 v91, v91
	v_pk_mul_f32 v[58:59], v[62:63], v[58:59]
	v_pk_mul_f32 v[60:61], v[64:65], v[60:61]
	v_pk_mul_f32 v[62:63], v[56:57], v[70:71] op_sel_hi:[1,0]
	v_pk_mul_f32 v[64:65], v[54:55], v[70:71] op_sel_hi:[1,0]
	v_add_f32_e32 v62, v150, v62
	v_add_f32_e32 v64, v152, v64
	v_add_f32_e32 v65, v153, v65
	v_add_f32_e32 v63, v151, v63
	v_exp_f32_e32 v64, v64
	v_exp_f32_e32 v62, v62
	v_exp_f32_e32 v63, v63
	v_exp_f32_e32 v65, v65
	v_pk_mul_f32 v[76:77], v[76:77], v[90:91]
	s_mov_b32 s30, 0x81000
	v_cvt_pk_bf16_f32 v67, v76, v77
	v_add_co_u32_e32 v76, vcc, s30, v146
	v_pk_add_f32 v[62:63], v[62:63], 1.0 op_sel_hi:[1,0]
	s_nop 0
	v_addc_co_u32_e32 v77, vcc, 0, v147, vcc
	v_pk_add_f32 v[64:65], v[64:65], 1.0 op_sel_hi:[1,0]
	global_store_dwordx4 v[76:77], v[66:69], off
	v_rcp_f32_e32 v64, v64
	v_rcp_f32_e32 v65, v65
	v_pk_add_f32 v[68:69], v[74:75], 1.0 op_sel_hi:[1,0]
	v_rcp_f32_e32 v62, v62
	v_rcp_f32_e32 v63, v63
	v_rcp_f32_e32 v68, v68
	v_rcp_f32_e32 v69, v69
	v_pk_fma_f32 v[56:57], v[56:57], v[162:163], v[88:89] op_sel_hi:[1,0,1]
	v_pk_fma_f32 v[54:55], v[54:55], v[162:163], v[86:87] op_sel_hi:[1,0,1]
	v_pk_fma_f32 v[52:53], v[52:53], v[162:163], v[84:85] op_sel_hi:[1,0,1]
	v_pk_fma_f32 v[50:51], v[50:51], v[162:163], v[82:83] op_sel_hi:[1,0,1]
	v_pk_mul_f32 v[52:53], v[56:57], v[52:53]
	v_pk_mul_f32 v[50:51], v[54:55], v[50:51]
	v_pk_mul_f32 v[54:55], v[52:53], v[62:63]
	v_pk_mul_f32 v[52:53], v[50:51], v[64:65]
	v_pk_mul_f32 v[58:59], v[58:59], v[68:69]
	v_cvt_pk_bf16_f32 v52, v52, v53
	v_cvt_pk_bf16_f32 v53, v54, v55
	v_mul_f32_e32 v54, 0xbfb8aa3b, v160
;     template <int QVV> __device__ __forceinline__ void run(f32x4 (&acc)[2][2][4][2], const Unit& u, int wr, int wc, int fr, int fq) const {
;     ...
; #pragma unroll
;         for (int ai = 0; ai < 2; ++ai)
; #pragma unroll
;             for (int m = 0; m < 4; ++m) { if (ai >= nai) continue;
;                 const float r = rs[ai][m], rn = r * (-LOG2E);
;                 f32x4 o[2];
; #pragma unroll
;                 for (int n = 0; n < 2; ++n) {
;                     const f32x4 gt = acc[ai][0][m][n] * r + sg[n], up = acc[ai][1][m][n] * r + su[n], ex = acc[ai][0][m][n] * rn + sgn[n];
;                     f32x4 den, rc;
; #pragma unroll
;                     for (int i = 0; i < 4; ++i) den[i] = __builtin_amdgcn_exp2f(ex[i]);
;                     den = den + 1.0f;
; #pragma unroll
;                     for (int i = 0; i < 4; ++i) rc[i] = __builtin_amdgcn_rcpf(den[i]);
;                     o[n] = (gt * up) * rc; }
;                 u32x4 w; w.x = pk2(o[0][0], o[0][1]); w.y = pk2(o[0][2], o[0][3]); w.z = pk2(o[1][0], o[1][1]); w.w = pk2(o[1][2], o[1][3]);
;                 *(u32x4*)(tb + lo + (unsigned)(ai * HALF + m * 16) * (DFF * 2)) = w; }
	v_exp_f32_e32 v73, v71
	v_cvt_pk_bf16_f32 v50, v58, v59
	v_pk_mul_f32 v[58:59], v[46:47], v[54:55] op_sel_hi:[1,0]
	v_pk_mul_f32 v[56:57], v[48:49], v[54:55] op_sel_hi:[1,0]
	v_add_f32_e32 v55, v156, v58
	v_exp_f32_e32 v58, v55
	v_add_f32_e32 v55, v157, v59
	v_exp_f32_e32 v59, v55
	v_add_f32_e32 v55, v154, v56
	v_pk_add_f32 v[66:67], v[72:73], 1.0 op_sel_hi:[1,0]
	v_exp_f32_e32 v56, v55
	v_add_f32_e32 v55, v155, v57
	v_pk_fma_f32 v[48:49], v[48:49], v[160:161], v[104:105] op_sel_hi:[1,0,1]
	v_pk_fma_f32 v[46:47], v[46:47], v[160:161], v[102:103] op_sel_hi:[1,0,1]
	v_pk_fma_f32 v[44:45], v[44:45], v[160:161], v[100:101] op_sel_hi:[1,0,1]
	v_pk_fma_f32 v[42:43], v[42:43], v[160:161], v[98:99] op_sel_hi:[1,0,1]
	v_rcp_f32_e32 v66, v66
	v_rcp_f32_e32 v67, v67
	v_pk_mul_f32 v[42:43], v[46:47], v[42:43]
	v_pk_mul_f32 v[44:45], v[48:49], v[44:45]
	v_pk_mul_f32 v[46:47], v[40:41], v[54:55] op_sel_hi:[1,0]
	v_pk_mul_f32 v[48:49], v[38:39], v[54:55] op_sel_hi:[1,0]
	v_add_f32_e32 v46, v150, v46
	v_add_f32_e32 v48, v152, v48
	v_add_f32_e32 v49, v153, v49
	v_add_f32_e32 v47, v151, v47
	v_exp_f32_e32 v48, v48
	v_exp_f32_e32 v46, v46
	v_exp_f32_e32 v47, v47
	v_exp_f32_e32 v49, v49
	v_pk_mul_f32 v[60:61], v[60:61], v[66:67]
	s_mov_b32 s30, 0x158000
	v_cvt_pk_bf16_f32 v51, v60, v61
	v_add_co_u32_e32 v60, vcc, s30, v146
	v_pk_add_f32 v[46:47], v[46:47], 1.0 op_sel_hi:[1,0]
	s_nop 0
	v_addc_co_u32_e32 v61, vcc, 0, v147, vcc
	v_pk_add_f32 v[48:49], v[48:49], 1.0 op_sel_hi:[1,0]
	global_store_dwordx4 v[60:61], v[50:53], off
	v_rcp_f32_e32 v48, v48
	v_rcp_f32_e32 v49, v49
	v_pk_add_f32 v[52:53], v[58:59], 1.0 op_sel_hi:[1,0]
	v_rcp_f32_e32 v46, v46
	v_rcp_f32_e32 v47, v47
	v_rcp_f32_e32 v52, v52
	v_rcp_f32_e32 v53, v53
	v_pk_fma_f32 v[40:41], v[40:41], v[160:161], v[88:89] op_sel_hi:[1,0,1]
	v_pk_fma_f32 v[38:39], v[38:39], v[160:161], v[86:87] op_sel_hi:[1,0,1]
	v_pk_fma_f32 v[36:37], v[36:37], v[160:161], v[84:85] op_sel_hi:[1,0,1]
	v_pk_fma_f32 v[34:35], v[34:35], v[160:161], v[82:83] op_sel_hi:[1,0,1]
	v_pk_mul_f32 v[36:37], v[40:41], v[36:37]
	v_pk_mul_f32 v[34:35], v[38:39], v[34:35]
	v_pk_mul_f32 v[38:39], v[36:37], v[46:47]
	v_pk_mul_f32 v[36:37], v[34:35], v[48:49]
	v_pk_mul_f32 v[42:43], v[42:43], v[52:53]
	v_cvt_pk_bf16_f32 v36, v36, v37
	v_cvt_pk_bf16_f32 v37, v38, v39
	v_mul_f32_e32 v38, 0xbfb8aa3b, v158
	v_exp_f32_e32 v57, v55
	v_cvt_pk_bf16_f32 v34, v42, v43
	v_pk_mul_f32 v[42:43], v[30:31], v[38:39] op_sel_hi:[1,0]
	v_pk_mul_f32 v[40:41], v[32:33], v[38:39] op_sel_hi:[1,0]
	v_add_f32_e32 v39, v156, v42
	v_exp_f32_e32 v42, v39
	v_add_f32_e32 v39, v157, v43
	v_exp_f32_e32 v43, v39
	v_add_f32_e32 v39, v154, v40
	v_pk_add_f32 v[50:51], v[56:57], 1.0 op_sel_hi:[1,0]
	v_exp_f32_e32 v40, v39
	v_add_f32_e32 v39, v155, v41
	v_pk_fma_f32 v[32:33], v[32:33], v[158:159], v[104:105] op_sel_hi:[1,0,1]
	v_pk_fma_f32 v[30:31], v[30:31], v[158:159], v[102:103] op_sel_hi:[1,0,1]
	v_pk_fma_f32 v[28:29], v[28:29], v[158:159], v[100:101] op_sel_hi:[1,0,1]
	v_pk_fma_f32 v[26:27], v[26:27], v[158:159], v[98:99] op_sel_hi:[1,0,1]
	v_rcp_f32_e32 v50, v50
	v_rcp_f32_e32 v51, v51
	v_pk_mul_f32 v[26:27], v[30:31], v[26:27]
	v_pk_mul_f32 v[28:29], v[32:33], v[28:29]
	v_pk_mul_f32 v[30:31], v[24:25], v[38:39] op_sel_hi:[1,0]
	v_pk_mul_f32 v[32:33], v[22:23], v[38:39] op_sel_hi:[1,0]
	v_add_f32_e32 v30, v150, v30
	v_add_f32_e32 v32, v152, v32
	v_add_f32_e32 v33, v153, v33
	v_add_f32_e32 v31, v151, v31
	v_exp_f32_e32 v32, v32
	v_exp_f32_e32 v30, v30
	v_exp_f32_e32 v31, v31
	v_exp_f32_e32 v33, v33
	v_pk_mul_f32 v[44:45], v[44:45], v[50:51]
	s_mov_b32 s30, 0x183000
	v_cvt_pk_bf16_f32 v35, v44, v45
	v_add_co_u32_e32 v44, vcc, s30, v146
	v_pk_add_f32 v[30:31], v[30:31], 1.0 op_sel_hi:[1,0]
	s_nop 0
	v_addc_co_u32_e32 v45, vcc, 0, v147, vcc
; #define PG8_BAR __builtin_amdgcn_s_barrier()
;     ...
;         if (!has_next) break;
;         if (!cur.keep) {
; #pragma unroll
;             for (int a = 0; a < 2; ++a)
; #pragma unroll
;                 for (int b = 0; b < 2; ++b)
; #pragma unroll
;                     for (int m = 0; m < 4; ++m)
; #pragma unroll
;                         for (int n = 0; n < 2; ++n) { f32x2 z0, z1; asm("v_mov_b64 %0, 0\n\tv_mov_b64 %1, 0" : "=v"(z0), "=v"(z1));
;                     acc[a][b][m][n] = __builtin_shufflevector(z0, z1, 0, 1, 2, 3); }
;         }
;         cur = nxt; cA = nA; cB = nB; ++ui;
;         if (wr == 1) PG8_BAR;
;     template <int QVV> __device__ __forceinline__ void run(f32x4 (&acc)[2][2][4][2], const Unit& u, int wr, int wc, int fr, int fq) const {
;     ...
;                     const f32x4 gt = acc[ai][0][m][n] * r + sg[n], up = acc[ai][1][m][n] * r + su[n], ex = acc[ai][0][m][n] * rn + sgn[n];
;                     f32x4 den, rc;
; #pragma unroll
;                     for (int i = 0; i < 4; ++i) den[i] = __builtin_amdgcn_exp2f(ex[i]);
;                     den = den + 1.0f;
; #pragma unroll
;                     for (int i = 0; i < 4; ++i) rc[i] = __builtin_amdgcn_rcpf(den[i]);
;                     o[n] = (gt * up) * rc; }
;                 u32x4 w; w.x = pk2(o[0][0], o[0][1]); w.y = pk2(o[0][2], o[0][3]); w.z = pk2(o[1][0], o[1][1]); w.w = pk2(o[1][2], o[1][3]);
;                 *(u32x4*)(tb + lo + (unsigned)(ai * HALF + m * 16) * (DFF * 2)) = w; }
	v_pk_add_f32 v[32:33], v[32:33], 1.0 op_sel_hi:[1,0]
	v_fmamk_f32 v148, v188, 0x30000000, v231
	global_store_dwordx4 v[44:45], v[34:37], off
	v_rcp_f32_e32 v32, v32
	v_rcp_f32_e32 v33, v33
	v_pk_add_f32 v[36:37], v[42:43], 1.0 op_sel_hi:[1,0]
	v_rcp_f32_e32 v30, v30
	v_rcp_f32_e32 v31, v31
	v_rsq_f32_e32 v148, v148
	v_rcp_f32_e32 v36, v36
	v_rcp_f32_e32 v37, v37
	v_pk_fma_f32 v[24:25], v[24:25], v[158:159], v[88:89] op_sel_hi:[1,0,1]
	v_pk_fma_f32 v[22:23], v[22:23], v[158:159], v[86:87] op_sel_hi:[1,0,1]
	v_pk_fma_f32 v[20:21], v[20:21], v[158:159], v[84:85] op_sel_hi:[1,0,1]
	v_pk_fma_f32 v[18:19], v[18:19], v[158:159], v[82:83] op_sel_hi:[1,0,1]
	v_pk_mul_f32 v[20:21], v[24:25], v[20:21]
	v_pk_mul_f32 v[18:19], v[22:23], v[18:19]
	v_pk_mul_f32 v[22:23], v[20:21], v[30:31]
	v_pk_mul_f32 v[20:21], v[18:19], v[32:33]
	v_pk_mul_f32 v[26:27], v[26:27], v[36:37]
	v_cvt_pk_bf16_f32 v20, v20, v21
	v_cvt_pk_bf16_f32 v21, v22, v23
	v_mul_f32_e32 v22, 0xbfb8aa3b, v148
	v_cvt_pk_bf16_f32 v18, v26, v27
	v_pk_mul_f32 v[26:27], v[14:15], v[22:23] op_sel_hi:[1,0]
	v_exp_f32_e32 v41, v39
	v_pk_mul_f32 v[24:25], v[16:17], v[22:23] op_sel_hi:[1,0]
	v_add_f32_e32 v23, v156, v26
	v_exp_f32_e32 v26, v23
	v_add_f32_e32 v23, v157, v27
	v_exp_f32_e32 v27, v23
	v_add_f32_e32 v23, v154, v24
	v_exp_f32_e32 v24, v23
	v_add_f32_e32 v23, v155, v25
	v_pk_fma_f32 v[16:17], v[16:17], v[148:149], v[104:105] op_sel_hi:[1,0,1]
	v_pk_fma_f32 v[14:15], v[14:15], v[148:149], v[102:103] op_sel_hi:[1,0,1]
	v_pk_fma_f32 v[12:13], v[12:13], v[148:149], v[100:101] op_sel_hi:[1,0,1]
	v_pk_fma_f32 v[10:11], v[10:11], v[148:149], v[98:99] op_sel_hi:[1,0,1]
	v_pk_add_f32 v[34:35], v[40:41], 1.0 op_sel_hi:[1,0]
	v_pk_mul_f32 v[10:11], v[14:15], v[10:11]
	v_pk_mul_f32 v[12:13], v[16:17], v[12:13]
	v_pk_mul_f32 v[14:15], v[8:9], v[22:23] op_sel_hi:[1,0]
	v_pk_mul_f32 v[16:17], v[6:7], v[22:23] op_sel_hi:[1,0]
	v_rcp_f32_e32 v34, v34
	v_rcp_f32_e32 v35, v35
	v_add_f32_e32 v16, v152, v16
	v_add_f32_e32 v17, v153, v17
	v_add_f32_e32 v14, v150, v14
	v_add_f32_e32 v15, v151, v15
	v_exp_f32_e32 v16, v16
	v_exp_f32_e32 v14, v14
	v_exp_f32_e32 v15, v15
	v_exp_f32_e32 v17, v17
	v_exp_f32_e32 v25, v23
	v_pk_mul_f32 v[28:29], v[28:29], v[34:35]
	s_mov_b32 s30, 0x1ae000
	v_cvt_pk_bf16_f32 v19, v28, v29
	v_add_co_u32_e32 v28, vcc, s30, v146
	v_pk_add_f32 v[14:15], v[14:15], 1.0 op_sel_hi:[1,0]
	v_pk_add_f32 v[16:17], v[16:17], 1.0 op_sel_hi:[1,0]
	v_addc_co_u32_e32 v29, vcc, 0, v147, vcc
	v_rcp_f32_e32 v16, v16
	v_rcp_f32_e32 v17, v17
	v_rcp_f32_e32 v14, v14
	v_rcp_f32_e32 v15, v15
	global_store_dwordx4 v[28:29], v[18:21], off
	v_pk_fma_f32 v[8:9], v[8:9], v[148:149], v[88:89] op_sel_hi:[1,0,1]
	v_pk_fma_f32 v[6:7], v[6:7], v[148:149], v[86:87] op_sel_hi:[1,0,1]
	v_pk_add_f32 v[18:19], v[24:25], 1.0 op_sel_hi:[1,0]
	v_pk_add_f32 v[20:21], v[26:27], 1.0 op_sel_hi:[1,0]
	v_rcp_f32_e32 v18, v18
	v_rcp_f32_e32 v20, v20
	v_rcp_f32_e32 v21, v21
	v_rcp_f32_e32 v19, v19
	v_pk_fma_f32 v[4:5], v[4:5], v[148:149], v[84:85] op_sel_hi:[1,0,1]
	v_pk_fma_f32 v[2:3], v[2:3], v[148:149], v[82:83] op_sel_hi:[1,0,1]
	v_pk_mul_f32 v[4:5], v[8:9], v[4:5]
	v_pk_mul_f32 v[2:3], v[6:7], v[2:3]
	v_pk_mul_f32 v[6:7], v[4:5], v[14:15]
	v_pk_mul_f32 v[4:5], v[2:3], v[16:17]
	v_pk_mul_f32 v[12:13], v[12:13], v[18:19]
	v_cvt_pk_bf16_f32 v4, v4, v5
	v_cvt_pk_bf16_f32 v5, v6, v7
	v_add_co_u32_e32 v6, vcc, 0x1d9000, v146
	v_pk_mul_f32 v[10:11], v[10:11], v[20:21]
	s_nop 0
	v_addc_co_u32_e32 v7, vcc, 0, v147, vcc
	v_cvt_pk_bf16_f32 v2, v10, v11
	v_cvt_pk_bf16_f32 v3, v12, v13
	s_andn2_b64 vcc, exec, s[38:39]
	s_mov_b64 s[30:31], -1
	global_store_dwordx4 v[6:7], v[2:5], off
	s_cbranch_vccnz .LBB0_215
	s_andn2_b64 vcc, exec, s[44:45]
	v_mov_b64 v[2:3], 0
	v_mov_b64 v[4:5], 0
	s_cbranch_vccnz .LBB0_214
	s_branch .LBB0_214

; #define PG8_STAGEX(rs, bufoff, soff, voff) do { _Pragma("unroll") for (int _i = 0; _i < 2; ++_i) \
;         __builtin_amdgcn_raw_ptr_buffer_load_lds(rs, (LAS unsigned*)(lds + (bufoff) + ldsw + _i * 8192), 16, (voff)[_i], (soff), 0, 0); } while (0)
; #define PG8_LDA(dst, b, h) do { _Pragma("unroll") for (int m = 0; m < 4; ++m) _Pragma("unroll") for (int k = 0; k < 2; ++k) dst[m][k] = *(const LAS bf16x8*)(lds + PG8_SA(b, h) + aoff + m * 2048 + k * 1024); } while (0)
; #define PG8_LDB(dst, b, h) do { _Pragma("unroll") for (int n = 0; n < 2; ++n) _Pragma("unroll") for (int k = 0; k < 2; ++k) dst[n][k] = *(const LAS bf16x8*)(lds + PG8_SB(b, h) + boff + n * 2048 + k * 1024); } while (0)
; #define PG8_WAIT_V(n) asm volatile("s_waitcnt vmcnt(" #n ")" ::: "memory")
; #define PG8_WAIT_L(n) asm volatile("s_waitcnt lgkmcnt(" #n ")" ::: "memory")
; #define PG8_BAR __builtin_amdgcn_s_barrier()
;     ...
;         bool has_next; if constexpr (QV == 2) has_next = S.next_tail(ui + 1, nxt); else has_next = S.next(ui + 1, nxt);
;         const unsigned nA = has_next ? (unsigned)nxt.pm * tstepA + nxt.aoff : cA, nB = has_next ? (unsigned)nxt.pn * tstepB + nxt.boff : cB;
;         if constexpr (QV == 0) {
; #pragma nounroll
;         for (int t = 0; t < nt; t += 2) {
;             const bool last = (t == nt - 2);
;             const unsigned a1 = cA + (unsigned)(t + 1) * kstep;
;             const unsigned a2 = last ? nA : cA + (unsigned)(t + 2) * kstep, b2 = last ? nB : cB + (unsigned)(t + 2) * kstep;
;             const unsigned a3 = a2 + kstep, b3 = b2 + kstep;
;             PG8_LDB(B0, 0, 0); PG8_LDB(B1, 0, 1); PG8_SCHED; PG8_LDA(At, 0, 0); PG8_STAGEX(rsA, PG8_SA(1, 1), a1 + hstepA, voffA);
;             PG8_WAIT_V(8); PG8_WAIT_L(0); PG8_BAR; PG8_MMA(0, 0, At, B0); PG8_MMA(0, 1, At, B1); PG8_BAR; PG8_SCHED;
;     ...
;         if (!cur.keep) {
; #pragma unroll
;             for (int a = 0; a < 2; ++a)
; #pragma unroll
;                 for (int b = 0; b < 2; ++b)
; #pragma unroll
;                     for (int m = 0; m < 4; ++m)
; #pragma unroll
;                         for (int n = 0; n < 2; ++n) { f32x2 z0, z1; asm("v_mov_b64 %0, 0\n\tv_mov_b64 %1, 0" : "=v"(z0), "=v"(z1));
;                     acc[a][b][m][n] = __builtin_shufflevector(z0, z1, 0, 1, 2, 3); }
;         }
;         cur = nxt; cA = nA; cB = nB; ++ui;
;         if (wr == 1) PG8_BAR;
.LBB0_436:
	s_lshl_b32 s26, s25, 20
	s_and_b64 s[30:31], s[48:49], exec
	s_cselect_b32 s2, s26, s7
	s_lshl_b32 s27, s24, 20
	s_and_b64 s[30:31], s[48:49], exec
	s_waitcnt vmcnt(15)
	v_mov_b64_e32 v[28:29], v[8:9]
	v_mov_b64_e32 v[2:3], v[6:7]
	v_mov_b64_e32 v[20:21], v[8:9]
	v_mov_b64_e32 v[12:13], v[8:9]
	v_mov_b64_e32 v[24:25], v[8:9]
	v_mov_b64_e32 v[16:17], v[8:9]
	v_mov_b64_e32 v[32:33], v[8:9]
	v_mov_b64_e32 v[76:77], v[8:9]
	v_mov_b64_e32 v[92:93], v[8:9]
	v_mov_b64_e32 v[68:69], v[8:9]
	v_mov_b64_e32 v[84:85], v[8:9]
	v_mov_b64_e32 v[72:73], v[8:9]
	v_mov_b64_e32 v[88:89], v[8:9]
	v_mov_b64_e32 v[80:81], v[8:9]
	v_mov_b64_e32 v[96:97], v[8:9]
	v_mov_b64_e32 v[44:45], v[8:9]
	v_mov_b64_e32 v[60:61], v[8:9]
	v_mov_b64_e32 v[36:37], v[8:9]
	v_mov_b64_e32 v[52:53], v[8:9]
	v_mov_b64_e32 v[40:41], v[8:9]
	v_mov_b64_e32 v[56:57], v[8:9]
	v_mov_b64_e32 v[48:49], v[8:9]
	v_mov_b64_e32 v[64:65], v[8:9]
	v_mov_b64_e32 v[108:109], v[8:9]
	v_mov_b64_e32 v[124:125], v[8:9]
	v_mov_b64_e32 v[100:101], v[8:9]
	v_mov_b64_e32 v[116:117], v[8:9]
	v_mov_b64_e32 v[104:105], v[8:9]
	v_mov_b64_e32 v[120:121], v[8:9]
	v_mov_b64_e32 v[112:113], v[8:9]
	v_mov_b64_e32 v[128:129], v[8:9]
	s_cselect_b32 s5, s27, s28
	s_add_i32 s7, s7, 0x80080
	s_addk_i32 s28, 0x100
	s_mov_b32 s29, -2
	v_mov_b64_e32 v[26:27], v[6:7]
	v_mov_b64_e32 v[4:5], v[8:9]
	v_mov_b64_e32 v[18:19], v[6:7]
	v_mov_b64_e32 v[10:11], v[6:7]
	v_mov_b64_e32 v[22:23], v[6:7]
	v_mov_b64_e32 v[14:15], v[6:7]
	v_mov_b64_e32 v[30:31], v[6:7]
	v_mov_b64_e32 v[74:75], v[6:7]
	v_mov_b64_e32 v[90:91], v[6:7]
	v_mov_b64_e32 v[66:67], v[6:7]
	v_mov_b64_e32 v[82:83], v[6:7]
	v_mov_b64_e32 v[70:71], v[6:7]
	v_mov_b64_e32 v[86:87], v[6:7]
	v_mov_b64_e32 v[78:79], v[6:7]
	v_mov_b64_e32 v[94:95], v[6:7]
	v_mov_b64_e32 v[42:43], v[6:7]
	v_mov_b64_e32 v[58:59], v[6:7]
	v_mov_b64_e32 v[34:35], v[6:7]
	v_mov_b64_e32 v[50:51], v[6:7]
	v_mov_b64_e32 v[38:39], v[6:7]
	v_mov_b64_e32 v[54:55], v[6:7]
	v_mov_b64_e32 v[46:47], v[6:7]
	v_mov_b64_e32 v[62:63], v[6:7]
	v_mov_b64_e32 v[106:107], v[6:7]
	v_mov_b64_e32 v[122:123], v[6:7]
	v_mov_b64_e32 v[98:99], v[6:7]
	v_mov_b64_e32 v[114:115], v[6:7]
	v_mov_b64_e32 v[102:103], v[6:7]
	v_mov_b64_e32 v[118:119], v[6:7]
	v_mov_b64_e32 v[110:111], v[6:7]
	v_mov_b64_e32 v[126:127], v[6:7]
	s_cmp_eq_u32 s21, 1
	s_cbranch_scc1 .Lrst_skip_437
	s_andn2_b64 vcc, exec, s[70:71]
	s_cbranch_vccnz .Lrst_skip_437
	s_barrier
.Lrst_skip_437:
.LBB0_437:
	v_add_u32_e32 v142, 0x10000, v220
	v_add_u32_e32 v158, 0x14000, v220
	ds_read_b128 v[130:133], v142
	ds_read_b128 v[134:137], v142 offset:1024
	ds_read_b128 v[138:141], v142 offset:2048
	ds_read_b128 v[142:145], v142 offset:3072
	ds_read_b128 v[146:149], v158
	ds_read_b128 v[150:153], v158 offset:1024
	ds_read_b128 v[154:157], v158 offset:2048
	ds_read_b128 v[158:161], v158 offset:3072
	s_add_i32 s30, s7, 0xfff80080
	s_cmp_eq_u32 s29, 28
	s_cselect_b32 s50, s2, s30
	s_cselect_b32 s31, s5, s28
	s_or_b32 s30, s50, 0x80
	s_mov_b32 m0, s20
	ds_read_b128 v[162:165], v221
	ds_read_b128 v[170:173], v221 offset:1024
	ds_read_b128 v[182:185], v221 offset:2048
	ds_read_b128 v[186:189], v221 offset:3072
	ds_read_b128 v[190:193], v221 offset:4096
	ds_read_b128 v[194:197], v221 offset:5120
	ds_read_b128 v[198:201], v221 offset:6144
	ds_read_b128 v[202:205], v221 offset:7168
	buffer_load_dwordx4 v178, s[76:79], s7 offen lds
	s_mov_b32 m0, s22
	s_nop 0
	buffer_load_dwordx4 v210, s[76:79], s7 offen lds
	s_waitcnt vmcnt(8)
	s_waitcnt lgkmcnt(0)
	s_setprio 1
	s_barrier
	v_mfma_f32_16x16x32_bf16 v[126:129], v[130:133], v[162:165], v[126:129]
	v_mfma_f32_16x16x32_bf16 v[110:113], v[138:141], v[162:165], v[110:113]
	v_mfma_f32_16x16x32_bf16 v[118:121], v[130:133], v[182:185], v[118:121]
	v_mfma_f32_16x16x32_bf16 v[102:105], v[138:141], v[182:185], v[102:105]
	v_mfma_f32_16x16x32_bf16 v[114:117], v[130:133], v[190:193], v[114:117]
	v_mfma_f32_16x16x32_bf16 v[98:101], v[138:141], v[190:193], v[98:101]
	v_mfma_f32_16x16x32_bf16 v[122:125], v[130:133], v[198:201], v[122:125]
	v_mfma_f32_16x16x32_bf16 v[106:109], v[138:141], v[198:201], v[106:109]
	v_mfma_f32_16x16x32_bf16 v[126:129], v[134:137], v[170:173], v[126:129]
	v_mfma_f32_16x16x32_bf16 v[110:113], v[142:145], v[170:173], v[110:113]
	v_mfma_f32_16x16x32_bf16 v[118:121], v[134:137], v[186:189], v[118:121]
	v_mfma_f32_16x16x32_bf16 v[102:105], v[142:145], v[186:189], v[102:105]
	v_mfma_f32_16x16x32_bf16 v[114:117], v[134:137], v[194:197], v[114:117]
	v_mfma_f32_16x16x32_bf16 v[98:101], v[142:145], v[194:197], v[98:101]
	v_mfma_f32_16x16x32_bf16 v[122:125], v[134:137], v[202:205], v[122:125]
	v_mfma_f32_16x16x32_bf16 v[106:109], v[142:145], v[202:205], v[106:109]
	v_mfma_f32_16x16x32_bf16 v[62:65], v[146:149], v[162:165], v[62:65]
	v_mfma_f32_16x16x32_bf16 v[46:49], v[154:157], v[162:165], v[46:49]
	v_mfma_f32_16x16x32_bf16 v[54:57], v[146:149], v[182:185], v[54:57]
	v_mfma_f32_16x16x32_bf16 v[38:41], v[154:157], v[182:185], v[38:41]
	v_mfma_f32_16x16x32_bf16 v[50:53], v[146:149], v[190:193], v[50:53]
	v_mfma_f32_16x16x32_bf16 v[34:37], v[154:157], v[190:193], v[34:37]
	v_mfma_f32_16x16x32_bf16 v[58:61], v[146:149], v[198:201], v[58:61]
	v_mfma_f32_16x16x32_bf16 v[42:45], v[154:157], v[198:201], v[42:45]
	v_mfma_f32_16x16x32_bf16 v[62:65], v[150:153], v[170:173], v[62:65]
	v_mfma_f32_16x16x32_bf16 v[46:49], v[158:161], v[170:173], v[46:49]
	v_mfma_f32_16x16x32_bf16 v[54:57], v[150:153], v[186:189], v[54:57]
	v_mfma_f32_16x16x32_bf16 v[38:41], v[158:161], v[186:189], v[38:41]
	v_mfma_f32_16x16x32_bf16 v[50:53], v[150:153], v[194:197], v[50:53]
	v_mfma_f32_16x16x32_bf16 v[34:37], v[158:161], v[194:197], v[34:37]
	v_mfma_f32_16x16x32_bf16 v[58:61], v[150:153], v[202:205], v[58:61]
	v_mfma_f32_16x16x32_bf16 v[42:45], v[158:161], v[202:205], v[42:45]
	s_barrier
; #define PG8_STAGEX(rs, bufoff, soff, voff) do { _Pragma("unroll") for (int _i = 0; _i < 2; ++_i) \
;         __builtin_amdgcn_raw_ptr_buffer_load_lds(rs, (LAS unsigned*)(lds + (bufoff) + ldsw + _i * 8192), 16, (voff)[_i], (soff), 0, 0); } while (0)
; #define PG8_LDA(dst, b, h) do { _Pragma("unroll") for (int m = 0; m < 4; ++m) _Pragma("unroll") for (int k = 0; k < 2; ++k) dst[m][k] = *(const LAS bf16x8*)(lds + PG8_SA(b, h) + aoff + m * 2048 + k * 1024); } while (0)
; #define PG8_LDB(dst, b, h) do { _Pragma("unroll") for (int n = 0; n < 2; ++n) _Pragma("unroll") for (int k = 0; k < 2; ++k) dst[n][k] = *(const LAS bf16x8*)(lds + PG8_SB(b, h) + boff + n * 2048 + k * 1024); } while (0)
; #define PG8_WAIT_V(n) asm volatile("s_waitcnt vmcnt(" #n ")" ::: "memory")
; #define PG8_WAIT_L(n) asm volatile("s_waitcnt lgkmcnt(" #n ")" ::: "memory")
; #define PG8_BAR __builtin_amdgcn_s_barrier()
; #define PG8_SCHED __builtin_amdgcn_sched_barrier(0)
;     ...
;             PG8_LDB(B0, 0, 0); PG8_LDB(B1, 0, 1); PG8_SCHED; PG8_LDA(At, 0, 0); PG8_STAGEX(rsA, PG8_SA(1, 1), a1 + hstepA, voffA);
;             PG8_WAIT_V(8); PG8_WAIT_L(0); PG8_BAR; PG8_MMA(0, 0, At, B0); PG8_MMA(0, 1, At, B1); PG8_BAR; PG8_SCHED;
;             PG8_LDA(At, 0, 1); PG8_STAGEX(rsB, PG8_SB(0, 0), b2, voffB); PG8_STAGEX(rsB, PG8_SB(0, 1), b2 + hstepB, voffB); PG8_STAGEX(rsA, PG8_SA(0, 0), a2, voffA);
;             PG8_WAIT_V(8); PG8_WAIT_L(0); PG8_BAR; PG8_MMA(1, 0, At, B0); PG8_MMA(1, 1, At, B1); PG8_BAR; PG8_SCHED;
;             PG8_LDB(B0, 1, 0); PG8_LDB(B1, 1, 1); PG8_SCHED; PG8_LDA(At, 1, 0); PG8_STAGEX(rsA, PG8_SA(0, 1), a2 + hstepA, voffA);
;             PG8_WAIT_V(8); PG8_WAIT_L(0); PG8_BAR; PG8_MMA(0, 0, At, B0); PG8_MMA(0, 1, At, B1); PG8_BAR; PG8_SCHED;
;             PG8_LDA(At, 1, 1); PG8_STAGEX(rsB, PG8_SB(1, 0), b3, voffB); PG8_STAGEX(rsB, PG8_SB(1, 1), b3 + hstepB, voffB); PG8_STAGEX(rsA, PG8_SA(1, 0), a3, voffA);
;             PG8_WAIT_V(8); PG8_WAIT_L(0); PG8_BAR; PG8_MMA(1, 0, At, B0); PG8_MMA(1, 1, At, B1); PG8_BAR; PG8_SCHED;
	s_setprio 0
	s_mov_b32 m0, s90
	s_mov_b32 s58, s78
	s_mov_b32 s59, s79
	ds_read_b128 v[162:165], v221 offset:16384
	ds_read_b128 v[170:173], v221 offset:17408
	ds_read_b128 v[182:185], v221 offset:18432
	ds_read_b128 v[186:189], v221 offset:19456
	ds_read_b128 v[190:193], v221 offset:20480
	ds_read_b128 v[194:197], v221 offset:21504
	ds_read_b128 v[198:201], v221 offset:22528
	ds_read_b128 v[202:205], v221 offset:23552
	buffer_load_dwordx4 v179, s[56:59], s31 offen lds
	s_mov_b32 m0, s91
	s_add_i32 s51, s31, 0x80000
	buffer_load_dwordx4 v211, s[56:59], s31 offen lds
	s_mov_b32 m0, s9
	s_nop 0
	buffer_load_dwordx4 v179, s[56:59], s51 offen lds
	s_mov_b32 m0, s10
	s_nop 0
	buffer_load_dwordx4 v211, s[56:59], s51 offen lds
	s_mov_b32 m0, s89
	s_nop 0
	buffer_load_dwordx4 v178, s[76:79], s50 offen lds
	s_mov_b32 m0, s11
	s_nop 0
	buffer_load_dwordx4 v210, s[76:79], s50 offen lds
	s_waitcnt vmcnt(8)
	s_waitcnt lgkmcnt(0)
	s_setprio 1
	s_barrier
	v_mfma_f32_16x16x32_bf16 v[94:97], v[130:133], v[162:165], v[94:97]
	v_mfma_f32_16x16x32_bf16 v[78:81], v[138:141], v[162:165], v[78:81]
	v_mfma_f32_16x16x32_bf16 v[86:89], v[130:133], v[182:185], v[86:89]
	v_mfma_f32_16x16x32_bf16 v[70:73], v[138:141], v[182:185], v[70:73]
	v_mfma_f32_16x16x32_bf16 v[82:85], v[130:133], v[190:193], v[82:85]
	v_mfma_f32_16x16x32_bf16 v[66:69], v[138:141], v[190:193], v[66:69]
	v_mfma_f32_16x16x32_bf16 v[90:93], v[130:133], v[198:201], v[90:93]
	v_mfma_f32_16x16x32_bf16 v[74:77], v[138:141], v[198:201], v[74:77]
	v_mfma_f32_16x16x32_bf16 v[94:97], v[134:137], v[170:173], v[94:97]
	v_mfma_f32_16x16x32_bf16 v[78:81], v[142:145], v[170:173], v[78:81]
	v_mfma_f32_16x16x32_bf16 v[86:89], v[134:137], v[186:189], v[86:89]
	v_mfma_f32_16x16x32_bf16 v[70:73], v[142:145], v[186:189], v[70:73]
	v_mfma_f32_16x16x32_bf16 v[82:85], v[134:137], v[194:197], v[82:85]
	v_mfma_f32_16x16x32_bf16 v[66:69], v[142:145], v[194:197], v[66:69]
	v_mfma_f32_16x16x32_bf16 v[90:93], v[134:137], v[202:205], v[90:93]
	v_mfma_f32_16x16x32_bf16 v[74:77], v[142:145], v[202:205], v[74:77]
	v_mfma_f32_16x16x32_bf16 v[30:33], v[146:149], v[162:165], v[30:33]
	v_mfma_f32_16x16x32_bf16 v[14:17], v[154:157], v[162:165], v[14:17]
	v_mfma_f32_16x16x32_bf16 v[22:25], v[146:149], v[182:185], v[22:25]
	v_mfma_f32_16x16x32_bf16 v[10:13], v[154:157], v[182:185], v[10:13]
	v_mfma_f32_16x16x32_bf16 v[18:21], v[146:149], v[190:193], v[18:21]
	v_mfma_f32_16x16x32_bf16 v[2:5], v[154:157], v[190:193], v[2:5]
	v_mfma_f32_16x16x32_bf16 v[26:29], v[146:149], v[198:201], v[26:29]
	v_mfma_f32_16x16x32_bf16 v[6:9], v[154:157], v[198:201], v[6:9]
	v_mfma_f32_16x16x32_bf16 v[30:33], v[150:153], v[170:173], v[30:33]
	v_mfma_f32_16x16x32_bf16 v[14:17], v[158:161], v[170:173], v[14:17]
	v_mfma_f32_16x16x32_bf16 v[22:25], v[150:153], v[186:189], v[22:25]
	v_mfma_f32_16x16x32_bf16 v[10:13], v[158:161], v[186:189], v[10:13]
	v_mfma_f32_16x16x32_bf16 v[18:21], v[150:153], v[194:197], v[18:21]
	v_mfma_f32_16x16x32_bf16 v[2:5], v[158:161], v[194:197], v[2:5]
	v_mfma_f32_16x16x32_bf16 v[26:29], v[150:153], v[202:205], v[26:29]
	v_mfma_f32_16x16x32_bf16 v[6:9], v[158:161], v[202:205], v[6:9]
	s_barrier
	s_setprio 0
	v_add_u32_e32 v142, 0x18000, v220
	v_add_u32_e32 v158, 0x1c000, v220
	ds_read_b128 v[130:133], v142
	ds_read_b128 v[134:137], v142 offset:1024
	ds_read_b128 v[138:141], v142 offset:2048
	ds_read_b128 v[142:145], v142 offset:3072
	ds_read_b128 v[146:149], v158
	ds_read_b128 v[150:153], v158 offset:1024
	ds_read_b128 v[154:157], v158 offset:2048
	ds_read_b128 v[158:161], v158 offset:3072
	s_add_i32 s50, s50, 0x80000
	s_mov_b32 m0, s74
	ds_read_b128 v[162:165], v221 offset:32768
	ds_read_b128 v[170:173], v221 offset:33792
	ds_read_b128 v[182:185], v221 offset:34816
	ds_read_b128 v[186:189], v221 offset:35840
	ds_read_b128 v[190:193], v221 offset:36864
	ds_read_b128 v[194:197], v221 offset:37888
	ds_read_b128 v[198:201], v221 offset:38912
	ds_read_b128 v[202:205], v221 offset:39936
	buffer_load_dwordx4 v178, s[76:79], s50 offen lds
	s_mov_b32 m0, s12
	s_nop 0
	buffer_load_dwordx4 v210, s[76:79], s50 offen lds
	s_waitcnt vmcnt(8)
	s_waitcnt lgkmcnt(0)
	s_setprio 1
	s_barrier
; #define PG8_STAGEX(rs, bufoff, soff, voff) do { _Pragma("unroll") for (int _i = 0; _i < 2; ++_i) \
;         __builtin_amdgcn_raw_ptr_buffer_load_lds(rs, (LAS unsigned*)(lds + (bufoff) + ldsw + _i * 8192), 16, (voff)[_i], (soff), 0, 0); } while (0)
; #define PG8_LDA(dst, b, h) do { _Pragma("unroll") for (int m = 0; m < 4; ++m) _Pragma("unroll") for (int k = 0; k < 2; ++k) dst[m][k] = *(const LAS bf16x8*)(lds + PG8_SA(b, h) + aoff + m * 2048 + k * 1024); } while (0)
; #define PG8_LDB(dst, b, h) do { _Pragma("unroll") for (int n = 0; n < 2; ++n) _Pragma("unroll") for (int k = 0; k < 2; ++k) dst[n][k] = *(const LAS bf16x8*)(lds + PG8_SB(b, h) + boff + n * 2048 + k * 1024); } while (0)
; #define PG8_WAIT_V(n) asm volatile("s_waitcnt vmcnt(" #n ")" ::: "memory")
; #define PG8_WAIT_L(n) asm volatile("s_waitcnt lgkmcnt(" #n ")" ::: "memory")
; #define PG8_BAR __builtin_amdgcn_s_barrier()
; #define PG8_SCHED __builtin_amdgcn_sched_barrier(0)
;     ...
;             PG8_LDB(B0, 1, 0); PG8_LDB(B1, 1, 1); PG8_SCHED; PG8_LDA(At, 1, 0); PG8_STAGEX(rsA, PG8_SA(0, 1), a2 + hstepA, voffA);
;             PG8_WAIT_V(8); PG8_WAIT_L(0); PG8_BAR; PG8_MMA(0, 0, At, B0); PG8_MMA(0, 1, At, B1); PG8_BAR; PG8_SCHED;
;             PG8_LDA(At, 1, 1); PG8_STAGEX(rsB, PG8_SB(1, 0), b3, voffB); PG8_STAGEX(rsB, PG8_SB(1, 1), b3 + hstepB, voffB); PG8_STAGEX(rsA, PG8_SA(1, 0), a3, voffA);
;             PG8_WAIT_V(8); PG8_WAIT_L(0); PG8_BAR; PG8_MMA(1, 0, At, B0); PG8_MMA(1, 1, At, B1); PG8_BAR; PG8_SCHED;
;     ...
;         if (wr == 0) PG8_BAR;
	v_mfma_f32_16x16x32_bf16 v[126:129], v[130:133], v[162:165], v[126:129]
	v_mfma_f32_16x16x32_bf16 v[110:113], v[138:141], v[162:165], v[110:113]
	v_mfma_f32_16x16x32_bf16 v[118:121], v[130:133], v[182:185], v[118:121]
	v_mfma_f32_16x16x32_bf16 v[102:105], v[138:141], v[182:185], v[102:105]
	v_mfma_f32_16x16x32_bf16 v[114:117], v[130:133], v[190:193], v[114:117]
	v_mfma_f32_16x16x32_bf16 v[98:101], v[138:141], v[190:193], v[98:101]
	v_mfma_f32_16x16x32_bf16 v[122:125], v[130:133], v[198:201], v[122:125]
	v_mfma_f32_16x16x32_bf16 v[106:109], v[138:141], v[198:201], v[106:109]
	v_mfma_f32_16x16x32_bf16 v[126:129], v[134:137], v[170:173], v[126:129]
	v_mfma_f32_16x16x32_bf16 v[110:113], v[142:145], v[170:173], v[110:113]
	v_mfma_f32_16x16x32_bf16 v[118:121], v[134:137], v[186:189], v[118:121]
	v_mfma_f32_16x16x32_bf16 v[102:105], v[142:145], v[186:189], v[102:105]
	v_mfma_f32_16x16x32_bf16 v[114:117], v[134:137], v[194:197], v[114:117]
	v_mfma_f32_16x16x32_bf16 v[98:101], v[142:145], v[194:197], v[98:101]
	v_mfma_f32_16x16x32_bf16 v[122:125], v[134:137], v[202:205], v[122:125]
	v_mfma_f32_16x16x32_bf16 v[106:109], v[142:145], v[202:205], v[106:109]
	v_mfma_f32_16x16x32_bf16 v[62:65], v[146:149], v[162:165], v[62:65]
	v_mfma_f32_16x16x32_bf16 v[46:49], v[154:157], v[162:165], v[46:49]
	v_mfma_f32_16x16x32_bf16 v[54:57], v[146:149], v[182:185], v[54:57]
	v_mfma_f32_16x16x32_bf16 v[38:41], v[154:157], v[182:185], v[38:41]
	v_mfma_f32_16x16x32_bf16 v[50:53], v[146:149], v[190:193], v[50:53]
	v_mfma_f32_16x16x32_bf16 v[34:37], v[154:157], v[190:193], v[34:37]
	v_mfma_f32_16x16x32_bf16 v[58:61], v[146:149], v[198:201], v[58:61]
	v_mfma_f32_16x16x32_bf16 v[42:45], v[154:157], v[198:201], v[42:45]
	v_mfma_f32_16x16x32_bf16 v[62:65], v[150:153], v[170:173], v[62:65]
	v_mfma_f32_16x16x32_bf16 v[46:49], v[158:161], v[170:173], v[46:49]
	v_mfma_f32_16x16x32_bf16 v[54:57], v[150:153], v[186:189], v[54:57]
	v_mfma_f32_16x16x32_bf16 v[38:41], v[158:161], v[186:189], v[38:41]
	v_mfma_f32_16x16x32_bf16 v[50:53], v[150:153], v[194:197], v[50:53]
	v_mfma_f32_16x16x32_bf16 v[34:37], v[158:161], v[194:197], v[34:37]
	v_mfma_f32_16x16x32_bf16 v[58:61], v[150:153], v[202:205], v[58:61]
	v_mfma_f32_16x16x32_bf16 v[42:45], v[158:161], v[202:205], v[42:45]
	s_barrier
	s_setprio 0
	s_mov_b32 m0, s13
	s_or_b32 s50, s31, 0x80
	ds_read_b128 v[162:165], v221 offset:49152
	ds_read_b128 v[170:173], v221 offset:50176
	ds_read_b128 v[182:185], v221 offset:51200
	ds_read_b128 v[186:189], v221 offset:52224
	ds_read_b128 v[190:193], v221 offset:53248
	ds_read_b128 v[194:197], v221 offset:54272
	ds_read_b128 v[198:201], v221 offset:55296
	ds_read_b128 v[202:205], v221 offset:56320
	buffer_load_dwordx4 v179, s[56:59], s50 offen lds
	s_mov_b32 m0, s14
	s_add_i32 s31, s31, 0x80080
	buffer_load_dwordx4 v211, s[56:59], s50 offen lds
	s_mov_b32 m0, s17
	s_nop 0
	buffer_load_dwordx4 v179, s[56:59], s31 offen lds
	s_mov_b32 m0, s18
	s_nop 0
	buffer_load_dwordx4 v211, s[56:59], s31 offen lds
	s_mov_b32 m0, s15
	s_nop 0
	buffer_load_dwordx4 v178, s[76:79], s30 offen lds
	s_mov_b32 m0, s16
	s_nop 0
	buffer_load_dwordx4 v210, s[76:79], s30 offen lds
	s_waitcnt vmcnt(8)
	s_waitcnt lgkmcnt(0)
	s_setprio 1
	s_barrier
	v_mfma_f32_16x16x32_bf16 v[94:97], v[130:133], v[162:165], v[94:97]
	v_mfma_f32_16x16x32_bf16 v[78:81], v[138:141], v[162:165], v[78:81]
	v_mfma_f32_16x16x32_bf16 v[86:89], v[130:133], v[182:185], v[86:89]
	v_mfma_f32_16x16x32_bf16 v[70:73], v[138:141], v[182:185], v[70:73]
	v_mfma_f32_16x16x32_bf16 v[82:85], v[130:133], v[190:193], v[82:85]
	v_mfma_f32_16x16x32_bf16 v[66:69], v[138:141], v[190:193], v[66:69]
	v_mfma_f32_16x16x32_bf16 v[90:93], v[130:133], v[198:201], v[90:93]
	v_mfma_f32_16x16x32_bf16 v[74:77], v[138:141], v[198:201], v[74:77]
	v_mfma_f32_16x16x32_bf16 v[94:97], v[134:137], v[170:173], v[94:97]
	v_mfma_f32_16x16x32_bf16 v[78:81], v[142:145], v[170:173], v[78:81]
	v_mfma_f32_16x16x32_bf16 v[86:89], v[134:137], v[186:189], v[86:89]
	v_mfma_f32_16x16x32_bf16 v[70:73], v[142:145], v[186:189], v[70:73]
	v_mfma_f32_16x16x32_bf16 v[82:85], v[134:137], v[194:197], v[82:85]
	v_mfma_f32_16x16x32_bf16 v[66:69], v[142:145], v[194:197], v[66:69]
	v_mfma_f32_16x16x32_bf16 v[90:93], v[134:137], v[202:205], v[90:93]
	v_mfma_f32_16x16x32_bf16 v[74:77], v[142:145], v[202:205], v[74:77]
	v_mfma_f32_16x16x32_bf16 v[30:33], v[146:149], v[162:165], v[30:33]
	v_mfma_f32_16x16x32_bf16 v[14:17], v[154:157], v[162:165], v[14:17]
	v_mfma_f32_16x16x32_bf16 v[22:25], v[146:149], v[182:185], v[22:25]
	v_mfma_f32_16x16x32_bf16 v[10:13], v[154:157], v[182:185], v[10:13]
	v_mfma_f32_16x16x32_bf16 v[18:21], v[146:149], v[190:193], v[18:21]
	v_mfma_f32_16x16x32_bf16 v[2:5], v[154:157], v[190:193], v[2:5]
	v_mfma_f32_16x16x32_bf16 v[26:29], v[146:149], v[198:201], v[26:29]
	v_mfma_f32_16x16x32_bf16 v[6:9], v[154:157], v[198:201], v[6:9]
	v_mfma_f32_16x16x32_bf16 v[30:33], v[150:153], v[170:173], v[30:33]
	v_mfma_f32_16x16x32_bf16 v[14:17], v[158:161], v[170:173], v[14:17]
	v_mfma_f32_16x16x32_bf16 v[22:25], v[150:153], v[186:189], v[22:25]
	v_mfma_f32_16x16x32_bf16 v[10:13], v[158:161], v[186:189], v[10:13]
	v_mfma_f32_16x16x32_bf16 v[18:21], v[150:153], v[194:197], v[18:21]
	v_mfma_f32_16x16x32_bf16 v[2:5], v[158:161], v[194:197], v[2:5]
	v_mfma_f32_16x16x32_bf16 v[26:29], v[150:153], v[202:205], v[26:29]
	v_mfma_f32_16x16x32_bf16 v[6:9], v[158:161], v[202:205], v[6:9]
	s_barrier
	s_setprio 0
	s_add_i32 s29, s29, 2
	s_addk_i32 s7, 0x100
	s_addk_i32 s28, 0x100
	s_cmp_gt_u32 s29, 29
	s_cbranch_scc0 .LBB0_437
	s_and_b64 vcc, exec, s[84:85]
	s_cbranch_vccz .LBB0_440
	s_barrier

; #define PG8_BAR __builtin_amdgcn_s_barrier()
;     ...
;         if (!has_next) break;
;         if (!cur.keep) {
; #pragma unroll
;             for (int a = 0; a < 2; ++a)
; #pragma unroll
;                 for (int b = 0; b < 2; ++b)
; #pragma unroll
;                     for (int m = 0; m < 4; ++m)
; #pragma unroll
;                         for (int n = 0; n < 2; ++n) { f32x2 z0, z1; asm("v_mov_b64 %0, 0\n\tv_mov_b64 %1, 0" : "=v"(z0), "=v"(z1));
;                     acc[a][b][m][n] = __builtin_shufflevector(z0, z1, 0, 1, 2, 3); }
;         }
;         cur = nxt; cA = nA; cB = nB; ++ui;
;         if (wr == 1) PG8_BAR;
.LBB0_534:
	v_readlane_b32 s82, v254, 31
	v_readlane_b32 s58, v254, 35
	s_andn2_b64 vcc, exec, s[48:49]
	s_mov_b64 s[30:31], -1
	v_readlane_b32 s83, v254, 32
	v_readlane_b32 s59, v254, 36
	s_cbranch_vccnz .LBB0_433
	s_andn2_b64 vcc, exec, s[70:71]
	v_mov_b64 v[6:7], 0
	v_mov_b64 v[8:9], 0
	s_cbranch_vccnz .LBB0_432
	s_branch .LBB0_432

; #define PG8_STAGEX(rs, bufoff, soff, voff) do { _Pragma("unroll") for (int _i = 0; _i < 2; ++_i) \
;         __builtin_amdgcn_raw_ptr_buffer_load_lds(rs, (LAS unsigned*)(lds + (bufoff) + ldsw + _i * 8192), 16, (voff)[_i], (soff), 0, 0); } while (0)
; #define PG8_LDA(dst, b, h) do { _Pragma("unroll") for (int m = 0; m < 4; ++m) _Pragma("unroll") for (int k = 0; k < 2; ++k) dst[m][k] = *(const LAS bf16x8*)(lds + PG8_SA(b, h) + aoff + m * 2048 + k * 1024); } while (0)
; #define PG8_LDB(dst, b, h) do { _Pragma("unroll") for (int n = 0; n < 2; ++n) _Pragma("unroll") for (int k = 0; k < 2; ++k) dst[n][k] = *(const LAS bf16x8*)(lds + PG8_SB(b, h) + boff + n * 2048 + k * 1024); } while (0)
; #define PG8_WAIT_V(n) asm volatile("s_waitcnt vmcnt(" #n ")" ::: "memory")
; #define PG8_WAIT_L(n) asm volatile("s_waitcnt lgkmcnt(" #n ")" ::: "memory")
; #define PG8_BAR __builtin_amdgcn_s_barrier()
;     ...
;         bool has_next; if constexpr (QV == 2) has_next = S.next_tail(ui + 1, nxt); else has_next = S.next(ui + 1, nxt);
;         const unsigned nA = has_next ? (unsigned)nxt.pm * tstepA + nxt.aoff : cA, nB = has_next ? (unsigned)nxt.pn * tstepB + nxt.boff : cB;
;         if constexpr (QV == 0) {
; #pragma nounroll
;         for (int t = 0; t < nt; t += 2) {
;             const bool last = (t == nt - 2);
;             const unsigned a1 = cA + (unsigned)(t + 1) * kstep;
;             const unsigned a2 = last ? nA : cA + (unsigned)(t + 2) * kstep, b2 = last ? nB : cB + (unsigned)(t + 2) * kstep;
;             const unsigned a3 = a2 + kstep, b3 = b2 + kstep;
;             PG8_LDB(B0, 0, 0); PG8_LDB(B1, 0, 1); PG8_SCHED; PG8_LDA(At, 0, 0); PG8_STAGEX(rsA, PG8_SA(1, 1), a1 + hstepA, voffA);
;             PG8_WAIT_V(8); PG8_WAIT_L(0); PG8_BAR; PG8_MMA(0, 0, At, B0); PG8_MMA(0, 1, At, B1); PG8_BAR; PG8_SCHED;
;     ...
;         if (!cur.keep) {
; #pragma unroll
;             for (int a = 0; a < 2; ++a)
; #pragma unroll
;                 for (int b = 0; b < 2; ++b)
; #pragma unroll
;                     for (int m = 0; m < 4; ++m)
; #pragma unroll
;                         for (int n = 0; n < 2; ++n) { f32x2 z0, z1; asm("v_mov_b64 %0, 0\n\tv_mov_b64 %1, 0" : "=v"(z0), "=v"(z1));
;                     acc[a][b][m][n] = __builtin_shufflevector(z0, z1, 0, 1, 2, 3); }
;         }
;         cur = nxt; cA = nA; cB = nB; ++ui;
;         if (wr == 1) PG8_BAR;
.LBB0_1273:
	s_lshl_b32 s65, s64, 20
	s_and_b64 s[30:31], s[38:39], exec
	s_cselect_b32 s30, s65, s62
	s_lshl_b32 s66, s59, 20
	s_and_b64 s[42:43], s[38:39], exec
	v_mov_b64_e32 v[8:9], v[4:5]
	v_mov_b64_e32 v[12:13], v[4:5]
	v_mov_b64_e32 v[16:17], v[4:5]
	v_mov_b64_e32 v[20:21], v[4:5]
	v_mov_b64_e32 v[24:25], v[4:5]
	s_waitcnt vmcnt(15)
	v_mov_b64_e32 v[28:29], v[4:5]
	v_mov_b64_e32 v[32:33], v[4:5]
	v_mov_b64_e32 v[68:69], v[4:5]
	v_mov_b64_e32 v[72:73], v[4:5]
	v_mov_b64_e32 v[76:77], v[4:5]
	v_mov_b64_e32 v[80:81], v[4:5]
	v_mov_b64_e32 v[84:85], v[4:5]
	v_mov_b64_e32 v[88:89], v[4:5]
	v_mov_b64_e32 v[92:93], v[4:5]
	v_mov_b64_e32 v[96:97], v[4:5]
	v_mov_b64_e32 v[36:37], v[4:5]
	v_mov_b64_e32 v[40:41], v[4:5]
	v_mov_b64_e32 v[44:45], v[4:5]
	v_mov_b64_e32 v[48:49], v[4:5]
	v_mov_b64_e32 v[52:53], v[4:5]
	v_mov_b64_e32 v[56:57], v[4:5]
	v_mov_b64_e32 v[60:61], v[4:5]
	v_mov_b64_e32 v[64:65], v[4:5]
	v_mov_b64_e32 v[100:101], v[4:5]
	v_mov_b64_e32 v[104:105], v[4:5]
	v_mov_b64_e32 v[108:109], v[4:5]
	v_mov_b64_e32 v[112:113], v[4:5]
	v_mov_b64_e32 v[116:117], v[4:5]
	v_mov_b64_e32 v[120:121], v[4:5]
	v_mov_b64_e32 v[124:125], v[4:5]
	v_mov_b64_e32 v[128:129], v[4:5]
	s_cselect_b32 s31, s66, s63
	s_add_i32 s62, s62, 0x80080
	s_addk_i32 s63, 0x100
	s_mov_b32 s67, -2
	v_mov_b64_e32 v[6:7], v[2:3]
	v_mov_b64_e32 v[10:11], v[2:3]
	v_mov_b64_e32 v[14:15], v[2:3]
	v_mov_b64_e32 v[18:19], v[2:3]
	v_mov_b64_e32 v[22:23], v[2:3]
	v_mov_b64_e32 v[26:27], v[2:3]
	v_mov_b64_e32 v[30:31], v[2:3]
	v_mov_b64_e32 v[66:67], v[2:3]
	v_mov_b64_e32 v[70:71], v[2:3]
	v_mov_b64_e32 v[74:75], v[2:3]
	v_mov_b64_e32 v[78:79], v[2:3]
	v_mov_b64_e32 v[82:83], v[2:3]
	v_mov_b64_e32 v[86:87], v[2:3]
	v_mov_b64_e32 v[90:91], v[2:3]
	v_mov_b64_e32 v[94:95], v[2:3]
	v_mov_b64_e32 v[34:35], v[2:3]
	v_mov_b64_e32 v[38:39], v[2:3]
	v_mov_b64_e32 v[42:43], v[2:3]
	v_mov_b64_e32 v[46:47], v[2:3]
	v_mov_b64_e32 v[50:51], v[2:3]
	v_mov_b64_e32 v[54:55], v[2:3]
	v_mov_b64_e32 v[58:59], v[2:3]
	v_mov_b64_e32 v[62:63], v[2:3]
	v_mov_b64_e32 v[98:99], v[2:3]
	v_mov_b64_e32 v[102:103], v[2:3]
	v_mov_b64_e32 v[106:107], v[2:3]
	v_mov_b64_e32 v[110:111], v[2:3]
	v_mov_b64_e32 v[114:115], v[2:3]
	v_mov_b64_e32 v[118:119], v[2:3]
	v_mov_b64_e32 v[122:123], v[2:3]
	v_mov_b64_e32 v[126:127], v[2:3]
	s_cmp_eq_u32 s55, 1
	s_cbranch_scc1 .Lrst_skip_1274
	s_andn2_b64 vcc, exec, s[48:49]
	s_cbranch_vccnz .Lrst_skip_1274
	s_barrier
.Lrst_skip_1274:
.LBB0_1274:
	v_add_u32_e32 v142, 0x10000, v157
	v_add_u32_e32 v159, 0x14000, v157
	ds_read_b128 v[130:133], v142
	ds_read_b128 v[134:137], v142 offset:1024
	ds_read_b128 v[138:141], v142 offset:2048
	ds_read_b128 v[142:145], v142 offset:3072
	ds_read_b128 v[146:149], v159
	ds_read_b128 v[164:167], v159 offset:1024
	ds_read_b128 v[168:171], v159 offset:2048
	ds_read_b128 v[182:185], v159 offset:3072
	s_add_i32 s42, s62, 0xfff80080
	s_cmp_eq_u32 s67, 28
	s_cselect_b32 s70, s30, s42
	s_cselect_b32 s69, s31, s63
	s_or_b32 s68, s70, 0x80
	s_mov_b32 m0, s29
	ds_read_b128 v[186:189], v158
	ds_read_b128 v[190:193], v158 offset:1024
	ds_read_b128 v[194:197], v158 offset:2048
	ds_read_b128 v[198:201], v158 offset:3072
	ds_read_b128 v[202:205], v158 offset:4096
	ds_read_b128 v[206:209], v158 offset:5120
	ds_read_b128 v[210:213], v158 offset:6144
	ds_read_b128 v[214:217], v158 offset:7168
	buffer_load_dwordx4 v150, s[76:79], s62 offen lds
	s_mov_b32 m0, s35
	s_nop 0
	buffer_load_dwordx4 v152, s[76:79], s62 offen lds
	s_waitcnt vmcnt(8)
	s_waitcnt lgkmcnt(0)
	s_setprio 1
	s_barrier
	v_mfma_f32_16x16x32_bf16 v[126:129], v[130:133], v[186:189], v[126:129]
	v_mfma_f32_16x16x32_bf16 v[122:125], v[138:141], v[186:189], v[122:125]
	v_mfma_f32_16x16x32_bf16 v[118:121], v[130:133], v[194:197], v[118:121]
	v_mfma_f32_16x16x32_bf16 v[114:117], v[138:141], v[194:197], v[114:117]
	v_mfma_f32_16x16x32_bf16 v[110:113], v[130:133], v[202:205], v[110:113]
	v_mfma_f32_16x16x32_bf16 v[106:109], v[138:141], v[202:205], v[106:109]
	v_mfma_f32_16x16x32_bf16 v[102:105], v[130:133], v[210:213], v[102:105]
	v_mfma_f32_16x16x32_bf16 v[98:101], v[138:141], v[210:213], v[98:101]
	v_mfma_f32_16x16x32_bf16 v[126:129], v[134:137], v[190:193], v[126:129]
	v_mfma_f32_16x16x32_bf16 v[122:125], v[142:145], v[190:193], v[122:125]
	v_mfma_f32_16x16x32_bf16 v[118:121], v[134:137], v[198:201], v[118:121]
	v_mfma_f32_16x16x32_bf16 v[114:117], v[142:145], v[198:201], v[114:117]
	v_mfma_f32_16x16x32_bf16 v[110:113], v[134:137], v[206:209], v[110:113]
	v_mfma_f32_16x16x32_bf16 v[106:109], v[142:145], v[206:209], v[106:109]
	v_mfma_f32_16x16x32_bf16 v[102:105], v[134:137], v[214:217], v[102:105]
	v_mfma_f32_16x16x32_bf16 v[98:101], v[142:145], v[214:217], v[98:101]
	v_mfma_f32_16x16x32_bf16 v[62:65], v[146:149], v[186:189], v[62:65]
	v_mfma_f32_16x16x32_bf16 v[58:61], v[168:171], v[186:189], v[58:61]
	v_mfma_f32_16x16x32_bf16 v[54:57], v[146:149], v[194:197], v[54:57]
	v_mfma_f32_16x16x32_bf16 v[50:53], v[168:171], v[194:197], v[50:53]
	v_mfma_f32_16x16x32_bf16 v[46:49], v[146:149], v[202:205], v[46:49]
	v_mfma_f32_16x16x32_bf16 v[42:45], v[168:171], v[202:205], v[42:45]
	v_mfma_f32_16x16x32_bf16 v[38:41], v[146:149], v[210:213], v[38:41]
	v_mfma_f32_16x16x32_bf16 v[34:37], v[168:171], v[210:213], v[34:37]
	v_mfma_f32_16x16x32_bf16 v[62:65], v[164:167], v[190:193], v[62:65]
	v_mfma_f32_16x16x32_bf16 v[58:61], v[182:185], v[190:193], v[58:61]
	v_mfma_f32_16x16x32_bf16 v[54:57], v[164:167], v[198:201], v[54:57]
	v_mfma_f32_16x16x32_bf16 v[50:53], v[182:185], v[198:201], v[50:53]
	v_mfma_f32_16x16x32_bf16 v[46:49], v[164:167], v[206:209], v[46:49]
	v_mfma_f32_16x16x32_bf16 v[42:45], v[182:185], v[206:209], v[42:45]
	v_mfma_f32_16x16x32_bf16 v[38:41], v[164:167], v[214:217], v[38:41]
	v_mfma_f32_16x16x32_bf16 v[34:37], v[182:185], v[214:217], v[34:37]
	s_barrier
; #define PG8_STAGEX(rs, bufoff, soff, voff) do { _Pragma("unroll") for (int _i = 0; _i < 2; ++_i) \
;         __builtin_amdgcn_raw_ptr_buffer_load_lds(rs, (LAS unsigned*)(lds + (bufoff) + ldsw + _i * 8192), 16, (voff)[_i], (soff), 0, 0); } while (0)
; #define PG8_LDA(dst, b, h) do { _Pragma("unroll") for (int m = 0; m < 4; ++m) _Pragma("unroll") for (int k = 0; k < 2; ++k) dst[m][k] = *(const LAS bf16x8*)(lds + PG8_SA(b, h) + aoff + m * 2048 + k * 1024); } while (0)
; #define PG8_LDB(dst, b, h) do { _Pragma("unroll") for (int n = 0; n < 2; ++n) _Pragma("unroll") for (int k = 0; k < 2; ++k) dst[n][k] = *(const LAS bf16x8*)(lds + PG8_SB(b, h) + boff + n * 2048 + k * 1024); } while (0)
; #define PG8_WAIT_V(n) asm volatile("s_waitcnt vmcnt(" #n ")" ::: "memory")
; #define PG8_WAIT_L(n) asm volatile("s_waitcnt lgkmcnt(" #n ")" ::: "memory")
; #define PG8_BAR __builtin_amdgcn_s_barrier()
; #define PG8_SCHED __builtin_amdgcn_sched_barrier(0)
;     ...
;             PG8_LDB(B0, 0, 0); PG8_LDB(B1, 0, 1); PG8_SCHED; PG8_LDA(At, 0, 0); PG8_STAGEX(rsA, PG8_SA(1, 1), a1 + hstepA, voffA);
;             PG8_WAIT_V(8); PG8_WAIT_L(0); PG8_BAR; PG8_MMA(0, 0, At, B0); PG8_MMA(0, 1, At, B1); PG8_BAR; PG8_SCHED;
;             PG8_LDA(At, 0, 1); PG8_STAGEX(rsB, PG8_SB(0, 0), b2, voffB); PG8_STAGEX(rsB, PG8_SB(0, 1), b2 + hstepB, voffB); PG8_STAGEX(rsA, PG8_SA(0, 0), a2, voffA);
;             PG8_WAIT_V(8); PG8_WAIT_L(0); PG8_BAR; PG8_MMA(1, 0, At, B0); PG8_MMA(1, 1, At, B1); PG8_BAR; PG8_SCHED;
;             PG8_LDB(B0, 1, 0); PG8_LDB(B1, 1, 1); PG8_SCHED; PG8_LDA(At, 1, 0); PG8_STAGEX(rsA, PG8_SA(0, 1), a2 + hstepA, voffA);
;             PG8_WAIT_V(8); PG8_WAIT_L(0); PG8_BAR; PG8_MMA(0, 0, At, B0); PG8_MMA(0, 1, At, B1); PG8_BAR; PG8_SCHED;
;             PG8_LDA(At, 1, 1); PG8_STAGEX(rsB, PG8_SB(1, 0), b3, voffB); PG8_STAGEX(rsB, PG8_SB(1, 1), b3 + hstepB, voffB); PG8_STAGEX(rsA, PG8_SA(1, 0), a3, voffA);
;             PG8_WAIT_V(8); PG8_WAIT_L(0); PG8_BAR; PG8_MMA(1, 0, At, B0); PG8_MMA(1, 1, At, B1); PG8_BAR; PG8_SCHED;
	s_setprio 0
	s_mov_b32 m0, s16
	s_mov_b32 s42, s78
	s_mov_b32 s43, s79
	ds_read_b128 v[186:189], v158 offset:16384
	ds_read_b128 v[190:193], v158 offset:17408
	ds_read_b128 v[194:197], v158 offset:18432
	ds_read_b128 v[198:201], v158 offset:19456
	ds_read_b128 v[202:205], v158 offset:20480
	ds_read_b128 v[206:209], v158 offset:21504
	ds_read_b128 v[210:213], v158 offset:22528
	ds_read_b128 v[214:217], v158 offset:23552
	buffer_load_dwordx4 v151, s[40:43], s69 offen lds
	s_mov_b32 m0, s17
	s_add_i32 s71, s69, 0x80000
	buffer_load_dwordx4 v153, s[40:43], s69 offen lds
	s_mov_b32 m0, s18
	s_nop 0
	buffer_load_dwordx4 v151, s[40:43], s71 offen lds
	s_mov_b32 m0, s19
	s_nop 0
	buffer_load_dwordx4 v153, s[40:43], s71 offen lds
	s_mov_b32 m0, s15
	s_nop 0
	buffer_load_dwordx4 v150, s[76:79], s70 offen lds
	s_mov_b32 m0, s20
	s_nop 0
	buffer_load_dwordx4 v152, s[76:79], s70 offen lds
	s_waitcnt vmcnt(8)
	s_waitcnt lgkmcnt(0)
	s_setprio 1
	s_barrier
	v_mfma_f32_16x16x32_bf16 v[94:97], v[130:133], v[186:189], v[94:97]
	v_mfma_f32_16x16x32_bf16 v[90:93], v[138:141], v[186:189], v[90:93]
	v_mfma_f32_16x16x32_bf16 v[86:89], v[130:133], v[194:197], v[86:89]
	v_mfma_f32_16x16x32_bf16 v[82:85], v[138:141], v[194:197], v[82:85]
	v_mfma_f32_16x16x32_bf16 v[78:81], v[130:133], v[202:205], v[78:81]
	v_mfma_f32_16x16x32_bf16 v[74:77], v[138:141], v[202:205], v[74:77]
	v_mfma_f32_16x16x32_bf16 v[70:73], v[130:133], v[210:213], v[70:73]
	v_mfma_f32_16x16x32_bf16 v[66:69], v[138:141], v[210:213], v[66:69]
	v_mfma_f32_16x16x32_bf16 v[94:97], v[134:137], v[190:193], v[94:97]
	v_mfma_f32_16x16x32_bf16 v[90:93], v[142:145], v[190:193], v[90:93]
	v_mfma_f32_16x16x32_bf16 v[86:89], v[134:137], v[198:201], v[86:89]
	v_mfma_f32_16x16x32_bf16 v[82:85], v[142:145], v[198:201], v[82:85]
	v_mfma_f32_16x16x32_bf16 v[78:81], v[134:137], v[206:209], v[78:81]
	v_mfma_f32_16x16x32_bf16 v[74:77], v[142:145], v[206:209], v[74:77]
	v_mfma_f32_16x16x32_bf16 v[70:73], v[134:137], v[214:217], v[70:73]
	v_mfma_f32_16x16x32_bf16 v[66:69], v[142:145], v[214:217], v[66:69]
	v_mfma_f32_16x16x32_bf16 v[30:33], v[146:149], v[186:189], v[30:33]
	v_mfma_f32_16x16x32_bf16 v[26:29], v[168:171], v[186:189], v[26:29]
	v_mfma_f32_16x16x32_bf16 v[22:25], v[146:149], v[194:197], v[22:25]
	v_mfma_f32_16x16x32_bf16 v[18:21], v[168:171], v[194:197], v[18:21]
	v_mfma_f32_16x16x32_bf16 v[14:17], v[146:149], v[202:205], v[14:17]
	v_mfma_f32_16x16x32_bf16 v[10:13], v[168:171], v[202:205], v[10:13]
	v_mfma_f32_16x16x32_bf16 v[6:9], v[146:149], v[210:213], v[6:9]
	v_mfma_f32_16x16x32_bf16 v[2:5], v[168:171], v[210:213], v[2:5]
	v_mfma_f32_16x16x32_bf16 v[30:33], v[164:167], v[190:193], v[30:33]
	v_mfma_f32_16x16x32_bf16 v[26:29], v[182:185], v[190:193], v[26:29]
	v_mfma_f32_16x16x32_bf16 v[22:25], v[164:167], v[198:201], v[22:25]
	v_mfma_f32_16x16x32_bf16 v[18:21], v[182:185], v[198:201], v[18:21]
	v_mfma_f32_16x16x32_bf16 v[14:17], v[164:167], v[206:209], v[14:17]
	v_mfma_f32_16x16x32_bf16 v[10:13], v[182:185], v[206:209], v[10:13]
	v_mfma_f32_16x16x32_bf16 v[6:9], v[164:167], v[214:217], v[6:9]
	v_mfma_f32_16x16x32_bf16 v[2:5], v[182:185], v[214:217], v[2:5]
	s_barrier
	s_setprio 0
	v_add_u32_e32 v142, 0x18000, v157
	v_add_u32_e32 v159, 0x1c000, v157
	ds_read_b128 v[130:133], v142
	ds_read_b128 v[134:137], v142 offset:1024
	ds_read_b128 v[138:141], v142 offset:2048
	ds_read_b128 v[142:145], v142 offset:3072
	ds_read_b128 v[146:149], v159
	ds_read_b128 v[164:167], v159 offset:1024
	ds_read_b128 v[168:171], v159 offset:2048
	ds_read_b128 v[182:185], v159 offset:3072
	s_add_i32 s70, s70, 0x80000
	s_mov_b32 m0, s21
	ds_read_b128 v[186:189], v158 offset:32768
	ds_read_b128 v[190:193], v158 offset:33792
	ds_read_b128 v[194:197], v158 offset:34816
	ds_read_b128 v[198:201], v158 offset:35840
	ds_read_b128 v[202:205], v158 offset:36864
	ds_read_b128 v[206:209], v158 offset:37888
	ds_read_b128 v[210:213], v158 offset:38912
	ds_read_b128 v[214:217], v158 offset:39936
	buffer_load_dwordx4 v150, s[76:79], s70 offen lds
	s_mov_b32 m0, s22
	s_nop 0
	buffer_load_dwordx4 v152, s[76:79], s70 offen lds
	s_waitcnt vmcnt(8)
	s_waitcnt lgkmcnt(0)
	s_setprio 1
	s_barrier
; #define PG8_STAGEX(rs, bufoff, soff, voff) do { _Pragma("unroll") for (int _i = 0; _i < 2; ++_i) \
;         __builtin_amdgcn_raw_ptr_buffer_load_lds(rs, (LAS unsigned*)(lds + (bufoff) + ldsw + _i * 8192), 16, (voff)[_i], (soff), 0, 0); } while (0)
; #define PG8_LDA(dst, b, h) do { _Pragma("unroll") for (int m = 0; m < 4; ++m) _Pragma("unroll") for (int k = 0; k < 2; ++k) dst[m][k] = *(const LAS bf16x8*)(lds + PG8_SA(b, h) + aoff + m * 2048 + k * 1024); } while (0)
; #define PG8_LDB(dst, b, h) do { _Pragma("unroll") for (int n = 0; n < 2; ++n) _Pragma("unroll") for (int k = 0; k < 2; ++k) dst[n][k] = *(const LAS bf16x8*)(lds + PG8_SB(b, h) + boff + n * 2048 + k * 1024); } while (0)
; #define PG8_WAIT_V(n) asm volatile("s_waitcnt vmcnt(" #n ")" ::: "memory")
; #define PG8_WAIT_L(n) asm volatile("s_waitcnt lgkmcnt(" #n ")" ::: "memory")
; #define PG8_BAR __builtin_amdgcn_s_barrier()
; #define PG8_SCHED __builtin_amdgcn_sched_barrier(0)
;     ...
;             PG8_LDB(B0, 1, 0); PG8_LDB(B1, 1, 1); PG8_SCHED; PG8_LDA(At, 1, 0); PG8_STAGEX(rsA, PG8_SA(0, 1), a2 + hstepA, voffA);
;             PG8_WAIT_V(8); PG8_WAIT_L(0); PG8_BAR; PG8_MMA(0, 0, At, B0); PG8_MMA(0, 1, At, B1); PG8_BAR; PG8_SCHED;
;             PG8_LDA(At, 1, 1); PG8_STAGEX(rsB, PG8_SB(1, 0), b3, voffB); PG8_STAGEX(rsB, PG8_SB(1, 1), b3 + hstepB, voffB); PG8_STAGEX(rsA, PG8_SA(1, 0), a3, voffA);
;             PG8_WAIT_V(8); PG8_WAIT_L(0); PG8_BAR; PG8_MMA(1, 0, At, B0); PG8_MMA(1, 1, At, B1); PG8_BAR; PG8_SCHED;
;     ...
;         if (wr == 0) PG8_BAR;
	v_mfma_f32_16x16x32_bf16 v[126:129], v[130:133], v[186:189], v[126:129]
	v_mfma_f32_16x16x32_bf16 v[122:125], v[138:141], v[186:189], v[122:125]
	v_mfma_f32_16x16x32_bf16 v[118:121], v[130:133], v[194:197], v[118:121]
	v_mfma_f32_16x16x32_bf16 v[114:117], v[138:141], v[194:197], v[114:117]
	v_mfma_f32_16x16x32_bf16 v[110:113], v[130:133], v[202:205], v[110:113]
	v_mfma_f32_16x16x32_bf16 v[106:109], v[138:141], v[202:205], v[106:109]
	v_mfma_f32_16x16x32_bf16 v[102:105], v[130:133], v[210:213], v[102:105]
	v_mfma_f32_16x16x32_bf16 v[98:101], v[138:141], v[210:213], v[98:101]
	v_mfma_f32_16x16x32_bf16 v[126:129], v[134:137], v[190:193], v[126:129]
	v_mfma_f32_16x16x32_bf16 v[122:125], v[142:145], v[190:193], v[122:125]
	v_mfma_f32_16x16x32_bf16 v[118:121], v[134:137], v[198:201], v[118:121]
	v_mfma_f32_16x16x32_bf16 v[114:117], v[142:145], v[198:201], v[114:117]
	v_mfma_f32_16x16x32_bf16 v[110:113], v[134:137], v[206:209], v[110:113]
	v_mfma_f32_16x16x32_bf16 v[106:109], v[142:145], v[206:209], v[106:109]
	v_mfma_f32_16x16x32_bf16 v[102:105], v[134:137], v[214:217], v[102:105]
	v_mfma_f32_16x16x32_bf16 v[98:101], v[142:145], v[214:217], v[98:101]
	v_mfma_f32_16x16x32_bf16 v[62:65], v[146:149], v[186:189], v[62:65]
	v_mfma_f32_16x16x32_bf16 v[58:61], v[168:171], v[186:189], v[58:61]
	v_mfma_f32_16x16x32_bf16 v[54:57], v[146:149], v[194:197], v[54:57]
	v_mfma_f32_16x16x32_bf16 v[50:53], v[168:171], v[194:197], v[50:53]
	v_mfma_f32_16x16x32_bf16 v[46:49], v[146:149], v[202:205], v[46:49]
	v_mfma_f32_16x16x32_bf16 v[42:45], v[168:171], v[202:205], v[42:45]
	v_mfma_f32_16x16x32_bf16 v[38:41], v[146:149], v[210:213], v[38:41]
	v_mfma_f32_16x16x32_bf16 v[34:37], v[168:171], v[210:213], v[34:37]
	v_mfma_f32_16x16x32_bf16 v[62:65], v[164:167], v[190:193], v[62:65]
	v_mfma_f32_16x16x32_bf16 v[58:61], v[182:185], v[190:193], v[58:61]
	v_mfma_f32_16x16x32_bf16 v[54:57], v[164:167], v[198:201], v[54:57]
	v_mfma_f32_16x16x32_bf16 v[50:53], v[182:185], v[198:201], v[50:53]
	v_mfma_f32_16x16x32_bf16 v[46:49], v[164:167], v[206:209], v[46:49]
	v_mfma_f32_16x16x32_bf16 v[42:45], v[182:185], v[206:209], v[42:45]
	v_mfma_f32_16x16x32_bf16 v[38:41], v[164:167], v[214:217], v[38:41]
	v_mfma_f32_16x16x32_bf16 v[34:37], v[182:185], v[214:217], v[34:37]
	s_barrier
	s_setprio 0
	s_mov_b32 m0, s23
	s_or_b32 s70, s69, 0x80
	ds_read_b128 v[186:189], v158 offset:49152
	ds_read_b128 v[190:193], v158 offset:50176
	ds_read_b128 v[194:197], v158 offset:51200
	ds_read_b128 v[198:201], v158 offset:52224
	ds_read_b128 v[202:205], v158 offset:53248
	ds_read_b128 v[206:209], v158 offset:54272
	ds_read_b128 v[210:213], v158 offset:55296
	ds_read_b128 v[214:217], v158 offset:56320
	buffer_load_dwordx4 v151, s[40:43], s70 offen lds
	s_mov_b32 m0, s24
	s_add_i32 s69, s69, 0x80080
	buffer_load_dwordx4 v153, s[40:43], s70 offen lds
	s_mov_b32 m0, s27
	s_nop 0
	buffer_load_dwordx4 v151, s[40:43], s69 offen lds
	s_mov_b32 m0, s28
	s_nop 0
	buffer_load_dwordx4 v153, s[40:43], s69 offen lds
	s_mov_b32 m0, s25
	s_nop 0
	buffer_load_dwordx4 v150, s[76:79], s68 offen lds
	s_mov_b32 m0, s26
	s_nop 0
	buffer_load_dwordx4 v152, s[76:79], s68 offen lds
	s_waitcnt vmcnt(8)
	s_waitcnt lgkmcnt(0)
	s_setprio 1
	s_barrier
	v_mfma_f32_16x16x32_bf16 v[94:97], v[130:133], v[186:189], v[94:97]
	v_mfma_f32_16x16x32_bf16 v[90:93], v[138:141], v[186:189], v[90:93]
	v_mfma_f32_16x16x32_bf16 v[86:89], v[130:133], v[194:197], v[86:89]
	v_mfma_f32_16x16x32_bf16 v[82:85], v[138:141], v[194:197], v[82:85]
	v_mfma_f32_16x16x32_bf16 v[78:81], v[130:133], v[202:205], v[78:81]
	v_mfma_f32_16x16x32_bf16 v[74:77], v[138:141], v[202:205], v[74:77]
	v_mfma_f32_16x16x32_bf16 v[70:73], v[130:133], v[210:213], v[70:73]
	v_mfma_f32_16x16x32_bf16 v[66:69], v[138:141], v[210:213], v[66:69]
	v_mfma_f32_16x16x32_bf16 v[94:97], v[134:137], v[190:193], v[94:97]
	v_mfma_f32_16x16x32_bf16 v[90:93], v[142:145], v[190:193], v[90:93]
	v_mfma_f32_16x16x32_bf16 v[86:89], v[134:137], v[198:201], v[86:89]
	v_mfma_f32_16x16x32_bf16 v[82:85], v[142:145], v[198:201], v[82:85]
	v_mfma_f32_16x16x32_bf16 v[78:81], v[134:137], v[206:209], v[78:81]
	v_mfma_f32_16x16x32_bf16 v[74:77], v[142:145], v[206:209], v[74:77]
	v_mfma_f32_16x16x32_bf16 v[70:73], v[134:137], v[214:217], v[70:73]
	v_mfma_f32_16x16x32_bf16 v[66:69], v[142:145], v[214:217], v[66:69]
	v_mfma_f32_16x16x32_bf16 v[30:33], v[146:149], v[186:189], v[30:33]
	v_mfma_f32_16x16x32_bf16 v[26:29], v[168:171], v[186:189], v[26:29]
	v_mfma_f32_16x16x32_bf16 v[22:25], v[146:149], v[194:197], v[22:25]
	v_mfma_f32_16x16x32_bf16 v[18:21], v[168:171], v[194:197], v[18:21]
	v_mfma_f32_16x16x32_bf16 v[14:17], v[146:149], v[202:205], v[14:17]
	v_mfma_f32_16x16x32_bf16 v[10:13], v[168:171], v[202:205], v[10:13]
	v_mfma_f32_16x16x32_bf16 v[6:9], v[146:149], v[210:213], v[6:9]
	v_mfma_f32_16x16x32_bf16 v[2:5], v[168:171], v[210:213], v[2:5]
	v_mfma_f32_16x16x32_bf16 v[30:33], v[164:167], v[190:193], v[30:33]
	v_mfma_f32_16x16x32_bf16 v[26:29], v[182:185], v[190:193], v[26:29]
	v_mfma_f32_16x16x32_bf16 v[22:25], v[164:167], v[198:201], v[22:25]
	v_mfma_f32_16x16x32_bf16 v[18:21], v[182:185], v[198:201], v[18:21]
	v_mfma_f32_16x16x32_bf16 v[14:17], v[164:167], v[206:209], v[14:17]
	v_mfma_f32_16x16x32_bf16 v[10:13], v[182:185], v[206:209], v[10:13]
	v_mfma_f32_16x16x32_bf16 v[6:9], v[164:167], v[214:217], v[6:9]
	v_mfma_f32_16x16x32_bf16 v[2:5], v[182:185], v[214:217], v[2:5]
	s_barrier
	s_setprio 0
	s_add_i32 s67, s67, 2
	s_addk_i32 s62, 0x100
	s_addk_i32 s63, 0x100
	s_cmp_gt_u32 s67, 29
	s_cbranch_scc0 .LBB0_1274
	s_and_b64 vcc, exec, s[50:51]
	s_cbranch_vccz .LBB0_1277
	s_barrier

; __device__ __forceinline__ void row_rstd(const unsigned long long* ssq, int row0, float (&rs)[2][4]) {
;     unsigned long long q[2][4];
; #pragma unroll
;     for (int ai = 0; ai < 2; ++ai)
; #pragma unroll
;         for (int m = 0; m < 4; ++m) q[ai][m] = ssq[row0 + ai * HALF + m * 16];
;     asm volatile("" : "+v"(q[0][0]), "+v"(q[0][1]), "+v"(q[0][2]), "+v"(q[0][3]), "+v"(q[1][0]), "+v"(q[1][1]), "+v"(q[1][2]), "+v"(q[1][3]));
; #pragma unroll
;     for (int ai = 0; ai < 2; ++ai)
; #pragma unroll
;         for (int m = 0; m < 4; ++m) {
;             const float qf = __builtin_fmaf((float)(unsigned)(q[ai][m] >> 32), 4294967296.0f, (float)(unsigned)q[ai][m]);
;             rs[ai][m] = __builtin_amdgcn_rsqf(__builtin_fmaf(qf, 1.0f / (SSQ_SCALE * DM), EPS)); }
; }
;     template <int QVV> __device__ __forceinline__ void run(f32x4 (&acc)[2][2][4][2], const Unit& u, int wr, int wc, int fr, int fq) const {
;         constexpr int nai = (QVV == 2) ? 1 : 2; const int r0 = u.pm * BM + (QVV == 2 ? (u.seg - 1) * HALF : 0);
;         char* tb = (char*)(O + (size_t)r0 * NGC + u.pn * BM);
;         const int v = u.pm < 4 ? 4 : ((u.pm - 4) >> 5);
;         const char* swb = (const char*)(sw + (size_t)v * SWLD + u.pn * BM); const char* bmb = (const char*)(bm + u.pn * BM);
;         unsigned lo = (unsigned)((wr * 64 + fr) * NGC + wc * 32 + 8 * fq);
;         unsigned co = (unsigned)(wc * 32 + 8 * fq) * 4u;
;         asm volatile("" : "+v"(lo), "+v"(co));
;         float rs[2][4]; row_rstd(ssq, r0 + wr * 64 + fr, rs);
; #pragma unroll
;         for (int bj = 0; bj < 2; ++bj) {
;             const f32x4 s0 = (*(const f32x4*)(swb + co + bj * HALF * 4) + *(const f32x4*)(bmb + co + bj * HALF * 4)) * (-LOG2E) - 7.994353436858858f,
;                         s1 = (*(const f32x4*)(swb + co + bj * HALF * 4 + 16) + *(const f32x4*)(bmb + co + bj * HALF * 4 + 16)) * (-LOG2E) - 7.994353436858858f;
.LBB0_1279:
	s_mul_i32 s98, s53, 24
	s_add_i32 s98, s98, s52
	s_lshl_b32 s98, s98, 16
	s_add_u32 s98, s1, s98
	s_addc_u32 s99, s2, 0
	s_lshl_b32 s67, s53, 8
	v_add_u32_e32 v130, s67, v154
	v_ashrrev_i32_e32 v131, 31, v130
	v_and_b32_e32 v146, 0x1c0, v0
	v_lshlrev_b32_e32 v146, 7, v146
	v_and_b32_e32 v148, 48, v0
	v_lshl_or_b32 v146, v148, 4, v146
	v_and_b32_e32 v148, 15, v0
	v_lshl_or_b32 v146, v148, 3, v146
	v_mov_b32_e32 v159, v156
	v_lshl_add_u64 v[130:131], v[130:131], 3, s[44:45]
	global_load_dwordx2 v[132:133], v[130:131], off
	global_load_dwordx2 v[134:135], v[130:131], off offset:128
	global_load_dwordx2 v[136:137], v[130:131], off offset:256
	global_load_dwordx2 v[138:139], v[130:131], off offset:384
	global_load_dwordx2 v[140:141], v[130:131], off offset:1024
	global_load_dwordx2 v[142:143], v[130:131], off offset:1152
	global_load_dwordx2 v[144:145], v[130:131], off offset:1280
	s_nop 0
	global_load_dwordx2 v[130:131], v[130:131], off offset:1408
	s_mul_i32 s42, s53, 0x180000
	s_mul_hi_i32 s43, s67, 0x1800
	s_add_u32 s42, s1, s42
	s_addc_u32 s43, s2, s43
	s_lshl_b32 s52, s52, 8
	s_ashr_i32 s53, s52, 31
	s_add_u32 s42, s42, s52
	s_addc_u32 s43, s43, s53
	s_lshl_b64 s[30:31], s[30:31], 2
	s_add_u32 s62, s7, s30
	s_addc_u32 s63, s9, s31
	s_lshl_b64 s[30:31], s[52:53], 2
	s_add_u32 s62, s62, s30
	s_addc_u32 s63, s63, s31
	s_add_u32 s52, s3, s30
	s_flbit_i32_b32 s30, 0
	s_addc_u32 s53, s5, s31
	s_min_u32 s30, s30, 32
	s_sub_i32 s31, 32, s30
	v_mov_b32_e32 v147, v175
	s_waitcnt vmcnt(0)
	s_nop 0
	v_mov_b32_e32 v174, v133
	v_lshlrev_b64 v[148:149], s30, v[174:175]
	v_min_u32_e32 v133, 1, v148
	v_or_b32_e32 v133, v149, v133
	v_cvt_f32_u32_e32 v133, v133
	v_cvt_f32_u32_e32 v132, v132
	v_mov_b32_e32 v174, v135
	v_cvt_f32_u32_e32 v130, v130
	v_ldexp_f32 v133, v133, s31
	v_fmac_f32_e32 v132, 0x4f800000, v133
	v_fmamk_f32 v132, v132, 0x30000000, v231
	v_rsq_f32_e32 v168, v132
	v_lshlrev_b64 v[132:133], s30, v[174:175]
	v_min_u32_e32 v132, 1, v132
	v_or_b32_e32 v132, v133, v132
	v_cvt_f32_u32_e32 v132, v132
	v_cvt_f32_u32_e32 v133, v134
	v_mov_b32_e32 v174, v137
	v_lshl_add_u64 v[148:149], s[98:99], 0, v[146:147]
	v_ldexp_f32 v132, v132, s31
	v_fmac_f32_e32 v133, 0x4f800000, v132
	v_fmamk_f32 v132, v133, 0x30000000, v231
	v_rsq_f32_e32 v167, v132
	v_lshlrev_b64 v[132:133], s30, v[174:175]
	v_min_u32_e32 v132, 1, v132
	v_or_b32_e32 v132, v133, v132
	v_cvt_f32_u32_e32 v132, v132
	v_cvt_f32_u32_e32 v133, v136
	v_mov_b32_e32 v174, v139
	v_mul_f32_e32 v147, 0xbfb8aa3b, v168
	v_ldexp_f32 v132, v132, s31
	v_fmac_f32_e32 v133, 0x4f800000, v132
	v_fmamk_f32 v132, v133, 0x30000000, v231
	v_rsq_f32_e32 v166, v132
	v_lshlrev_b64 v[132:133], s30, v[174:175]
	v_min_u32_e32 v132, 1, v132
	v_or_b32_e32 v132, v133, v132
	v_cvt_f32_u32_e32 v132, v132
	v_cvt_f32_u32_e32 v133, v138
	v_mov_b32_e32 v174, v141
	v_ldexp_f32 v132, v132, s31
	v_fmac_f32_e32 v133, 0x4f800000, v132
	v_fmamk_f32 v132, v133, 0x30000000, v231
	v_rsq_f32_e32 v165, v132
	v_lshlrev_b64 v[132:133], s30, v[174:175]
	v_min_u32_e32 v132, 1, v132
	v_or_b32_e32 v132, v133, v132
	v_cvt_f32_u32_e32 v132, v132
	v_cvt_f32_u32_e32 v133, v140
	v_mov_b32_e32 v174, v143
	v_ldexp_f32 v132, v132, s31
	v_fmac_f32_e32 v133, 0x4f800000, v132
	v_fmamk_f32 v132, v133, 0x30000000, v231
	v_rsq_f32_e32 v164, v132
	v_lshlrev_b64 v[132:133], s30, v[174:175]
	v_min_u32_e32 v132, 1, v132
	v_or_b32_e32 v132, v133, v132
	v_cvt_f32_u32_e32 v132, v132
	v_cvt_f32_u32_e32 v133, v142
	v_mov_b32_e32 v174, v145
	v_ldexp_f32 v132, v132, s31
	v_fmac_f32_e32 v133, 0x4f800000, v132
	v_fmamk_f32 v132, v133, 0x30000000, v231
	v_rsq_f32_e32 v163, v132
	v_lshlrev_b64 v[132:133], s30, v[174:175]
	v_min_u32_e32 v132, 1, v132
	v_or_b32_e32 v132, v133, v132
	v_cvt_f32_u32_e32 v132, v132
	v_cvt_f32_u32_e32 v133, v144
	v_mov_b32_e32 v174, v131
	v_ldexp_f32 v132, v132, s31
	v_fmac_f32_e32 v133, 0x4f800000, v132
	v_fmamk_f32 v132, v133, 0x30000000, v231
	v_rsq_f32_e32 v161, v132
	v_lshlrev_b64 v[132:133], s30, v[174:175]
	v_min_u32_e32 v131, 1, v132
	v_or_b32_e32 v131, v133, v131
	v_cvt_f32_u32_e32 v131, v131
	s_mov_b32 s30, 0x400
	v_ldexp_f32 v131, v131, s31
	v_fmac_f32_e32 v130, 0x4f800000, v131
	v_fmamk_f32 v130, v130, 0x30000000, v231
	v_rsq_f32_e32 v160, v130
	global_load_dwordx4 v[130:133], v159, s[62:63] offset:16
	global_load_dwordx4 v[138:141], v159, s[62:63]
	global_load_dwordx4 v[134:137], v159, s[52:53] offset:16
	global_load_dwordx4 v[142:145], v159, s[52:53]
	s_waitcnt vmcnt(0)
;     template <int QVV> __device__ __forceinline__ void run(f32x4 (&acc)[2][2][4][2], const Unit& u, int wr, int wc, int fr, int fq) const {
;     ...
;             for (int ai = 0; ai < 2; ++ai)
; #pragma unroll
;                 for (int m = 0; m < 4; ++m) { if (ai >= nai) continue;
;                     const float rn = rs[ai][m] * (-LOG2E);
;                     const f32x4 x0 = acc[ai][bj][m][0] * rn + s0, x1 = acc[ai][bj][m][1] * rn + s1;
;                     f32x4 d0, d1;
; #pragma unroll
;                     for (int i = 0; i < 4; ++i) { d0[i] = __builtin_amdgcn_exp2f(x0[i]); d1[i] = __builtin_amdgcn_exp2f(x1[i]); }
;                     d0 = d0 + (1.0f / 255.0f); d1 = d1 + (1.0f / 255.0f);
;                     u32x2 w = {0u, 0u};
; #pragma unroll
;                     for (int i = 0; i < 4; ++i) { const float g0 = fmaxf(__builtin_amdgcn_rcpf(d0[i]), 1.0f), g1 = fmaxf(__builtin_amdgcn_rcpf(d1[i]), 1.0f);
;                         w.x = __builtin_amdgcn_cvt_pk_u8_f32(g0, i, w.x); w.y = __builtin_amdgcn_cvt_pk_u8_f32(g1, i, w.y); }
;                     *(u32x2*)(tb + lo + (unsigned)((ai * HALF + m * 16) * NGC + bj * HALF)) = w; }
	v_add_f32_e32 v138, v138, v142
	v_fmamk_f32 v138, v138, 0xbfb8aa3b, v236
	v_fma_f32 v126, v126, v147, v138
	v_exp_f32_e32 v142, v126
	v_add_f32_e32 v126, v130, v134
	v_fmamk_f32 v126, v126, 0xbfb8aa3b, v236
	v_fma_f32 v122, v122, v147, v126
	v_exp_f32_e32 v134, v122
	v_add_f32_e32 v122, v139, v143
	v_fmamk_f32 v130, v122, 0xbfb8aa3b, v236
	v_fma_f32 v122, v127, v147, v130
	v_exp_f32_e32 v143, v122
	v_add_f32_e32 v122, v131, v135
	v_fmamk_f32 v127, v122, 0xbfb8aa3b, v236
	v_fma_f32 v122, v123, v147, v127
	v_exp_f32_e32 v135, v122
	v_add_f32_e32 v122, v140, v144
	v_fmamk_f32 v123, v122, 0xbfb8aa3b, v236
	v_fma_f32 v122, v128, v147, v123
	v_exp_f32_e32 v140, v122
	v_add_f32_e32 v122, v132, v136
	v_fmamk_f32 v128, v122, 0xbfb8aa3b, v236
	v_fma_f32 v122, v124, v147, v128
	v_exp_f32_e32 v132, v122
	v_add_f32_e32 v122, v141, v145
	v_fmamk_f32 v124, v122, 0xbfb8aa3b, v236
	v_fma_f32 v122, v129, v147, v124
	v_exp_f32_e32 v141, v122
	v_add_f32_e32 v122, v133, v137
	v_fmamk_f32 v129, v122, 0xbfb8aa3b, v236
	v_fma_f32 v122, v125, v147, v129
	v_pk_add_f32 v[136:137], v[140:141], s[0:1] op_sel_hi:[1,0]
	v_pk_add_f32 v[140:141], v[142:143], s[0:1] op_sel_hi:[1,0]
	v_exp_f32_e32 v133, v122
	v_rcp_f32_e32 v122, v140
	v_rcp_f32_e32 v131, v141
	v_pk_add_f32 v[134:135], v[134:135], s[0:1] op_sel_hi:[1,0]
	v_pk_add_f32 v[132:133], v[132:133], s[0:1] op_sel_hi:[1,0]
	v_max_f32_e32 v122, 1.0, v122
	v_rcp_f32_e32 v125, v134
	v_cvt_pk_u8_f32 v122, v122, 0, 0
	v_max_f32_e32 v131, 1.0, v131
	v_rcp_f32_e32 v134, v135
	v_cvt_pk_u8_f32 v122, v131, 1, v122
	v_rcp_f32_e32 v131, v136
	v_rcp_f32_e32 v132, v132
	v_max_f32_e32 v125, 1.0, v125
	v_cvt_pk_u8_f32 v125, v125, 0, 0
	v_max_f32_e32 v134, 1.0, v134
	v_max_f32_e32 v131, 1.0, v131
	v_cvt_pk_u8_f32 v125, v134, 1, v125
	v_max_f32_e32 v132, 1.0, v132
	v_cvt_pk_u8_f32 v122, v131, 2, v122
	v_rcp_f32_e32 v131, v137
	v_cvt_pk_u8_f32 v125, v132, 2, v125
	v_rcp_f32_e32 v132, v133
	v_max_f32_e32 v131, 1.0, v131
	v_max_f32_e32 v133, 1.0, v132
	v_cvt_pk_u8_f32 v132, v131, 3, v122
	v_mul_f32_e32 v122, 0xbfb8aa3b, v167
	v_fma_f32 v114, v114, v122, v126
	v_fma_f32 v115, v115, v122, v127
	v_exp_f32_e32 v114, v114
	v_exp_f32_e32 v115, v115
	v_fma_f32 v116, v116, v122, v128
	v_fma_f32 v117, v117, v122, v129
	v_exp_f32_e32 v116, v116
	v_exp_f32_e32 v117, v117
	v_fma_f32 v118, v118, v122, v138
	v_fma_f32 v119, v119, v122, v130
	v_exp_f32_e32 v118, v118
	v_exp_f32_e32 v119, v119
	v_pk_add_f32 v[114:115], v[114:115], s[0:1] op_sel_hi:[1,0]
	v_fma_f32 v120, v120, v122, v123
	v_fma_f32 v121, v121, v122, v124
	v_rcp_f32_e32 v114, v114
	v_exp_f32_e32 v120, v120
	v_exp_f32_e32 v121, v121
	v_pk_add_f32 v[116:117], v[116:117], s[0:1] op_sel_hi:[1,0]
	v_rcp_f32_e32 v115, v115
	v_rcp_f32_e32 v116, v116
	v_pk_add_f32 v[118:119], v[118:119], s[0:1] op_sel_hi:[1,0]
	v_max_f32_e32 v114, 1.0, v114
	v_rcp_f32_e32 v118, v118
	v_pk_add_f32 v[120:121], v[120:121], s[0:1] op_sel_hi:[1,0]
	v_cvt_pk_u8_f32 v114, v114, 0, 0
	v_rcp_f32_e32 v119, v119
	v_max_f32_e32 v115, 1.0, v115
	v_cvt_pk_u8_f32 v114, v115, 1, v114
	v_rcp_f32_e32 v115, v120
	v_max_f32_e32 v116, 1.0, v116
	v_rcp_f32_e32 v117, v117
	v_cvt_pk_u8_f32 v114, v116, 2, v114
	v_rcp_f32_e32 v116, v121
	v_max_f32_e32 v118, 1.0, v118
	v_cvt_pk_u8_f32 v118, v118, 0, 0
	v_max_f32_e32 v119, 1.0, v119
	v_cvt_pk_u8_f32 v118, v119, 1, v118
	v_max_f32_e32 v115, 1.0, v115
	v_max_f32_e32 v117, 1.0, v117
	v_cvt_pk_u8_f32 v115, v115, 2, v118
	v_max_f32_e32 v116, 1.0, v116
	v_cvt_pk_u8_f32 v117, v117, 3, v114
	v_add_co_u32_e32 v114, vcc, s30, v148
	v_cvt_pk_u8_f32 v116, v116, 3, v115
	s_nop 0
	v_addc_co_u32_e32 v115, vcc, 0, v149, vcc
	global_store_dwordx2 v[114:115], v[116:117], off
	v_mul_f32_e32 v116, 0xbfb8aa3b, v166
	v_fma_f32 v106, v106, v116, v126
	v_fma_f32 v107, v107, v116, v127
	v_exp_f32_e32 v106, v106
	v_exp_f32_e32 v107, v107
	v_fma_f32 v108, v108, v116, v128
	v_fma_f32 v109, v109, v116, v129
	v_exp_f32_e32 v108, v108
	v_exp_f32_e32 v109, v109
	v_fma_f32 v110, v110, v116, v138
	v_fma_f32 v111, v111, v116, v130
	v_exp_f32_e32 v110, v110
	v_exp_f32_e32 v111, v111
	v_pk_add_f32 v[106:107], v[106:107], s[0:1] op_sel_hi:[1,0]
	v_fma_f32 v112, v112, v116, v123
	v_fma_f32 v113, v113, v116, v124
	v_rcp_f32_e32 v106, v106
	v_exp_f32_e32 v112, v112
	v_exp_f32_e32 v113, v113
	v_pk_add_f32 v[108:109], v[108:109], s[0:1] op_sel_hi:[1,0]
	v_rcp_f32_e32 v107, v107
	v_rcp_f32_e32 v108, v108
	v_pk_add_f32 v[110:111], v[110:111], s[0:1] op_sel_hi:[1,0]
	v_max_f32_e32 v106, 1.0, v106
	v_rcp_f32_e32 v110, v110
	v_pk_add_f32 v[112:113], v[112:113], s[0:1] op_sel_hi:[1,0]
	v_cvt_pk_u8_f32 v106, v106, 0, 0
	v_rcp_f32_e32 v111, v111
	v_max_f32_e32 v107, 1.0, v107
	v_cvt_pk_u8_f32 v106, v107, 1, v106
	v_rcp_f32_e32 v107, v112
	v_max_f32_e32 v108, 1.0, v108
	v_rcp_f32_e32 v109, v109
	v_cvt_pk_u8_f32 v106, v108, 2, v106
	v_rcp_f32_e32 v108, v113
	v_max_f32_e32 v110, 1.0, v110
	v_cvt_pk_u8_f32 v110, v110, 0, 0
	v_max_f32_e32 v111, 1.0, v111
	v_cvt_pk_u8_f32 v110, v111, 1, v110
	v_max_f32_e32 v107, 1.0, v107
	v_max_f32_e32 v109, 1.0, v109
	s_mov_b32 s30, 0x800
	v_cvt_pk_u8_f32 v107, v107, 2, v110
	v_max_f32_e32 v108, 1.0, v108
	v_cvt_pk_u8_f32 v109, v109, 3, v106
	v_add_co_u32_e32 v106, vcc, s30, v148
	v_cvt_pk_u8_f32 v108, v108, 3, v107
	s_nop 0
	v_addc_co_u32_e32 v107, vcc, 0, v149, vcc
	global_store_dwordx2 v[106:107], v[108:109], off
	v_mul_f32_e32 v108, 0xbfb8aa3b, v165
	v_fma_f32 v98, v98, v108, v126
	v_fma_f32 v99, v99, v108, v127
	v_exp_f32_e32 v98, v98
	v_exp_f32_e32 v99, v99
	v_fma_f32 v100, v100, v108, v128
	v_fma_f32 v101, v101, v108, v129
	v_exp_f32_e32 v100, v100
	v_exp_f32_e32 v101, v101
	v_fma_f32 v102, v102, v108, v138
;     template <int QVV> __device__ __forceinline__ void run(f32x4 (&acc)[2][2][4][2], const Unit& u, int wr, int wc, int fr, int fq) const {
;     ...
;             for (int ai = 0; ai < 2; ++ai)
; #pragma unroll
;                 for (int m = 0; m < 4; ++m) { if (ai >= nai) continue;
;                     const float rn = rs[ai][m] * (-LOG2E);
;                     const f32x4 x0 = acc[ai][bj][m][0] * rn + s0, x1 = acc[ai][bj][m][1] * rn + s1;
;                     f32x4 d0, d1;
; #pragma unroll
;                     for (int i = 0; i < 4; ++i) { d0[i] = __builtin_amdgcn_exp2f(x0[i]); d1[i] = __builtin_amdgcn_exp2f(x1[i]); }
;                     d0 = d0 + (1.0f / 255.0f); d1 = d1 + (1.0f / 255.0f);
;                     u32x2 w = {0u, 0u};
; #pragma unroll
;                     for (int i = 0; i < 4; ++i) { const float g0 = fmaxf(__builtin_amdgcn_rcpf(d0[i]), 1.0f), g1 = fmaxf(__builtin_amdgcn_rcpf(d1[i]), 1.0f);
;                         w.x = __builtin_amdgcn_cvt_pk_u8_f32(g0, i, w.x); w.y = __builtin_amdgcn_cvt_pk_u8_f32(g1, i, w.y); }
;                     *(u32x2*)(tb + lo + (unsigned)((ai * HALF + m * 16) * NGC + bj * HALF)) = w; }
	v_fma_f32 v103, v103, v108, v130
	v_exp_f32_e32 v102, v102
	v_exp_f32_e32 v103, v103
	v_pk_add_f32 v[98:99], v[98:99], s[0:1] op_sel_hi:[1,0]
	v_fma_f32 v104, v104, v108, v123
	v_fma_f32 v105, v105, v108, v124
	v_rcp_f32_e32 v98, v98
	v_exp_f32_e32 v104, v104
	v_exp_f32_e32 v105, v105
	v_pk_add_f32 v[100:101], v[100:101], s[0:1] op_sel_hi:[1,0]
	v_rcp_f32_e32 v99, v99
	v_rcp_f32_e32 v100, v100
	v_pk_add_f32 v[102:103], v[102:103], s[0:1] op_sel_hi:[1,0]
	v_max_f32_e32 v98, 1.0, v98
	v_rcp_f32_e32 v102, v102
	v_pk_add_f32 v[104:105], v[104:105], s[0:1] op_sel_hi:[1,0]
	v_cvt_pk_u8_f32 v98, v98, 0, 0
	v_rcp_f32_e32 v103, v103
	v_max_f32_e32 v99, 1.0, v99
	v_cvt_pk_u8_f32 v98, v99, 1, v98
	v_rcp_f32_e32 v99, v104
	v_max_f32_e32 v100, 1.0, v100
	v_rcp_f32_e32 v101, v101
	v_cvt_pk_u8_f32 v98, v100, 2, v98
	v_rcp_f32_e32 v100, v105
	v_max_f32_e32 v102, 1.0, v102
	v_cvt_pk_u8_f32 v102, v102, 0, 0
	v_max_f32_e32 v103, 1.0, v103
	v_cvt_pk_u8_f32 v102, v103, 1, v102
	v_max_f32_e32 v99, 1.0, v99
	v_max_f32_e32 v101, 1.0, v101
	s_mov_b32 s30, 0xc00
	v_cvt_pk_u8_f32 v99, v99, 2, v102
	v_max_f32_e32 v100, 1.0, v100
	v_cvt_pk_u8_f32 v101, v101, 3, v98
	v_add_co_u32_e32 v98, vcc, s30, v148
	v_cvt_pk_u8_f32 v100, v100, 3, v99
	s_nop 0
	v_addc_co_u32_e32 v99, vcc, 0, v149, vcc
	global_store_dwordx2 v[98:99], v[100:101], off
	v_mul_f32_e32 v100, 0xbfb8aa3b, v164
	v_fma_f32 v90, v90, v100, v126
	v_fma_f32 v91, v91, v100, v127
	v_exp_f32_e32 v90, v90
	v_exp_f32_e32 v91, v91
	v_fma_f32 v92, v92, v100, v128
	v_fma_f32 v93, v93, v100, v129
	v_exp_f32_e32 v92, v92
	v_exp_f32_e32 v93, v93
	v_fma_f32 v94, v94, v100, v138
	v_fma_f32 v95, v95, v100, v130
	v_exp_f32_e32 v94, v94
	v_exp_f32_e32 v95, v95
	v_pk_add_f32 v[90:91], v[90:91], s[0:1] op_sel_hi:[1,0]
	v_fma_f32 v96, v96, v100, v123
	v_fma_f32 v97, v97, v100, v124
	v_rcp_f32_e32 v90, v90
	v_exp_f32_e32 v96, v96
	v_exp_f32_e32 v97, v97
	v_pk_add_f32 v[92:93], v[92:93], s[0:1] op_sel_hi:[1,0]
	v_rcp_f32_e32 v91, v91
	v_rcp_f32_e32 v92, v92
	v_pk_add_f32 v[94:95], v[94:95], s[0:1] op_sel_hi:[1,0]
	v_max_f32_e32 v90, 1.0, v90
	v_rcp_f32_e32 v94, v94
	v_pk_add_f32 v[96:97], v[96:97], s[0:1] op_sel_hi:[1,0]
	v_cvt_pk_u8_f32 v90, v90, 0, 0
	v_rcp_f32_e32 v95, v95
	v_max_f32_e32 v91, 1.0, v91
	v_cvt_pk_u8_f32 v90, v91, 1, v90
	v_rcp_f32_e32 v91, v96
	v_max_f32_e32 v92, 1.0, v92
	v_rcp_f32_e32 v93, v93
	v_cvt_pk_u8_f32 v90, v92, 2, v90
	v_rcp_f32_e32 v92, v97
	v_max_f32_e32 v94, 1.0, v94
	v_cvt_pk_u8_f32 v94, v94, 0, 0
	v_max_f32_e32 v95, 1.0, v95
	v_cvt_pk_u8_f32 v94, v95, 1, v94
	v_max_f32_e32 v91, 1.0, v91
	v_max_f32_e32 v93, 1.0, v93
	s_mov_b32 s30, 0x1000
	v_cvt_pk_u8_f32 v91, v91, 2, v94
	v_max_f32_e32 v92, 1.0, v92
	v_cvt_pk_u8_f32 v93, v93, 3, v90
	v_add_co_u32_e32 v90, vcc, s30, v148
	v_cvt_pk_u8_f32 v92, v92, 3, v91
	s_nop 0
	v_addc_co_u32_e32 v91, vcc, 0, v149, vcc
	global_store_dwordx2 v[90:91], v[92:93], off
	v_mul_f32_e32 v92, 0xbfb8aa3b, v163
	v_fma_f32 v82, v82, v92, v126
	v_fma_f32 v83, v83, v92, v127
	v_exp_f32_e32 v82, v82
	v_exp_f32_e32 v83, v83
	v_fma_f32 v84, v84, v92, v128
	v_fma_f32 v85, v85, v92, v129
	v_exp_f32_e32 v84, v84
	v_exp_f32_e32 v85, v85
	v_fma_f32 v86, v86, v92, v138
	v_fma_f32 v87, v87, v92, v130
	v_exp_f32_e32 v86, v86
	v_exp_f32_e32 v87, v87
	v_pk_add_f32 v[82:83], v[82:83], s[0:1] op_sel_hi:[1,0]
	v_fma_f32 v88, v88, v92, v123
	v_fma_f32 v89, v89, v92, v124
	v_rcp_f32_e32 v82, v82
	v_exp_f32_e32 v88, v88
	v_exp_f32_e32 v89, v89
	v_pk_add_f32 v[84:85], v[84:85], s[0:1] op_sel_hi:[1,0]
	v_rcp_f32_e32 v83, v83
	v_rcp_f32_e32 v84, v84
	v_pk_add_f32 v[86:87], v[86:87], s[0:1] op_sel_hi:[1,0]
	v_max_f32_e32 v82, 1.0, v82
	v_rcp_f32_e32 v86, v86
	v_pk_add_f32 v[88:89], v[88:89], s[0:1] op_sel_hi:[1,0]
	v_cvt_pk_u8_f32 v82, v82, 0, 0
	v_rcp_f32_e32 v87, v87
	v_max_f32_e32 v83, 1.0, v83
	v_cvt_pk_u8_f32 v82, v83, 1, v82
	v_rcp_f32_e32 v83, v88
	v_max_f32_e32 v84, 1.0, v84
	v_rcp_f32_e32 v85, v85
	v_cvt_pk_u8_f32 v82, v84, 2, v82
	v_rcp_f32_e32 v84, v89
	v_max_f32_e32 v86, 1.0, v86
	v_cvt_pk_u8_f32 v86, v86, 0, 0
	v_max_f32_e32 v87, 1.0, v87
	v_cvt_pk_u8_f32 v86, v87, 1, v86
	v_max_f32_e32 v83, 1.0, v83
	v_max_f32_e32 v85, 1.0, v85
	s_mov_b32 s30, 0x1400
	v_cvt_pk_u8_f32 v83, v83, 2, v86
	v_max_f32_e32 v84, 1.0, v84
	v_cvt_pk_u8_f32 v85, v85, 3, v82
	v_add_co_u32_e32 v82, vcc, s30, v148
	v_cvt_pk_u8_f32 v84, v84, 3, v83
	s_nop 0
	v_addc_co_u32_e32 v83, vcc, 0, v149, vcc
	global_store_dwordx2 v[82:83], v[84:85], off
	v_mul_f32_e32 v84, 0xbfb8aa3b, v161
	v_fma_f32 v74, v74, v84, v126
	v_fma_f32 v75, v75, v84, v127
	v_exp_f32_e32 v74, v74
	v_exp_f32_e32 v75, v75
	v_fma_f32 v76, v76, v84, v128
	v_fma_f32 v77, v77, v84, v129
	v_exp_f32_e32 v76, v76
	v_exp_f32_e32 v77, v77
	v_fma_f32 v78, v78, v84, v138
	v_fma_f32 v79, v79, v84, v130
	v_exp_f32_e32 v78, v78
	v_exp_f32_e32 v79, v79
	v_pk_add_f32 v[74:75], v[74:75], s[0:1] op_sel_hi:[1,0]
	v_fma_f32 v80, v80, v84, v123
	v_fma_f32 v81, v81, v84, v124
	v_rcp_f32_e32 v74, v74
	v_exp_f32_e32 v80, v80
	v_exp_f32_e32 v81, v81
	v_pk_add_f32 v[76:77], v[76:77], s[0:1] op_sel_hi:[1,0]
	v_rcp_f32_e32 v75, v75
	v_rcp_f32_e32 v76, v76
	v_pk_add_f32 v[78:79], v[78:79], s[0:1] op_sel_hi:[1,0]
	v_max_f32_e32 v74, 1.0, v74
	v_rcp_f32_e32 v78, v78
	v_pk_add_f32 v[80:81], v[80:81], s[0:1] op_sel_hi:[1,0]
	v_cvt_pk_u8_f32 v74, v74, 0, 0
	v_rcp_f32_e32 v79, v79
	v_max_f32_e32 v75, 1.0, v75
	v_cvt_pk_u8_f32 v74, v75, 1, v74
	v_rcp_f32_e32 v75, v80
	v_max_f32_e32 v76, 1.0, v76
	v_rcp_f32_e32 v77, v77
	v_cvt_pk_u8_f32 v74, v76, 2, v74
	v_rcp_f32_e32 v76, v81
	v_max_f32_e32 v78, 1.0, v78
	v_cvt_pk_u8_f32 v78, v78, 0, 0
	v_max_f32_e32 v79, 1.0, v79
	v_cvt_pk_u8_f32 v78, v79, 1, v78
;     template <int QVV> __device__ __forceinline__ void run(f32x4 (&acc)[2][2][4][2], const Unit& u, int wr, int wc, int fr, int fq) const {
;     ...
;             for (int ai = 0; ai < 2; ++ai)
; #pragma unroll
;                 for (int m = 0; m < 4; ++m) { if (ai >= nai) continue;
;                     const float rn = rs[ai][m] * (-LOG2E);
;                     const f32x4 x0 = acc[ai][bj][m][0] * rn + s0, x1 = acc[ai][bj][m][1] * rn + s1;
;                     f32x4 d0, d1;
; #pragma unroll
;                     for (int i = 0; i < 4; ++i) { d0[i] = __builtin_amdgcn_exp2f(x0[i]); d1[i] = __builtin_amdgcn_exp2f(x1[i]); }
;                     d0 = d0 + (1.0f / 255.0f); d1 = d1 + (1.0f / 255.0f);
;                     u32x2 w = {0u, 0u};
; #pragma unroll
;                     for (int i = 0; i < 4; ++i) { const float g0 = fmaxf(__builtin_amdgcn_rcpf(d0[i]), 1.0f), g1 = fmaxf(__builtin_amdgcn_rcpf(d1[i]), 1.0f);
;                         w.x = __builtin_amdgcn_cvt_pk_u8_f32(g0, i, w.x); w.y = __builtin_amdgcn_cvt_pk_u8_f32(g1, i, w.y); }
;                     *(u32x2*)(tb + lo + (unsigned)((ai * HALF + m * 16) * NGC + bj * HALF)) = w; }
	v_max_f32_e32 v75, 1.0, v75
	v_max_f32_e32 v77, 1.0, v77
	s_mov_b32 s30, 0x1800
	v_cvt_pk_u8_f32 v75, v75, 2, v78
	v_max_f32_e32 v76, 1.0, v76
	v_cvt_pk_u8_f32 v77, v77, 3, v74
	v_add_co_u32_e32 v74, vcc, s30, v148
	v_cvt_pk_u8_f32 v76, v76, 3, v75
	s_nop 0
	v_addc_co_u32_e32 v75, vcc, 0, v149, vcc
	global_store_dwordx2 v[74:75], v[76:77], off
	v_mul_f32_e32 v76, 0xbfb8aa3b, v160
	v_fmac_f32_e32 v126, v66, v76
	v_fmac_f32_e32 v127, v67, v76
	v_exp_f32_e32 v66, v126
	v_exp_f32_e32 v67, v127
	v_fmac_f32_e32 v128, v68, v76
	v_fmac_f32_e32 v129, v69, v76
	v_exp_f32_e32 v68, v128
	v_exp_f32_e32 v69, v129
	v_fmac_f32_e32 v138, v70, v76
	v_fmac_f32_e32 v130, v71, v76
	v_exp_f32_e32 v70, v138
	v_exp_f32_e32 v71, v130
	v_pk_add_f32 v[66:67], v[66:67], s[0:1] op_sel_hi:[1,0]
	v_fmac_f32_e32 v123, v72, v76
	v_fmac_f32_e32 v124, v73, v76
	v_rcp_f32_e32 v66, v66
	v_exp_f32_e32 v72, v123
	v_exp_f32_e32 v73, v124
	v_pk_add_f32 v[68:69], v[68:69], s[0:1] op_sel_hi:[1,0]
	v_rcp_f32_e32 v67, v67
	v_rcp_f32_e32 v68, v68
	v_pk_add_f32 v[70:71], v[70:71], s[0:1] op_sel_hi:[1,0]
	v_max_f32_e32 v66, 1.0, v66
	v_rcp_f32_e32 v70, v70
	v_pk_add_f32 v[72:73], v[72:73], s[0:1] op_sel_hi:[1,0]
	v_cvt_pk_u8_f32 v66, v66, 0, 0
	v_rcp_f32_e32 v71, v71
	v_max_f32_e32 v67, 1.0, v67
	v_cvt_pk_u8_f32 v66, v67, 1, v66
	v_rcp_f32_e32 v67, v72
	v_max_f32_e32 v68, 1.0, v68
	v_rcp_f32_e32 v69, v69
	v_cvt_pk_u8_f32 v66, v68, 2, v66
	v_rcp_f32_e32 v68, v73
	v_max_f32_e32 v70, 1.0, v70
	v_cvt_pk_u8_f32 v70, v70, 0, 0
	v_max_f32_e32 v71, 1.0, v71
	v_cvt_pk_u8_f32 v70, v71, 1, v70
	v_max_f32_e32 v67, 1.0, v67
	v_max_f32_e32 v69, 1.0, v69
	s_mov_b32 s30, 0x1c00
	v_cvt_pk_u8_f32 v67, v67, 2, v70
	v_max_f32_e32 v68, 1.0, v68
	v_cvt_pk_u8_f32 v69, v69, 3, v66
	v_add_co_u32_e32 v66, vcc, s30, v148
	v_cvt_pk_u8_f32 v133, v133, 3, v125
	v_cvt_pk_u8_f32 v68, v68, 3, v67
	v_addc_co_u32_e32 v67, vcc, 0, v149, vcc
	global_store_dwordx2 v146, v[132:133], s[98:99]
	global_store_dwordx2 v[66:67], v[68:69], off
	global_load_dwordx4 v[70:73], v159, s[62:63] offset:528
	global_load_dwordx4 v[78:81], v159, s[62:63] offset:512
	global_load_dwordx4 v[86:89], v159, s[52:53] offset:528
	global_load_dwordx4 v[94:97], v159, s[52:53] offset:512
	s_mov_b64 s[30:31], -1
	s_andn2_b64 vcc, exec, s[38:39]
	s_waitcnt vmcnt(0)
	v_add_f32_e32 v68, v78, v94
	v_fmamk_f32 v68, v68, 0xbfb8aa3b, v236
	v_fma_f32 v62, v62, v147, v68
	v_exp_f32_e32 v78, v62
	v_add_f32_e32 v62, v70, v86
	v_fmamk_f32 v62, v62, 0xbfb8aa3b, v236
	v_fma_f32 v58, v58, v147, v62
	v_exp_f32_e32 v70, v58
	v_add_f32_e32 v58, v79, v95
	v_fmamk_f32 v58, v58, 0xbfb8aa3b, v236
	v_fma_f32 v63, v63, v147, v58
	v_exp_f32_e32 v79, v63
	v_add_f32_e32 v63, v71, v87
	v_fmamk_f32 v63, v63, 0xbfb8aa3b, v236
	v_fma_f32 v59, v59, v147, v63
	v_exp_f32_e32 v71, v59
	v_add_f32_e32 v59, v80, v96
	v_fmamk_f32 v59, v59, 0xbfb8aa3b, v236
	v_fma_f32 v64, v64, v147, v59
	v_exp_f32_e32 v80, v64
	v_add_f32_e32 v64, v72, v88
	v_fmamk_f32 v64, v64, 0xbfb8aa3b, v236
	v_fma_f32 v60, v60, v147, v64
	v_exp_f32_e32 v72, v60
	v_add_f32_e32 v60, v81, v97
	v_fmamk_f32 v60, v60, 0xbfb8aa3b, v236
	v_fma_f32 v65, v65, v147, v60
	v_exp_f32_e32 v81, v65
	v_add_f32_e32 v65, v73, v89
	v_fmamk_f32 v65, v65, 0xbfb8aa3b, v236
	v_fma_f32 v50, v50, v122, v62
	v_fma_f32 v51, v51, v122, v63
	v_fma_f32 v42, v42, v116, v62
	v_fma_f32 v43, v43, v116, v63
	v_fma_f32 v34, v34, v108, v62
	v_fma_f32 v35, v35, v108, v63
	v_fma_f32 v26, v26, v100, v62
	v_fma_f32 v27, v27, v100, v63
	v_fma_f32 v18, v18, v92, v62
	v_fma_f32 v19, v19, v92, v63
	v_fma_f32 v10, v10, v84, v62
	v_fma_f32 v11, v11, v84, v63
	v_fmac_f32_e32 v62, v2, v76
	v_fmac_f32_e32 v63, v3, v76
	v_fma_f32 v61, v61, v147, v65
	v_pk_add_f32 v[78:79], v[78:79], s[0:1] op_sel_hi:[1,0]
	v_pk_add_f32 v[70:71], v[70:71], s[0:1] op_sel_hi:[1,0]
	v_exp_f32_e32 v50, v50
	v_exp_f32_e32 v51, v51
	v_exp_f32_e32 v42, v42
	v_exp_f32_e32 v43, v43
	v_exp_f32_e32 v34, v34
	v_exp_f32_e32 v35, v35
	v_exp_f32_e32 v26, v26
	v_exp_f32_e32 v27, v27
	v_exp_f32_e32 v18, v18
	v_exp_f32_e32 v19, v19
	v_exp_f32_e32 v10, v10
	v_exp_f32_e32 v11, v11
	v_exp_f32_e32 v2, v62
	v_exp_f32_e32 v3, v63
	v_exp_f32_e32 v73, v61
	v_rcp_f32_e32 v61, v78
	v_rcp_f32_e32 v69, v70
	v_fma_f32 v52, v52, v122, v64
	v_fma_f32 v53, v53, v122, v65
	v_fma_f32 v44, v44, v116, v64
	v_fma_f32 v45, v45, v116, v65
	v_fma_f32 v36, v36, v108, v64
	v_fma_f32 v37, v37, v108, v65
	v_fma_f32 v28, v28, v100, v64
	v_fma_f32 v29, v29, v100, v65
	v_fma_f32 v20, v20, v92, v64
	v_fma_f32 v21, v21, v92, v65
	v_fma_f32 v12, v12, v84, v64
	v_fma_f32 v13, v13, v84, v65
	v_fmac_f32_e32 v64, v4, v76
	v_fmac_f32_e32 v65, v5, v76
	v_rcp_f32_e32 v70, v79
	v_rcp_f32_e32 v71, v71
	v_exp_f32_e32 v52, v52
	v_exp_f32_e32 v53, v53
	v_exp_f32_e32 v44, v44
	v_exp_f32_e32 v45, v45
	v_exp_f32_e32 v36, v36
	v_exp_f32_e32 v37, v37
	v_exp_f32_e32 v28, v28
	v_exp_f32_e32 v29, v29
	v_exp_f32_e32 v20, v20
	v_exp_f32_e32 v21, v21
	v_exp_f32_e32 v12, v12
	v_exp_f32_e32 v13, v13
	v_exp_f32_e32 v4, v64
	v_exp_f32_e32 v5, v65
	v_fma_f32 v54, v54, v122, v68
	v_fma_f32 v55, v55, v122, v58
	v_fma_f32 v46, v46, v116, v68
	v_fma_f32 v47, v47, v116, v58
	v_fma_f32 v38, v38, v108, v68
	v_fma_f32 v39, v39, v108, v58
	v_fma_f32 v30, v30, v100, v68
	v_fma_f32 v31, v31, v100, v58
	v_fma_f32 v22, v22, v92, v68
	v_fma_f32 v23, v23, v92, v58
	v_fma_f32 v14, v14, v84, v68
	v_fma_f32 v15, v15, v84, v58
	v_fmac_f32_e32 v68, v6, v76
	v_fmac_f32_e32 v58, v7, v76
	v_exp_f32_e32 v54, v54
	v_exp_f32_e32 v55, v55
	v_pk_add_f32 v[50:51], v[50:51], s[0:1] op_sel_hi:[1,0]
	v_exp_f32_e32 v46, v46
	v_exp_f32_e32 v47, v47
	v_pk_add_f32 v[42:43], v[42:43], s[0:1] op_sel_hi:[1,0]
;     template <int QVV> __device__ __forceinline__ void run(f32x4 (&acc)[2][2][4][2], const Unit& u, int wr, int wc, int fr, int fq) const {
;     ...
;             for (int ai = 0; ai < 2; ++ai)
; #pragma unroll
;                 for (int m = 0; m < 4; ++m) { if (ai >= nai) continue;
;                     const float rn = rs[ai][m] * (-LOG2E);
;                     const f32x4 x0 = acc[ai][bj][m][0] * rn + s0, x1 = acc[ai][bj][m][1] * rn + s1;
;                     f32x4 d0, d1;
; #pragma unroll
;                     for (int i = 0; i < 4; ++i) { d0[i] = __builtin_amdgcn_exp2f(x0[i]); d1[i] = __builtin_amdgcn_exp2f(x1[i]); }
;                     d0 = d0 + (1.0f / 255.0f); d1 = d1 + (1.0f / 255.0f);
;                     u32x2 w = {0u, 0u};
; #pragma unroll
;                     for (int i = 0; i < 4; ++i) { const float g0 = fmaxf(__builtin_amdgcn_rcpf(d0[i]), 1.0f), g1 = fmaxf(__builtin_amdgcn_rcpf(d1[i]), 1.0f);
;                         w.x = __builtin_amdgcn_cvt_pk_u8_f32(g0, i, w.x); w.y = __builtin_amdgcn_cvt_pk_u8_f32(g1, i, w.y); }
;                     *(u32x2*)(tb + lo + (unsigned)((ai * HALF + m * 16) * NGC + bj * HALF)) = w; }
	v_exp_f32_e32 v38, v38
	v_exp_f32_e32 v39, v39
	v_pk_add_f32 v[34:35], v[34:35], s[0:1] op_sel_hi:[1,0]
	v_exp_f32_e32 v30, v30
	v_exp_f32_e32 v31, v31
	v_pk_add_f32 v[26:27], v[26:27], s[0:1] op_sel_hi:[1,0]
	v_exp_f32_e32 v22, v22
	v_exp_f32_e32 v23, v23
	v_pk_add_f32 v[18:19], v[18:19], s[0:1] op_sel_hi:[1,0]
	v_exp_f32_e32 v14, v14
	v_exp_f32_e32 v15, v15
	v_pk_add_f32 v[10:11], v[10:11], s[0:1] op_sel_hi:[1,0]
	v_exp_f32_e32 v6, v68
	v_exp_f32_e32 v7, v58
	v_pk_add_f32 v[2:3], v[2:3], s[0:1] op_sel_hi:[1,0]
	v_max_f32_e32 v61, 1.0, v61
	v_max_f32_e32 v69, 1.0, v69
	v_fma_f32 v56, v56, v122, v59
	v_fma_f32 v57, v57, v122, v60
	v_rcp_f32_e32 v50, v50
	v_fma_f32 v48, v48, v116, v59
	v_fma_f32 v49, v49, v116, v60
	v_rcp_f32_e32 v42, v42
	v_fma_f32 v40, v40, v108, v59
	v_fma_f32 v41, v41, v108, v60
	v_rcp_f32_e32 v34, v34
	v_fma_f32 v32, v32, v100, v59
	v_fma_f32 v33, v33, v100, v60
	v_rcp_f32_e32 v26, v26
	v_fma_f32 v24, v24, v92, v59
	v_fma_f32 v25, v25, v92, v60
	v_rcp_f32_e32 v18, v18
	v_fma_f32 v16, v16, v84, v59
	v_fma_f32 v17, v17, v84, v60
	v_rcp_f32_e32 v10, v10
	v_fmac_f32_e32 v59, v8, v76
	v_fmac_f32_e32 v60, v9, v76
	v_rcp_f32_e32 v2, v2
	v_pk_add_f32 v[80:81], v[80:81], s[0:1] op_sel_hi:[1,0]
	v_pk_add_f32 v[72:73], v[72:73], s[0:1] op_sel_hi:[1,0]
	v_cvt_pk_u8_f32 v61, v61, 0, 0
	v_cvt_pk_u8_f32 v69, v69, 0, 0
	v_max_f32_e32 v70, 1.0, v70
	v_max_f32_e32 v71, 1.0, v71
	v_exp_f32_e32 v56, v56
	v_exp_f32_e32 v57, v57
	v_pk_add_f32 v[52:53], v[52:53], s[0:1] op_sel_hi:[1,0]
	v_rcp_f32_e32 v51, v51
	v_exp_f32_e32 v48, v48
	v_exp_f32_e32 v49, v49
	v_pk_add_f32 v[44:45], v[44:45], s[0:1] op_sel_hi:[1,0]
	v_rcp_f32_e32 v43, v43
	v_exp_f32_e32 v40, v40
	v_exp_f32_e32 v41, v41
	v_pk_add_f32 v[36:37], v[36:37], s[0:1] op_sel_hi:[1,0]
	v_rcp_f32_e32 v35, v35
	v_exp_f32_e32 v32, v32
	v_exp_f32_e32 v33, v33
	v_pk_add_f32 v[28:29], v[28:29], s[0:1] op_sel_hi:[1,0]
	v_rcp_f32_e32 v27, v27
	v_exp_f32_e32 v24, v24
	v_exp_f32_e32 v25, v25
	v_pk_add_f32 v[20:21], v[20:21], s[0:1] op_sel_hi:[1,0]
	v_rcp_f32_e32 v19, v19
	v_exp_f32_e32 v16, v16
	v_exp_f32_e32 v17, v17
	v_pk_add_f32 v[12:13], v[12:13], s[0:1] op_sel_hi:[1,0]
	v_rcp_f32_e32 v11, v11
	v_exp_f32_e32 v8, v59
	v_exp_f32_e32 v9, v60
	v_pk_add_f32 v[4:5], v[4:5], s[0:1] op_sel_hi:[1,0]
	v_rcp_f32_e32 v3, v3
	v_cvt_pk_u8_f32 v61, v70, 1, v61
	v_cvt_pk_u8_f32 v69, v71, 1, v69
	v_rcp_f32_e32 v70, v80
	v_rcp_f32_e32 v71, v72
	v_rcp_f32_e32 v52, v52
	v_rcp_f32_e32 v44, v44
	v_rcp_f32_e32 v36, v36
	v_rcp_f32_e32 v28, v28
	v_rcp_f32_e32 v20, v20
	v_rcp_f32_e32 v12, v12
	v_rcp_f32_e32 v4, v4
	v_pk_add_f32 v[54:55], v[54:55], s[0:1] op_sel_hi:[1,0]
	v_pk_add_f32 v[46:47], v[46:47], s[0:1] op_sel_hi:[1,0]
	v_pk_add_f32 v[38:39], v[38:39], s[0:1] op_sel_hi:[1,0]
	v_pk_add_f32 v[30:31], v[30:31], s[0:1] op_sel_hi:[1,0]
	v_pk_add_f32 v[22:23], v[22:23], s[0:1] op_sel_hi:[1,0]
	v_pk_add_f32 v[14:15], v[14:15], s[0:1] op_sel_hi:[1,0]
	v_pk_add_f32 v[6:7], v[6:7], s[0:1] op_sel_hi:[1,0]
	v_rcp_f32_e32 v54, v54
	v_max_f32_e32 v50, 1.0, v50
	v_rcp_f32_e32 v46, v46
	v_max_f32_e32 v42, 1.0, v42
	v_rcp_f32_e32 v38, v38
	v_max_f32_e32 v34, 1.0, v34
	v_rcp_f32_e32 v30, v30
	v_max_f32_e32 v26, 1.0, v26
	v_rcp_f32_e32 v22, v22
	v_max_f32_e32 v18, 1.0, v18
	v_rcp_f32_e32 v14, v14
	v_max_f32_e32 v10, 1.0, v10
	v_rcp_f32_e32 v6, v6
	v_max_f32_e32 v2, 1.0, v2
	v_pk_add_f32 v[56:57], v[56:57], s[0:1] op_sel_hi:[1,0]
	v_cvt_pk_u8_f32 v50, v50, 0, 0
	v_rcp_f32_e32 v55, v55
	v_max_f32_e32 v51, 1.0, v51
	v_pk_add_f32 v[48:49], v[48:49], s[0:1] op_sel_hi:[1,0]
	v_cvt_pk_u8_f32 v42, v42, 0, 0
	v_rcp_f32_e32 v47, v47
	v_max_f32_e32 v43, 1.0, v43
	v_pk_add_f32 v[40:41], v[40:41], s[0:1] op_sel_hi:[1,0]
	v_cvt_pk_u8_f32 v34, v34, 0, 0
	v_rcp_f32_e32 v39, v39
	v_max_f32_e32 v35, 1.0, v35
	v_pk_add_f32 v[32:33], v[32:33], s[0:1] op_sel_hi:[1,0]
	v_cvt_pk_u8_f32 v26, v26, 0, 0
	v_rcp_f32_e32 v31, v31
	v_max_f32_e32 v27, 1.0, v27
	v_pk_add_f32 v[24:25], v[24:25], s[0:1] op_sel_hi:[1,0]
	v_cvt_pk_u8_f32 v18, v18, 0, 0
	v_rcp_f32_e32 v23, v23
	v_max_f32_e32 v19, 1.0, v19
	v_pk_add_f32 v[16:17], v[16:17], s[0:1] op_sel_hi:[1,0]
	v_cvt_pk_u8_f32 v10, v10, 0, 0
	v_rcp_f32_e32 v15, v15
	v_max_f32_e32 v11, 1.0, v11
	v_pk_add_f32 v[8:9], v[8:9], s[0:1] op_sel_hi:[1,0]
	v_cvt_pk_u8_f32 v2, v2, 0, 0
; #define PG8_BAR __builtin_amdgcn_s_barrier()
;     ...
;         if (!has_next) break;
;         if (!cur.keep) {
; #pragma unroll
;             for (int a = 0; a < 2; ++a)
; #pragma unroll
;                 for (int b = 0; b < 2; ++b)
; #pragma unroll
;                     for (int m = 0; m < 4; ++m)
; #pragma unroll
;                         for (int n = 0; n < 2; ++n) { f32x2 z0, z1; asm("v_mov_b64 %0, 0\n\tv_mov_b64 %1, 0" : "=v"(z0), "=v"(z1));
;                     acc[a][b][m][n] = __builtin_shufflevector(z0, z1, 0, 1, 2, 3); }
;         }
;         cur = nxt; cA = nA; cB = nB; ++ui;
;         if (wr == 1) PG8_BAR;
;     template <int QVV> __device__ __forceinline__ void run(f32x4 (&acc)[2][2][4][2], const Unit& u, int wr, int wc, int fr, int fq) const {
;     ...
;             for (int ai = 0; ai < 2; ++ai)
; #pragma unroll
;                 for (int m = 0; m < 4; ++m) { if (ai >= nai) continue;
;                     const float rn = rs[ai][m] * (-LOG2E);
;                     const f32x4 x0 = acc[ai][bj][m][0] * rn + s0, x1 = acc[ai][bj][m][1] * rn + s1;
;                     f32x4 d0, d1;
; #pragma unroll
;                     for (int i = 0; i < 4; ++i) { d0[i] = __builtin_amdgcn_exp2f(x0[i]); d1[i] = __builtin_amdgcn_exp2f(x1[i]); }
;                     d0 = d0 + (1.0f / 255.0f); d1 = d1 + (1.0f / 255.0f);
;                     u32x2 w = {0u, 0u};
; #pragma unroll
;                     for (int i = 0; i < 4; ++i) { const float g0 = fmaxf(__builtin_amdgcn_rcpf(d0[i]), 1.0f), g1 = fmaxf(__builtin_amdgcn_rcpf(d1[i]), 1.0f);
;                         w.x = __builtin_amdgcn_cvt_pk_u8_f32(g0, i, w.x); w.y = __builtin_amdgcn_cvt_pk_u8_f32(g1, i, w.y); }
;                     *(u32x2*)(tb + lo + (unsigned)((ai * HALF + m * 16) * NGC + bj * HALF)) = w; }
	v_rcp_f32_e32 v7, v7
	v_max_f32_e32 v3, 1.0, v3
	v_max_f32_e32 v70, 1.0, v70
	v_max_f32_e32 v71, 1.0, v71
	v_cvt_pk_u8_f32 v50, v51, 1, v50
	v_rcp_f32_e32 v51, v56
	v_max_f32_e32 v52, 1.0, v52
	v_cvt_pk_u8_f32 v42, v43, 1, v42
	v_rcp_f32_e32 v43, v48
	v_max_f32_e32 v44, 1.0, v44
	v_cvt_pk_u8_f32 v34, v35, 1, v34
	v_rcp_f32_e32 v35, v40
	v_max_f32_e32 v36, 1.0, v36
	v_cvt_pk_u8_f32 v26, v27, 1, v26
	v_rcp_f32_e32 v27, v32
	v_max_f32_e32 v28, 1.0, v28
	v_cvt_pk_u8_f32 v18, v19, 1, v18
	v_rcp_f32_e32 v19, v24
	v_max_f32_e32 v20, 1.0, v20
	v_cvt_pk_u8_f32 v10, v11, 1, v10
	v_rcp_f32_e32 v11, v16
	v_max_f32_e32 v12, 1.0, v12
	v_cvt_pk_u8_f32 v2, v3, 1, v2
	v_rcp_f32_e32 v3, v8
	v_max_f32_e32 v4, 1.0, v4
	v_cvt_pk_u8_f32 v61, v70, 2, v61
	v_cvt_pk_u8_f32 v69, v71, 2, v69
	v_rcp_f32_e32 v70, v81
	v_rcp_f32_e32 v71, v73
	v_cvt_pk_u8_f32 v52, v52, 2, v50
	v_rcp_f32_e32 v50, v57
	v_rcp_f32_e32 v53, v53
	v_cvt_pk_u8_f32 v44, v44, 2, v42
	v_rcp_f32_e32 v42, v49
	v_rcp_f32_e32 v45, v45
	v_cvt_pk_u8_f32 v36, v36, 2, v34
	v_rcp_f32_e32 v34, v41
	v_rcp_f32_e32 v37, v37
	v_cvt_pk_u8_f32 v28, v28, 2, v26
	v_rcp_f32_e32 v26, v33
	v_rcp_f32_e32 v29, v29
	v_cvt_pk_u8_f32 v20, v20, 2, v18
	v_rcp_f32_e32 v18, v25
	v_rcp_f32_e32 v21, v21
	v_cvt_pk_u8_f32 v12, v12, 2, v10
	v_rcp_f32_e32 v10, v17
	v_rcp_f32_e32 v13, v13
	v_cvt_pk_u8_f32 v4, v4, 2, v2
	v_rcp_f32_e32 v2, v9
	v_rcp_f32_e32 v5, v5
	v_max_f32_e32 v54, 1.0, v54
	v_max_f32_e32 v46, 1.0, v46
	v_max_f32_e32 v38, 1.0, v38
	v_max_f32_e32 v30, 1.0, v30
	v_max_f32_e32 v22, 1.0, v22
	v_max_f32_e32 v14, 1.0, v14
	v_max_f32_e32 v6, 1.0, v6
	v_cvt_pk_u8_f32 v54, v54, 0, 0
	v_max_f32_e32 v55, 1.0, v55
	v_cvt_pk_u8_f32 v46, v46, 0, 0
	v_max_f32_e32 v47, 1.0, v47
	v_cvt_pk_u8_f32 v38, v38, 0, 0
	v_max_f32_e32 v39, 1.0, v39
	v_cvt_pk_u8_f32 v30, v30, 0, 0
	v_max_f32_e32 v31, 1.0, v31
	v_cvt_pk_u8_f32 v22, v22, 0, 0
	v_max_f32_e32 v23, 1.0, v23
	v_cvt_pk_u8_f32 v14, v14, 0, 0
	v_max_f32_e32 v15, 1.0, v15
	v_cvt_pk_u8_f32 v6, v6, 0, 0
	v_max_f32_e32 v7, 1.0, v7
	v_cvt_pk_u8_f32 v54, v55, 1, v54
	v_max_f32_e32 v51, 1.0, v51
	v_cvt_pk_u8_f32 v46, v47, 1, v46
	v_max_f32_e32 v43, 1.0, v43
	v_cvt_pk_u8_f32 v38, v39, 1, v38
	v_max_f32_e32 v35, 1.0, v35
	v_cvt_pk_u8_f32 v30, v31, 1, v30
	v_max_f32_e32 v27, 1.0, v27
	v_cvt_pk_u8_f32 v22, v23, 1, v22
	v_max_f32_e32 v19, 1.0, v19
	v_cvt_pk_u8_f32 v14, v15, 1, v14
	v_max_f32_e32 v11, 1.0, v11
	v_cvt_pk_u8_f32 v6, v7, 1, v6
	v_max_f32_e32 v3, 1.0, v3
	v_max_f32_e32 v70, 1.0, v70
	v_max_f32_e32 v71, 1.0, v71
	v_cvt_pk_u8_f32 v51, v51, 2, v54
	v_max_f32_e32 v50, 1.0, v50
	v_max_f32_e32 v53, 1.0, v53
	v_cvt_pk_u8_f32 v43, v43, 2, v46
	v_max_f32_e32 v42, 1.0, v42
	v_max_f32_e32 v45, 1.0, v45
	v_cvt_pk_u8_f32 v35, v35, 2, v38
	v_max_f32_e32 v34, 1.0, v34
	v_max_f32_e32 v37, 1.0, v37
	v_cvt_pk_u8_f32 v27, v27, 2, v30
	v_max_f32_e32 v26, 1.0, v26
	v_max_f32_e32 v29, 1.0, v29
	v_cvt_pk_u8_f32 v19, v19, 2, v22
	v_max_f32_e32 v18, 1.0, v18
	v_max_f32_e32 v21, 1.0, v21
	v_cvt_pk_u8_f32 v11, v11, 2, v14
	v_max_f32_e32 v10, 1.0, v10
	v_max_f32_e32 v13, 1.0, v13
	v_cvt_pk_u8_f32 v3, v3, 2, v6
	v_max_f32_e32 v2, 1.0, v2
	v_max_f32_e32 v5, 1.0, v5
	v_cvt_pk_u8_f32 v70, v70, 3, v61
	v_cvt_pk_u8_f32 v71, v71, 3, v69
	v_cvt_pk_u8_f32 v50, v50, 3, v51
	v_cvt_pk_u8_f32 v51, v53, 3, v52
	v_cvt_pk_u8_f32 v42, v42, 3, v43
	v_cvt_pk_u8_f32 v43, v45, 3, v44
	v_cvt_pk_u8_f32 v34, v34, 3, v35
	v_cvt_pk_u8_f32 v35, v37, 3, v36
	v_cvt_pk_u8_f32 v26, v26, 3, v27
	v_cvt_pk_u8_f32 v27, v29, 3, v28
	v_cvt_pk_u8_f32 v18, v18, 3, v19
	v_cvt_pk_u8_f32 v19, v21, 3, v20
	v_cvt_pk_u8_f32 v10, v10, 3, v11
	v_cvt_pk_u8_f32 v11, v13, 3, v12
	v_cvt_pk_u8_f32 v2, v2, 3, v3
	v_cvt_pk_u8_f32 v3, v5, 3, v4
	global_store_dwordx2 v146, v[70:71], s[98:99] offset:128
	global_store_dwordx2 v[114:115], v[50:51], off offset:128
	global_store_dwordx2 v[106:107], v[42:43], off offset:128
	global_store_dwordx2 v[98:99], v[34:35], off offset:128
	global_store_dwordx2 v[90:91], v[26:27], off offset:128
	global_store_dwordx2 v[82:83], v[18:19], off offset:128
	global_store_dwordx2 v[74:75], v[10:11], off offset:128
	global_store_dwordx2 v[66:67], v[2:3], off offset:128
	s_cbranch_vccnz .LBB0_1270
	s_andn2_b64 vcc, exec, s[48:49]
	v_mov_b64 v[2:3], 0
	v_mov_b64 v[4:5], 0
	s_cbranch_vccnz .LBB0_1269
	s_branch .LBB0_1269

; #define PG8_STAGEX(rs, bufoff, soff, voff) do { _Pragma("unroll") for (int _i = 0; _i < 2; ++_i) \
;         __builtin_amdgcn_raw_ptr_buffer_load_lds(rs, (LAS unsigned*)(lds + (bufoff) + ldsw + _i * 8192), 16, (voff)[_i], (soff), 0, 0); } while (0)
; #define PG8_LDA(dst, b, h) do { _Pragma("unroll") for (int m = 0; m < 4; ++m) _Pragma("unroll") for (int k = 0; k < 2; ++k) dst[m][k] = *(const LAS bf16x8*)(lds + PG8_SA(b, h) + aoff + m * 2048 + k * 1024); } while (0)
; #define PG8_LDB(dst, b, h) do { _Pragma("unroll") for (int n = 0; n < 2; ++n) _Pragma("unroll") for (int k = 0; k < 2; ++k) dst[n][k] = *(const LAS bf16x8*)(lds + PG8_SB(b, h) + boff + n * 2048 + k * 1024); } while (0)
; #define PG8_WAIT_V(n) asm volatile("s_waitcnt vmcnt(" #n ")" ::: "memory")
; #define PG8_WAIT_L(n) asm volatile("s_waitcnt lgkmcnt(" #n ")" ::: "memory")
; #define PG8_BAR __builtin_amdgcn_s_barrier()
;     ...
;         bool has_next; if constexpr (QV == 2) has_next = S.next_tail(ui + 1, nxt); else has_next = S.next(ui + 1, nxt);
;         const unsigned nA = has_next ? (unsigned)nxt.pm * tstepA + nxt.aoff : cA, nB = has_next ? (unsigned)nxt.pn * tstepB + nxt.boff : cB;
;         if constexpr (QV == 0) {
; #pragma nounroll
;         for (int t = 0; t < nt; t += 2) {
;             const bool last = (t == nt - 2);
;             const unsigned a1 = cA + (unsigned)(t + 1) * kstep;
;             const unsigned a2 = last ? nA : cA + (unsigned)(t + 2) * kstep, b2 = last ? nB : cB + (unsigned)(t + 2) * kstep;
;             const unsigned a3 = a2 + kstep, b3 = b2 + kstep;
;             PG8_LDB(B0, 0, 0); PG8_LDB(B1, 0, 1); PG8_SCHED; PG8_LDA(At, 0, 0); PG8_STAGEX(rsA, PG8_SA(1, 1), a1 + hstepA, voffA);
;             PG8_WAIT_V(8); PG8_WAIT_L(0); PG8_BAR; PG8_MMA(0, 0, At, B0); PG8_MMA(0, 1, At, B1); PG8_BAR; PG8_SCHED;
;     ...
;         if (!cur.keep) {
; #pragma unroll
;             for (int a = 0; a < 2; ++a)
; #pragma unroll
;                 for (int b = 0; b < 2; ++b)
; #pragma unroll
;                     for (int m = 0; m < 4; ++m)
; #pragma unroll
;                         for (int n = 0; n < 2; ++n) { f32x2 z0, z1; asm("v_mov_b64 %0, 0\n\tv_mov_b64 %1, 0" : "=v"(z0), "=v"(z1));
;                     acc[a][b][m][n] = __builtin_shufflevector(z0, z1, 0, 1, 2, 3); }
;         }
;         cur = nxt; cA = nA; cB = nB; ++ui;
;         if (wr == 1) PG8_BAR;
.LBB0_1650:
	s_lshl_b32 s55, s54, 20
	s_and_b64 s[30:31], s[38:39], exec
	s_cselect_b32 s30, s55, s61
	s_lshl_b32 s58, s53, 20
	s_and_b64 s[42:43], s[38:39], exec
	v_mov_b64_e32 v[12:13], v[4:5]
	v_mov_b64_e32 v[20:21], v[4:5]
	s_waitcnt vmcnt(15)
	v_mov_b64_e32 v[28:29], v[4:5]
	v_mov_b64_e32 v[36:37], v[4:5]
	v_mov_b64_e32 v[44:45], v[4:5]
	v_mov_b64_e32 v[52:53], v[4:5]
	v_mov_b64_e32 v[60:61], v[4:5]
	v_mov_b64_e32 v[8:9], v[4:5]
	v_mov_b64_e32 v[16:17], v[4:5]
	v_mov_b64_e32 v[24:25], v[4:5]
	v_mov_b64_e32 v[32:33], v[4:5]
	v_mov_b64_e32 v[40:41], v[4:5]
	v_mov_b64_e32 v[48:49], v[4:5]
	v_mov_b64_e32 v[56:57], v[4:5]
	v_mov_b64_e32 v[64:65], v[4:5]
	v_mov_b64_e32 v[68:69], v[4:5]
	v_mov_b64_e32 v[76:77], v[4:5]
	v_mov_b64_e32 v[92:93], v[4:5]
	v_mov_b64_e32 v[108:109], v[4:5]
	v_mov_b64_e32 v[116:117], v[4:5]
	v_mov_b64_e32 v[124:125], v[4:5]
	v_mov_b64_e32 v[132:133], v[4:5]
	v_mov_b64_e32 v[140:141], v[4:5]
	v_mov_b64_e32 v[72:73], v[4:5]
	v_mov_b64_e32 v[80:81], v[4:5]
	v_mov_b64_e32 v[96:97], v[4:5]
	v_mov_b64_e32 v[112:113], v[4:5]
	v_mov_b64_e32 v[120:121], v[4:5]
	v_mov_b64_e32 v[128:129], v[4:5]
	v_mov_b64_e32 v[136:137], v[4:5]
	v_mov_b64_e32 v[144:145], v[4:5]
	s_cselect_b32 s31, s58, s62
	s_add_i32 s61, s61, 0x80080
	s_addk_i32 s62, 0x100
	s_mov_b32 s63, -2
	v_mov_b64_e32 v[10:11], v[2:3]
	v_mov_b64_e32 v[18:19], v[2:3]
	v_mov_b64_e32 v[26:27], v[2:3]
	v_mov_b64_e32 v[34:35], v[2:3]
	v_mov_b64_e32 v[42:43], v[2:3]
	v_mov_b64_e32 v[50:51], v[2:3]
	v_mov_b64_e32 v[58:59], v[2:3]
	v_mov_b64_e32 v[6:7], v[2:3]
	v_mov_b64_e32 v[14:15], v[2:3]
	v_mov_b64_e32 v[22:23], v[2:3]
	v_mov_b64_e32 v[30:31], v[2:3]
	v_mov_b64_e32 v[38:39], v[2:3]
	v_mov_b64_e32 v[46:47], v[2:3]
	v_mov_b64_e32 v[54:55], v[2:3]
	v_mov_b64_e32 v[62:63], v[2:3]
	v_mov_b64_e32 v[66:67], v[2:3]
	v_mov_b64_e32 v[74:75], v[2:3]
	v_mov_b64_e32 v[90:91], v[2:3]
	v_mov_b64_e32 v[106:107], v[2:3]
	v_mov_b64_e32 v[114:115], v[2:3]
	v_mov_b64_e32 v[122:123], v[2:3]
	v_mov_b64_e32 v[130:131], v[2:3]
	v_mov_b64_e32 v[138:139], v[2:3]
	v_mov_b64_e32 v[70:71], v[2:3]
	v_mov_b64_e32 v[78:79], v[2:3]
	v_mov_b64_e32 v[94:95], v[2:3]
	v_mov_b64_e32 v[110:111], v[2:3]
	v_mov_b64_e32 v[118:119], v[2:3]
	v_mov_b64_e32 v[126:127], v[2:3]
	v_mov_b64_e32 v[134:135], v[2:3]
	v_mov_b64_e32 v[142:143], v[2:3]
	s_cmp_eq_u32 s52, 1
	s_cbranch_scc1 .Lrst_skip_1651
	s_andn2_b64 vcc, exec, s[46:47]
	s_cbranch_vccnz .Lrst_skip_1651
	s_barrier
.Lrst_skip_1651:
.LBB0_1651:
	v_add_u32_e32 v102, 0x10000, v172
	v_add_u32_e32 v146, 0x14000, v172
	ds_read_b128 v[82:85], v102
	ds_read_b128 v[86:89], v102 offset:1024
	ds_read_b128 v[98:101], v102 offset:2048
	ds_read_b128 v[102:105], v102 offset:3072
	ds_read_b128 v[150:153], v146
	ds_read_b128 v[154:157], v146 offset:1024
	ds_read_b128 v[182:185], v146 offset:2048
	ds_read_b128 v[186:189], v146 offset:3072
	s_add_i32 s42, s61, 0xfff80080
	s_cmp_eq_u32 s63, 28
	s_cselect_b32 s66, s30, s42
	s_cselect_b32 s65, s31, s62
	s_or_b32 s64, s66, 0x80
	s_mov_b32 m0, s29
	ds_read_b128 v[190:193], v173
	ds_read_b128 v[194:197], v173 offset:1024
	ds_read_b128 v[198:201], v173 offset:2048
	ds_read_b128 v[202:205], v173 offset:3072
	ds_read_b128 v[206:209], v173 offset:4096
	ds_read_b128 v[210:213], v173 offset:5120
	ds_read_b128 v[214:217], v173 offset:6144
	ds_read_b128 v[218:221], v173 offset:7168
	buffer_load_dwordx4 v159, s[76:79], s61 offen lds
	s_mov_b32 m0, s50
	s_nop 0
	buffer_load_dwordx4 v163, s[76:79], s61 offen lds
	s_waitcnt vmcnt(8)
	s_waitcnt lgkmcnt(0)
	s_setprio 1
	s_barrier
	v_mfma_f32_16x16x32_bf16 v[142:145], v[82:85], v[190:193], v[142:145]
	v_mfma_f32_16x16x32_bf16 v[134:137], v[98:101], v[190:193], v[134:137]
	v_mfma_f32_16x16x32_bf16 v[126:129], v[82:85], v[198:201], v[126:129]
	v_mfma_f32_16x16x32_bf16 v[118:121], v[98:101], v[198:201], v[118:121]
	v_mfma_f32_16x16x32_bf16 v[110:113], v[82:85], v[206:209], v[110:113]
	v_mfma_f32_16x16x32_bf16 v[94:97], v[98:101], v[206:209], v[94:97]
	v_mfma_f32_16x16x32_bf16 v[78:81], v[82:85], v[214:217], v[78:81]
	v_mfma_f32_16x16x32_bf16 v[70:73], v[98:101], v[214:217], v[70:73]
	v_mfma_f32_16x16x32_bf16 v[142:145], v[86:89], v[194:197], v[142:145]
	v_mfma_f32_16x16x32_bf16 v[134:137], v[102:105], v[194:197], v[134:137]
	v_mfma_f32_16x16x32_bf16 v[126:129], v[86:89], v[202:205], v[126:129]
	v_mfma_f32_16x16x32_bf16 v[118:121], v[102:105], v[202:205], v[118:121]
	v_mfma_f32_16x16x32_bf16 v[110:113], v[86:89], v[210:213], v[110:113]
	v_mfma_f32_16x16x32_bf16 v[94:97], v[102:105], v[210:213], v[94:97]
	v_mfma_f32_16x16x32_bf16 v[78:81], v[86:89], v[218:221], v[78:81]
	v_mfma_f32_16x16x32_bf16 v[70:73], v[102:105], v[218:221], v[70:73]
	v_mfma_f32_16x16x32_bf16 v[138:141], v[150:153], v[190:193], v[138:141]
	v_mfma_f32_16x16x32_bf16 v[130:133], v[182:185], v[190:193], v[130:133]
	v_mfma_f32_16x16x32_bf16 v[122:125], v[150:153], v[198:201], v[122:125]
	v_mfma_f32_16x16x32_bf16 v[114:117], v[182:185], v[198:201], v[114:117]
	v_mfma_f32_16x16x32_bf16 v[106:109], v[150:153], v[206:209], v[106:109]
	v_mfma_f32_16x16x32_bf16 v[90:93], v[182:185], v[206:209], v[90:93]
	v_mfma_f32_16x16x32_bf16 v[74:77], v[150:153], v[214:217], v[74:77]
	v_mfma_f32_16x16x32_bf16 v[66:69], v[182:185], v[214:217], v[66:69]
	v_mfma_f32_16x16x32_bf16 v[138:141], v[154:157], v[194:197], v[138:141]
	v_mfma_f32_16x16x32_bf16 v[130:133], v[186:189], v[194:197], v[130:133]
	v_mfma_f32_16x16x32_bf16 v[122:125], v[154:157], v[202:205], v[122:125]
	v_mfma_f32_16x16x32_bf16 v[114:117], v[186:189], v[202:205], v[114:117]
	v_mfma_f32_16x16x32_bf16 v[106:109], v[154:157], v[210:213], v[106:109]
	v_mfma_f32_16x16x32_bf16 v[90:93], v[186:189], v[210:213], v[90:93]
	v_mfma_f32_16x16x32_bf16 v[74:77], v[154:157], v[218:221], v[74:77]
	v_mfma_f32_16x16x32_bf16 v[66:69], v[186:189], v[218:221], v[66:69]
	s_barrier
; #define PG8_STAGEX(rs, bufoff, soff, voff) do { _Pragma("unroll") for (int _i = 0; _i < 2; ++_i) \
;         __builtin_amdgcn_raw_ptr_buffer_load_lds(rs, (LAS unsigned*)(lds + (bufoff) + ldsw + _i * 8192), 16, (voff)[_i], (soff), 0, 0); } while (0)
; #define PG8_LDA(dst, b, h) do { _Pragma("unroll") for (int m = 0; m < 4; ++m) _Pragma("unroll") for (int k = 0; k < 2; ++k) dst[m][k] = *(const LAS bf16x8*)(lds + PG8_SA(b, h) + aoff + m * 2048 + k * 1024); } while (0)
; #define PG8_LDB(dst, b, h) do { _Pragma("unroll") for (int n = 0; n < 2; ++n) _Pragma("unroll") for (int k = 0; k < 2; ++k) dst[n][k] = *(const LAS bf16x8*)(lds + PG8_SB(b, h) + boff + n * 2048 + k * 1024); } while (0)
; #define PG8_WAIT_V(n) asm volatile("s_waitcnt vmcnt(" #n ")" ::: "memory")
; #define PG8_WAIT_L(n) asm volatile("s_waitcnt lgkmcnt(" #n ")" ::: "memory")
; #define PG8_BAR __builtin_amdgcn_s_barrier()
; #define PG8_SCHED __builtin_amdgcn_sched_barrier(0)
;     ...
;             PG8_LDB(B0, 0, 0); PG8_LDB(B1, 0, 1); PG8_SCHED; PG8_LDA(At, 0, 0); PG8_STAGEX(rsA, PG8_SA(1, 1), a1 + hstepA, voffA);
;             PG8_WAIT_V(8); PG8_WAIT_L(0); PG8_BAR; PG8_MMA(0, 0, At, B0); PG8_MMA(0, 1, At, B1); PG8_BAR; PG8_SCHED;
;             PG8_LDA(At, 0, 1); PG8_STAGEX(rsB, PG8_SB(0, 0), b2, voffB); PG8_STAGEX(rsB, PG8_SB(0, 1), b2 + hstepB, voffB); PG8_STAGEX(rsA, PG8_SA(0, 0), a2, voffA);
;             PG8_WAIT_V(8); PG8_WAIT_L(0); PG8_BAR; PG8_MMA(1, 0, At, B0); PG8_MMA(1, 1, At, B1); PG8_BAR; PG8_SCHED;
;             PG8_LDB(B0, 1, 0); PG8_LDB(B1, 1, 1); PG8_SCHED; PG8_LDA(At, 1, 0); PG8_STAGEX(rsA, PG8_SA(0, 1), a2 + hstepA, voffA);
;             PG8_WAIT_V(8); PG8_WAIT_L(0); PG8_BAR; PG8_MMA(0, 0, At, B0); PG8_MMA(0, 1, At, B1); PG8_BAR; PG8_SCHED;
;             PG8_LDA(At, 1, 1); PG8_STAGEX(rsB, PG8_SB(1, 0), b3, voffB); PG8_STAGEX(rsB, PG8_SB(1, 1), b3 + hstepB, voffB); PG8_STAGEX(rsA, PG8_SA(1, 0), a3, voffA);
;             PG8_WAIT_V(8); PG8_WAIT_L(0); PG8_BAR; PG8_MMA(1, 0, At, B0); PG8_MMA(1, 1, At, B1); PG8_BAR; PG8_SCHED;
	s_setprio 0
	s_mov_b32 m0, s16
	s_mov_b32 s42, s78
	s_mov_b32 s43, s79
	ds_read_b128 v[190:193], v173 offset:16384
	ds_read_b128 v[194:197], v173 offset:17408
	ds_read_b128 v[198:201], v173 offset:18432
	ds_read_b128 v[202:205], v173 offset:19456
	ds_read_b128 v[206:209], v173 offset:20480
	ds_read_b128 v[210:213], v173 offset:21504
	ds_read_b128 v[214:217], v173 offset:22528
	ds_read_b128 v[218:221], v173 offset:23552
	buffer_load_dwordx4 v161, s[40:43], s65 offen lds
	s_mov_b32 m0, s17
	s_add_i32 s67, s65, 0x80000
	buffer_load_dwordx4 v165, s[40:43], s65 offen lds
	s_mov_b32 m0, s18
	s_nop 0
	buffer_load_dwordx4 v161, s[40:43], s67 offen lds
	s_mov_b32 m0, s19
	s_nop 0
	buffer_load_dwordx4 v165, s[40:43], s67 offen lds
	s_mov_b32 m0, s15
	s_nop 0
	buffer_load_dwordx4 v159, s[76:79], s66 offen lds
	s_mov_b32 m0, s20
	s_nop 0
	buffer_load_dwordx4 v163, s[76:79], s66 offen lds
	s_waitcnt vmcnt(8)
	s_waitcnt lgkmcnt(0)
	s_setprio 1
	s_barrier
	v_mfma_f32_16x16x32_bf16 v[62:65], v[82:85], v[190:193], v[62:65]
	v_mfma_f32_16x16x32_bf16 v[54:57], v[98:101], v[190:193], v[54:57]
	v_mfma_f32_16x16x32_bf16 v[46:49], v[82:85], v[198:201], v[46:49]
	v_mfma_f32_16x16x32_bf16 v[38:41], v[98:101], v[198:201], v[38:41]
	v_mfma_f32_16x16x32_bf16 v[30:33], v[82:85], v[206:209], v[30:33]
	v_mfma_f32_16x16x32_bf16 v[22:25], v[98:101], v[206:209], v[22:25]
	v_mfma_f32_16x16x32_bf16 v[14:17], v[82:85], v[214:217], v[14:17]
	v_mfma_f32_16x16x32_bf16 v[6:9], v[98:101], v[214:217], v[6:9]
	v_mfma_f32_16x16x32_bf16 v[62:65], v[86:89], v[194:197], v[62:65]
	v_mfma_f32_16x16x32_bf16 v[54:57], v[102:105], v[194:197], v[54:57]
	v_mfma_f32_16x16x32_bf16 v[46:49], v[86:89], v[202:205], v[46:49]
	v_mfma_f32_16x16x32_bf16 v[38:41], v[102:105], v[202:205], v[38:41]
	v_mfma_f32_16x16x32_bf16 v[30:33], v[86:89], v[210:213], v[30:33]
	v_mfma_f32_16x16x32_bf16 v[22:25], v[102:105], v[210:213], v[22:25]
	v_mfma_f32_16x16x32_bf16 v[14:17], v[86:89], v[218:221], v[14:17]
	v_mfma_f32_16x16x32_bf16 v[6:9], v[102:105], v[218:221], v[6:9]
	v_mfma_f32_16x16x32_bf16 v[58:61], v[150:153], v[190:193], v[58:61]
	v_mfma_f32_16x16x32_bf16 v[50:53], v[182:185], v[190:193], v[50:53]
	v_mfma_f32_16x16x32_bf16 v[42:45], v[150:153], v[198:201], v[42:45]
	v_mfma_f32_16x16x32_bf16 v[34:37], v[182:185], v[198:201], v[34:37]
	v_mfma_f32_16x16x32_bf16 v[26:29], v[150:153], v[206:209], v[26:29]
	v_mfma_f32_16x16x32_bf16 v[18:21], v[182:185], v[206:209], v[18:21]
	v_mfma_f32_16x16x32_bf16 v[10:13], v[150:153], v[214:217], v[10:13]
	v_mfma_f32_16x16x32_bf16 v[2:5], v[182:185], v[214:217], v[2:5]
	v_mfma_f32_16x16x32_bf16 v[58:61], v[154:157], v[194:197], v[58:61]
	v_mfma_f32_16x16x32_bf16 v[50:53], v[186:189], v[194:197], v[50:53]
	v_mfma_f32_16x16x32_bf16 v[42:45], v[154:157], v[202:205], v[42:45]
	v_mfma_f32_16x16x32_bf16 v[34:37], v[186:189], v[202:205], v[34:37]
	v_mfma_f32_16x16x32_bf16 v[26:29], v[154:157], v[210:213], v[26:29]
	v_mfma_f32_16x16x32_bf16 v[18:21], v[186:189], v[210:213], v[18:21]
	v_mfma_f32_16x16x32_bf16 v[10:13], v[154:157], v[218:221], v[10:13]
	v_mfma_f32_16x16x32_bf16 v[2:5], v[186:189], v[218:221], v[2:5]
	s_barrier
	s_setprio 0
	v_add_u32_e32 v102, 0x18000, v172
	v_add_u32_e32 v146, 0x1c000, v172
	ds_read_b128 v[82:85], v102
	ds_read_b128 v[86:89], v102 offset:1024
	ds_read_b128 v[98:101], v102 offset:2048
	ds_read_b128 v[102:105], v102 offset:3072
	ds_read_b128 v[150:153], v146
	ds_read_b128 v[154:157], v146 offset:1024
	ds_read_b128 v[182:185], v146 offset:2048
	ds_read_b128 v[186:189], v146 offset:3072
	s_add_i32 s66, s66, 0x80000
	s_mov_b32 m0, s21
	ds_read_b128 v[190:193], v173 offset:32768
	ds_read_b128 v[194:197], v173 offset:33792
	ds_read_b128 v[198:201], v173 offset:34816
	ds_read_b128 v[202:205], v173 offset:35840
	ds_read_b128 v[206:209], v173 offset:36864
	ds_read_b128 v[210:213], v173 offset:37888
	ds_read_b128 v[214:217], v173 offset:38912
	ds_read_b128 v[218:221], v173 offset:39936
	buffer_load_dwordx4 v159, s[76:79], s66 offen lds
	s_mov_b32 m0, s22
	s_nop 0
	buffer_load_dwordx4 v163, s[76:79], s66 offen lds
	s_waitcnt vmcnt(8)
	s_waitcnt lgkmcnt(0)
	s_setprio 1
	s_barrier
; #define PG8_STAGEX(rs, bufoff, soff, voff) do { _Pragma("unroll") for (int _i = 0; _i < 2; ++_i) \
;         __builtin_amdgcn_raw_ptr_buffer_load_lds(rs, (LAS unsigned*)(lds + (bufoff) + ldsw + _i * 8192), 16, (voff)[_i], (soff), 0, 0); } while (0)
; #define PG8_LDA(dst, b, h) do { _Pragma("unroll") for (int m = 0; m < 4; ++m) _Pragma("unroll") for (int k = 0; k < 2; ++k) dst[m][k] = *(const LAS bf16x8*)(lds + PG8_SA(b, h) + aoff + m * 2048 + k * 1024); } while (0)
; #define PG8_LDB(dst, b, h) do { _Pragma("unroll") for (int n = 0; n < 2; ++n) _Pragma("unroll") for (int k = 0; k < 2; ++k) dst[n][k] = *(const LAS bf16x8*)(lds + PG8_SB(b, h) + boff + n * 2048 + k * 1024); } while (0)
; #define PG8_WAIT_V(n) asm volatile("s_waitcnt vmcnt(" #n ")" ::: "memory")
; #define PG8_WAIT_L(n) asm volatile("s_waitcnt lgkmcnt(" #n ")" ::: "memory")
; #define PG8_BAR __builtin_amdgcn_s_barrier()
; #define PG8_SCHED __builtin_amdgcn_sched_barrier(0)
;     ...
;             PG8_LDB(B0, 1, 0); PG8_LDB(B1, 1, 1); PG8_SCHED; PG8_LDA(At, 1, 0); PG8_STAGEX(rsA, PG8_SA(0, 1), a2 + hstepA, voffA);
;             PG8_WAIT_V(8); PG8_WAIT_L(0); PG8_BAR; PG8_MMA(0, 0, At, B0); PG8_MMA(0, 1, At, B1); PG8_BAR; PG8_SCHED;
;             PG8_LDA(At, 1, 1); PG8_STAGEX(rsB, PG8_SB(1, 0), b3, voffB); PG8_STAGEX(rsB, PG8_SB(1, 1), b3 + hstepB, voffB); PG8_STAGEX(rsA, PG8_SA(1, 0), a3, voffA);
;             PG8_WAIT_V(8); PG8_WAIT_L(0); PG8_BAR; PG8_MMA(1, 0, At, B0); PG8_MMA(1, 1, At, B1); PG8_BAR; PG8_SCHED;
;     ...
;         if (wr == 0) PG8_BAR;
	v_mfma_f32_16x16x32_bf16 v[142:145], v[82:85], v[190:193], v[142:145]
	v_mfma_f32_16x16x32_bf16 v[134:137], v[98:101], v[190:193], v[134:137]
	v_mfma_f32_16x16x32_bf16 v[126:129], v[82:85], v[198:201], v[126:129]
	v_mfma_f32_16x16x32_bf16 v[118:121], v[98:101], v[198:201], v[118:121]
	v_mfma_f32_16x16x32_bf16 v[110:113], v[82:85], v[206:209], v[110:113]
	v_mfma_f32_16x16x32_bf16 v[94:97], v[98:101], v[206:209], v[94:97]
	v_mfma_f32_16x16x32_bf16 v[78:81], v[82:85], v[214:217], v[78:81]
	v_mfma_f32_16x16x32_bf16 v[70:73], v[98:101], v[214:217], v[70:73]
	v_mfma_f32_16x16x32_bf16 v[142:145], v[86:89], v[194:197], v[142:145]
	v_mfma_f32_16x16x32_bf16 v[134:137], v[102:105], v[194:197], v[134:137]
	v_mfma_f32_16x16x32_bf16 v[126:129], v[86:89], v[202:205], v[126:129]
	v_mfma_f32_16x16x32_bf16 v[118:121], v[102:105], v[202:205], v[118:121]
	v_mfma_f32_16x16x32_bf16 v[110:113], v[86:89], v[210:213], v[110:113]
	v_mfma_f32_16x16x32_bf16 v[94:97], v[102:105], v[210:213], v[94:97]
	v_mfma_f32_16x16x32_bf16 v[78:81], v[86:89], v[218:221], v[78:81]
	v_mfma_f32_16x16x32_bf16 v[70:73], v[102:105], v[218:221], v[70:73]
	v_mfma_f32_16x16x32_bf16 v[138:141], v[150:153], v[190:193], v[138:141]
	v_mfma_f32_16x16x32_bf16 v[130:133], v[182:185], v[190:193], v[130:133]
	v_mfma_f32_16x16x32_bf16 v[122:125], v[150:153], v[198:201], v[122:125]
	v_mfma_f32_16x16x32_bf16 v[114:117], v[182:185], v[198:201], v[114:117]
	v_mfma_f32_16x16x32_bf16 v[106:109], v[150:153], v[206:209], v[106:109]
	v_mfma_f32_16x16x32_bf16 v[90:93], v[182:185], v[206:209], v[90:93]
	v_mfma_f32_16x16x32_bf16 v[74:77], v[150:153], v[214:217], v[74:77]
	v_mfma_f32_16x16x32_bf16 v[66:69], v[182:185], v[214:217], v[66:69]
	v_mfma_f32_16x16x32_bf16 v[138:141], v[154:157], v[194:197], v[138:141]
	v_mfma_f32_16x16x32_bf16 v[130:133], v[186:189], v[194:197], v[130:133]
	v_mfma_f32_16x16x32_bf16 v[122:125], v[154:157], v[202:205], v[122:125]
	v_mfma_f32_16x16x32_bf16 v[114:117], v[186:189], v[202:205], v[114:117]
	v_mfma_f32_16x16x32_bf16 v[106:109], v[154:157], v[210:213], v[106:109]
	v_mfma_f32_16x16x32_bf16 v[90:93], v[186:189], v[210:213], v[90:93]
	v_mfma_f32_16x16x32_bf16 v[74:77], v[154:157], v[218:221], v[74:77]
	v_mfma_f32_16x16x32_bf16 v[66:69], v[186:189], v[218:221], v[66:69]
	s_barrier
	s_setprio 0
	s_mov_b32 m0, s23
	s_or_b32 s66, s65, 0x80
	ds_read_b128 v[190:193], v173 offset:49152
	ds_read_b128 v[194:197], v173 offset:50176
	ds_read_b128 v[198:201], v173 offset:51200
	ds_read_b128 v[202:205], v173 offset:52224
	ds_read_b128 v[206:209], v173 offset:53248
	ds_read_b128 v[210:213], v173 offset:54272
	ds_read_b128 v[214:217], v173 offset:55296
	ds_read_b128 v[218:221], v173 offset:56320
	buffer_load_dwordx4 v161, s[40:43], s66 offen lds
	s_mov_b32 m0, s24
	s_add_i32 s65, s65, 0x80080
	buffer_load_dwordx4 v165, s[40:43], s66 offen lds
	s_mov_b32 m0, s27
	s_nop 0
	buffer_load_dwordx4 v161, s[40:43], s65 offen lds
	s_mov_b32 m0, s28
	s_nop 0
	buffer_load_dwordx4 v165, s[40:43], s65 offen lds
	s_mov_b32 m0, s25
	s_nop 0
	buffer_load_dwordx4 v159, s[76:79], s64 offen lds
	s_mov_b32 m0, s26
	s_nop 0
	buffer_load_dwordx4 v163, s[76:79], s64 offen lds
	s_waitcnt vmcnt(8)
	s_waitcnt lgkmcnt(0)
	s_setprio 1
	s_barrier
	v_mfma_f32_16x16x32_bf16 v[62:65], v[82:85], v[190:193], v[62:65]
	v_mfma_f32_16x16x32_bf16 v[54:57], v[98:101], v[190:193], v[54:57]
	v_mfma_f32_16x16x32_bf16 v[46:49], v[82:85], v[198:201], v[46:49]
	v_mfma_f32_16x16x32_bf16 v[38:41], v[98:101], v[198:201], v[38:41]
	v_mfma_f32_16x16x32_bf16 v[30:33], v[82:85], v[206:209], v[30:33]
	v_mfma_f32_16x16x32_bf16 v[22:25], v[98:101], v[206:209], v[22:25]
	v_mfma_f32_16x16x32_bf16 v[14:17], v[82:85], v[214:217], v[14:17]
	v_mfma_f32_16x16x32_bf16 v[6:9], v[98:101], v[214:217], v[6:9]
	v_mfma_f32_16x16x32_bf16 v[62:65], v[86:89], v[194:197], v[62:65]
	v_mfma_f32_16x16x32_bf16 v[54:57], v[102:105], v[194:197], v[54:57]
	v_mfma_f32_16x16x32_bf16 v[46:49], v[86:89], v[202:205], v[46:49]
	v_mfma_f32_16x16x32_bf16 v[38:41], v[102:105], v[202:205], v[38:41]
	v_mfma_f32_16x16x32_bf16 v[30:33], v[86:89], v[210:213], v[30:33]
	v_mfma_f32_16x16x32_bf16 v[22:25], v[102:105], v[210:213], v[22:25]
	v_mfma_f32_16x16x32_bf16 v[14:17], v[86:89], v[218:221], v[14:17]
	v_mfma_f32_16x16x32_bf16 v[6:9], v[102:105], v[218:221], v[6:9]
	v_mfma_f32_16x16x32_bf16 v[58:61], v[150:153], v[190:193], v[58:61]
	v_mfma_f32_16x16x32_bf16 v[50:53], v[182:185], v[190:193], v[50:53]
	v_mfma_f32_16x16x32_bf16 v[42:45], v[150:153], v[198:201], v[42:45]
	v_mfma_f32_16x16x32_bf16 v[34:37], v[182:185], v[198:201], v[34:37]
	v_mfma_f32_16x16x32_bf16 v[26:29], v[150:153], v[206:209], v[26:29]
	v_mfma_f32_16x16x32_bf16 v[18:21], v[182:185], v[206:209], v[18:21]
	v_mfma_f32_16x16x32_bf16 v[10:13], v[150:153], v[214:217], v[10:13]
	v_mfma_f32_16x16x32_bf16 v[2:5], v[182:185], v[214:217], v[2:5]
	v_mfma_f32_16x16x32_bf16 v[58:61], v[154:157], v[194:197], v[58:61]
	v_mfma_f32_16x16x32_bf16 v[50:53], v[186:189], v[194:197], v[50:53]
	v_mfma_f32_16x16x32_bf16 v[42:45], v[154:157], v[202:205], v[42:45]
	v_mfma_f32_16x16x32_bf16 v[34:37], v[186:189], v[202:205], v[34:37]
	v_mfma_f32_16x16x32_bf16 v[26:29], v[154:157], v[210:213], v[26:29]
	v_mfma_f32_16x16x32_bf16 v[18:21], v[186:189], v[210:213], v[18:21]
	v_mfma_f32_16x16x32_bf16 v[10:13], v[154:157], v[218:221], v[10:13]
	v_mfma_f32_16x16x32_bf16 v[2:5], v[186:189], v[218:221], v[2:5]
	s_barrier
	s_setprio 0
	s_add_i32 s63, s63, 2
	s_addk_i32 s61, 0x100
	s_addk_i32 s62, 0x100
	s_cmp_gt_u32 s63, 29
	s_cbranch_scc0 .LBB0_1651
	s_and_b64 vcc, exec, s[48:49]
	s_cbranch_vccz .LBB0_1654
	s_barrier

; __device__ __forceinline__ void row_rstd(const unsigned long long* ssq, int row0, float (&rs)[2][4]) {
;     unsigned long long q[2][4];
; #pragma unroll
;     for (int ai = 0; ai < 2; ++ai)
; #pragma unroll
;         for (int m = 0; m < 4; ++m) q[ai][m] = ssq[row0 + ai * HALF + m * 16];
;     asm volatile("" : "+v"(q[0][0]), "+v"(q[0][1]), "+v"(q[0][2]), "+v"(q[0][3]), "+v"(q[1][0]), "+v"(q[1][1]), "+v"(q[1][2]), "+v"(q[1][3]));
; #pragma unroll
;     for (int ai = 0; ai < 2; ++ai)
; #pragma unroll
;         for (int m = 0; m < 4; ++m) {
;             const float qf = __builtin_fmaf((float)(unsigned)(q[ai][m] >> 32), 4294967296.0f, (float)(unsigned)q[ai][m]);
;             rs[ai][m] = __builtin_amdgcn_rsqf(__builtin_fmaf(qf, 1.0f / (SSQ_SCALE * DM), EPS)); }
; }
;     template <int QVV> __device__ __forceinline__ void run(f32x4 (&acc)[2][2][4][2], const Unit& u, int wr, int wc, int fr, int fq) const {
;         constexpr int nai = (QVV == 2) ? 1 : 2; const int r0 = u.pm * BM + (QVV == 2 ? (u.seg - 1) * HALF : 0);
;         char* tb = (char*)(O + (size_t)r0 * DFF + u.pn * HALF);
;         const int v = u.pm < 4 ? 4 : ((u.pm - 4) >> 5);
;         const char* swb = (const char*)(sw + (size_t)v * SWLD + u.pn * BM);
;         unsigned lo = (unsigned)((wr * 64 + fr) * DFF + wc * 32 + 8 * fq) * 2u;
;         unsigned co = (unsigned)(wc * 32 + 8 * fq) * 4u;
;         asm volatile("" : "+v"(lo), "+v"(co));
;         float rs[2][4]; row_rstd(ssq, r0 + wr * 64 + fr, rs);
;         f32x4 sg[2], su[2], sgn[2];
; #pragma unroll
;         for (int n = 0; n < 2; ++n) { sg[n] = *(const f32x4*)(swb + co + n * 16); su[n] = *(const f32x4*)(swb + co + HALF * 4 + n * 16); sgn[n] = sg[n] * (-LOG2E); }
.LBB0_1656:
	s_lshl_b32 s30, s60, 8
	v_add_u32_e32 v82, s30, v169
	v_ashrrev_i32_e32 v83, 31, v82
	v_mov_b32_e32 v98, v171
	v_mov_b32_e32 v166, v170
	v_lshl_add_u64 v[82:83], v[82:83], 3, s[34:35]
	global_load_dwordx2 v[150:151], v[82:83], off
	global_load_dwordx2 v[152:153], v[82:83], off offset:128
	global_load_dwordx2 v[154:155], v[82:83], off offset:256
	global_load_dwordx2 v[156:157], v[82:83], off offset:384
	global_load_dwordx2 v[178:179], v[82:83], off offset:1024
	global_load_dwordx2 v[180:181], v[82:83], off offset:1152
	global_load_dwordx2 v[182:183], v[82:83], off offset:1280
	global_load_dwordx2 v[184:185], v[82:83], off offset:1408
	s_mul_i32 s31, s60, 0x2b0000
	s_mul_hi_i32 s30, s30, 0x2b00
	s_add_u32 s60, s2, s31
	s_addc_u32 s61, s3, s30
	s_lshl_b32 s30, s59, 7
	s_ashr_i32 s31, s30, 31
	s_lshl_b64 s[30:31], s[30:31], 1
	s_add_u32 s30, s60, s30
	s_addc_u32 s31, s61, s31
	s_lshl_b64 s[42:43], s[42:43], 2
	s_add_u32 s60, s5, s42
	s_addc_u32 s61, s7, s43
	s_lshl_b32 s42, s59, 8
	s_ashr_i32 s43, s42, 31
	s_lshl_b64 s[42:43], s[42:43], 2
	s_add_u32 s42, s60, s42
	s_addc_u32 s43, s61, s43
	s_flbit_i32_b32 s59, 0
	s_min_u32 s59, s59, 32
	s_sub_i32 s60, 32, s59
	v_mov_b32_e32 v167, v175
	v_lshl_add_u64 v[146:147], s[30:31], 0, v[166:167]
	s_waitcnt vmcnt(0)
	global_load_dwordx4 v[86:89], v98, s[42:43] offset:16
	global_load_dwordx4 v[102:105], v98, s[42:43]
	global_load_dwordx4 v[82:85], v98, s[42:43] offset:528
	s_nop 0
	global_load_dwordx4 v[98:101], v98, s[42:43] offset:512
	v_mov_b32_e32 v174, v151
	v_cvt_f32_u32_e32 v148, v150
	v_lshlrev_b64 v[150:151], s59, v[174:175]
	v_mov_b32_e32 v174, v153
	v_cvt_f32_u32_e32 v158, v152
	v_min_u32_e32 v150, 1, v150
	v_lshlrev_b64 v[152:153], s59, v[174:175]
	v_mov_b32_e32 v174, v155
	v_or_b32_e32 v155, v151, v150
	v_min_u32_e32 v152, 1, v152
	v_lshlrev_b64 v[150:151], s59, v[174:175]
	v_mov_b32_e32 v174, v157
	v_cvt_f32_u32_e32 v155, v155
	v_or_b32_e32 v157, v153, v152
	v_min_u32_e32 v150, 1, v150
	v_lshlrev_b64 v[152:153], s59, v[174:175]
	v_mov_b32_e32 v174, v179
	v_cvt_f32_u32_e32 v157, v157
	v_or_b32_e32 v162, v151, v150
	v_min_u32_e32 v152, 1, v152
	v_lshlrev_b64 v[150:151], s59, v[174:175]
	v_mov_b32_e32 v174, v181
	v_cvt_f32_u32_e32 v162, v162
	v_or_b32_e32 v164, v153, v152
	v_min_u32_e32 v150, 1, v150
	v_lshlrev_b64 v[152:153], s59, v[174:175]
	v_mov_b32_e32 v174, v183
	v_cvt_f32_u32_e32 v154, v154
	v_cvt_f32_u32_e32 v164, v164
	v_or_b32_e32 v168, v151, v150
	v_lshlrev_b64 v[150:151], s59, v[174:175]
	v_cvt_f32_u32_e32 v156, v156
	v_min_u32_e32 v152, 1, v152
	v_mov_b32_e32 v174, v185
	v_ldexp_f32 v155, v155, s60
	v_cvt_f32_u32_e32 v168, v168
	v_min_u32_e32 v150, 1, v150
	v_cvt_f32_u32_e32 v160, v178
	v_or_b32_e32 v178, v153, v152
	v_lshlrev_b64 v[152:153], s59, v[174:175]
	v_fmac_f32_e32 v148, 0x4f800000, v155
	v_ldexp_f32 v155, v157, s60
	v_or_b32_e32 v150, v151, v150
	v_cvt_f32_u32_e32 v157, v178
	v_min_u32_e32 v151, 1, v152
	v_fmamk_f32 v148, v148, 0x30000000, v231
	v_fmac_f32_e32 v158, 0x4f800000, v155
	v_ldexp_f32 v152, v162, s60
	v_cvt_f32_u32_e32 v150, v150
	v_cvt_f32_u32_e32 v167, v180
	v_cvt_f32_u32_e32 v177, v182
	v_or_b32_e32 v151, v153, v151
	v_rsq_f32_e32 v174, v148
	v_fmamk_f32 v148, v158, 0x30000000, v231
	v_fmac_f32_e32 v154, 0x4f800000, v152
	v_ldexp_f32 v152, v164, s60
	v_cvt_f32_u32_e32 v151, v151
	v_rsq_f32_e32 v178, v148
	v_fmamk_f32 v148, v154, 0x30000000, v231
	v_fmac_f32_e32 v156, 0x4f800000, v152
	v_ldexp_f32 v152, v168, s60
	v_cvt_f32_u32_e32 v188, v184
	v_rsq_f32_e32 v168, v148
	v_fmamk_f32 v148, v156, 0x30000000, v231
	v_fmac_f32_e32 v160, 0x4f800000, v152
	v_ldexp_f32 v152, v157, s60
	v_rsq_f32_e32 v164, v148
	v_fmamk_f32 v148, v160, 0x30000000, v231
	v_ldexp_f32 v150, v150, s60
	v_fmac_f32_e32 v167, 0x4f800000, v152
	v_rsq_f32_e32 v162, v148
	v_fmac_f32_e32 v177, 0x4f800000, v150
	v_mul_f32_e32 v148, 0xbfb8aa3b, v174
	s_mov_b32 s42, 0xbfb8aa3b
	v_fmamk_f32 v152, v167, 0x30000000, v231
	v_ldexp_f32 v150, v151, s60
	v_fmamk_f32 v151, v177, 0x30000000, v231
	v_pk_mul_f32 v[182:183], v[142:143], v[148:149] op_sel_hi:[1,0]
	s_waitcnt vmcnt(2)
	v_pk_mul_f32 v[156:157], v[102:103], s[42:43] op_sel_hi:[1,0]
	v_rsq_f32_e32 v160, v152
	v_fmac_f32_e32 v188, 0x4f800000, v150
	v_pk_mul_f32 v[180:181], v[144:145], v[148:149] op_sel_hi:[1,0]
	v_pk_mul_f32 v[184:185], v[136:137], v[148:149] op_sel_hi:[1,0]
	v_pk_mul_f32 v[186:187], v[134:135], v[148:149] op_sel_hi:[1,0]
	v_rsq_f32_e32 v158, v151
	v_pk_mul_f32 v[154:155], v[104:105], s[42:43] op_sel_hi:[1,0]
	v_pk_mul_f32 v[150:151], v[88:89], s[42:43] op_sel_hi:[1,0]
	v_pk_mul_f32 v[152:153], v[86:87], s[42:43] op_sel_hi:[1,0]
	v_pk_fma_f32 v[144:145], v[144:145], v[174:175], v[104:105] op_sel_hi:[1,0,1]
	v_pk_fma_f32 v[142:143], v[142:143], v[174:175], v[102:103] op_sel_hi:[1,0,1]
	s_waitcnt vmcnt(0)
;     template <int QVV> __device__ __forceinline__ void run(f32x4 (&acc)[2][2][4][2], const Unit& u, int wr, int wc, int fr, int fq) const {
;     ...
; #pragma unroll
;         for (int ai = 0; ai < 2; ++ai)
; #pragma unroll
;             for (int m = 0; m < 4; ++m) { if (ai >= nai) continue;
;                 const float r = rs[ai][m], rn = r * (-LOG2E);
;                 f32x4 o[2];
; #pragma unroll
;                 for (int n = 0; n < 2; ++n) {
;                     const f32x4 gt = acc[ai][0][m][n] * r + sg[n], up = acc[ai][1][m][n] * r + su[n], ex = acc[ai][0][m][n] * rn + sgn[n];
;                     f32x4 den, rc;
; #pragma unroll
;                     for (int i = 0; i < 4; ++i) den[i] = __builtin_amdgcn_exp2f(ex[i]);
;                     den = den + 1.0f;
; #pragma unroll
;                     for (int i = 0; i < 4; ++i) rc[i] = __builtin_amdgcn_rcpf(den[i]);
;                     o[n] = (gt * up) * rc; }
;                 u32x4 w; w.x = pk2(o[0][0], o[0][1]); w.y = pk2(o[0][2], o[0][3]); w.z = pk2(o[1][0], o[1][1]); w.w = pk2(o[1][2], o[1][3]);
;                 *(u32x4*)(tb + lo + (unsigned)(ai * HALF + m * 16) * (DFF * 2)) = w; }
	v_pk_fma_f32 v[140:141], v[140:141], v[174:175], v[100:101] op_sel_hi:[1,0,1]
	v_pk_fma_f32 v[138:139], v[138:139], v[174:175], v[98:99] op_sel_hi:[1,0,1]
	v_pk_fma_f32 v[136:137], v[136:137], v[174:175], v[88:89] op_sel_hi:[1,0,1]
	v_pk_fma_f32 v[134:135], v[134:135], v[174:175], v[86:87] op_sel_hi:[1,0,1]
	v_pk_fma_f32 v[132:133], v[132:133], v[174:175], v[84:85] op_sel_hi:[1,0,1]
	v_pk_fma_f32 v[130:131], v[130:131], v[174:175], v[82:83] op_sel_hi:[1,0,1]
	v_add_f32_e32 v167, v156, v182
	v_add_f32_e32 v174, v157, v183
	v_add_f32_e32 v177, v154, v180
	v_add_f32_e32 v179, v155, v181
	v_pk_mul_f32 v[138:139], v[142:143], v[138:139]
	v_pk_mul_f32 v[140:141], v[144:145], v[140:141]
	v_add_f32_e32 v142, v152, v186
	v_add_f32_e32 v143, v153, v187
	v_add_f32_e32 v144, v150, v184
	v_add_f32_e32 v145, v151, v185
	v_pk_mul_f32 v[130:131], v[134:135], v[130:131]
	v_exp_f32_e32 v134, v167
	v_exp_f32_e32 v135, v174
	v_pk_mul_f32 v[132:133], v[136:137], v[132:133]
	v_exp_f32_e32 v136, v177
	v_exp_f32_e32 v137, v179
	v_exp_f32_e32 v142, v142
	v_exp_f32_e32 v144, v144
	v_exp_f32_e32 v145, v145
	v_exp_f32_e32 v143, v143
	v_pk_add_f32 v[134:135], v[134:135], 1.0 op_sel_hi:[1,0]
	v_pk_add_f32 v[136:137], v[136:137], 1.0 op_sel_hi:[1,0]
	v_pk_add_f32 v[144:145], v[144:145], 1.0 op_sel_hi:[1,0]
	v_pk_add_f32 v[142:143], v[142:143], 1.0 op_sel_hi:[1,0]
	v_rcp_f32_e32 v134, v134
	v_rcp_f32_e32 v135, v135
	v_rcp_f32_e32 v136, v136
	v_rcp_f32_e32 v137, v137
	v_rcp_f32_e32 v142, v142
	v_rcp_f32_e32 v144, v144
	v_rcp_f32_e32 v145, v145
	v_rcp_f32_e32 v143, v143
	v_pk_mul_f32 v[134:135], v[138:139], v[134:135]
	v_pk_mul_f32 v[136:137], v[140:141], v[136:137]
	v_pk_mul_f32 v[138:139], v[132:133], v[144:145]
	v_pk_mul_f32 v[132:133], v[130:131], v[142:143]
	v_cvt_pk_bf16_f32 v130, v134, v135
	v_mul_f32_e32 v134, 0xbfb8aa3b, v178
	v_cvt_pk_bf16_f32 v131, v136, v137
	v_pk_mul_f32 v[136:137], v[128:129], v[134:135] op_sel_hi:[1,0]
	v_pk_mul_f32 v[140:141], v[126:127], v[134:135] op_sel_hi:[1,0]
	v_add_f32_e32 v135, v154, v136
	v_exp_f32_e32 v136, v135
	v_add_f32_e32 v135, v155, v137
	v_pk_fma_f32 v[128:129], v[128:129], v[178:179], v[104:105] op_sel_hi:[1,0,1]
	v_pk_fma_f32 v[126:127], v[126:127], v[178:179], v[102:103] op_sel_hi:[1,0,1]
	v_pk_fma_f32 v[124:125], v[124:125], v[178:179], v[100:101] op_sel_hi:[1,0,1]
	v_pk_fma_f32 v[122:123], v[122:123], v[178:179], v[98:99] op_sel_hi:[1,0,1]
	v_pk_mul_f32 v[124:125], v[128:129], v[124:125]
	v_pk_mul_f32 v[122:123], v[126:127], v[122:123]
	v_pk_mul_f32 v[126:127], v[120:121], v[134:135] op_sel_hi:[1,0]
	v_pk_mul_f32 v[128:129], v[118:119], v[134:135] op_sel_hi:[1,0]
	v_cvt_pk_bf16_f32 v132, v132, v133
	v_add_f32_e32 v133, v156, v140
	v_add_f32_e32 v128, v152, v128
	v_add_f32_e32 v129, v153, v129
	v_add_f32_e32 v126, v150, v126
	v_add_f32_e32 v127, v151, v127
	v_exp_f32_e32 v140, v133
	v_add_f32_e32 v133, v157, v141
	v_exp_f32_e32 v128, v128
	v_exp_f32_e32 v126, v126
	v_exp_f32_e32 v127, v127
	v_exp_f32_e32 v129, v129
	v_exp_f32_e32 v141, v133
	v_cvt_pk_bf16_f32 v133, v138, v139
	v_pk_add_f32 v[126:127], v[126:127], 1.0 op_sel_hi:[1,0]
	v_pk_add_f32 v[128:129], v[128:129], 1.0 op_sel_hi:[1,0]
	global_store_dwordx4 v166, v[130:133], s[30:31]
	v_rcp_f32_e32 v128, v128
	v_rcp_f32_e32 v129, v129
	v_pk_add_f32 v[132:133], v[140:141], 1.0 op_sel_hi:[1,0]
	v_rcp_f32_e32 v126, v126
	v_rcp_f32_e32 v127, v127
	v_rcp_f32_e32 v132, v132
	v_rcp_f32_e32 v133, v133
	v_pk_fma_f32 v[120:121], v[120:121], v[178:179], v[88:89] op_sel_hi:[1,0,1]
	v_pk_fma_f32 v[118:119], v[118:119], v[178:179], v[86:87] op_sel_hi:[1,0,1]
	v_pk_fma_f32 v[116:117], v[116:117], v[178:179], v[84:85] op_sel_hi:[1,0,1]
	v_pk_fma_f32 v[114:115], v[114:115], v[178:179], v[82:83] op_sel_hi:[1,0,1]
	v_pk_mul_f32 v[116:117], v[120:121], v[116:117]
	v_pk_mul_f32 v[114:115], v[118:119], v[114:115]
	v_pk_mul_f32 v[118:119], v[116:117], v[126:127]
	v_pk_mul_f32 v[116:117], v[114:115], v[128:129]
	v_pk_mul_f32 v[122:123], v[122:123], v[132:133]
	v_cvt_pk_bf16_f32 v116, v116, v117
	v_cvt_pk_bf16_f32 v117, v118, v119
	v_mul_f32_e32 v118, 0xbfb8aa3b, v168
	v_exp_f32_e32 v137, v135
	v_cvt_pk_bf16_f32 v114, v122, v123
	v_pk_mul_f32 v[122:123], v[110:111], v[118:119] op_sel_hi:[1,0]
	v_pk_mul_f32 v[120:121], v[112:113], v[118:119] op_sel_hi:[1,0]
	v_add_f32_e32 v119, v156, v122
	v_exp_f32_e32 v122, v119
	v_add_f32_e32 v119, v157, v123
	v_exp_f32_e32 v123, v119
	v_add_f32_e32 v119, v154, v120
	v_pk_add_f32 v[130:131], v[136:137], 1.0 op_sel_hi:[1,0]
	v_exp_f32_e32 v120, v119
	v_add_f32_e32 v119, v155, v121
	v_pk_fma_f32 v[112:113], v[112:113], v[168:169], v[104:105] op_sel_hi:[1,0,1]
	v_pk_fma_f32 v[110:111], v[110:111], v[168:169], v[102:103] op_sel_hi:[1,0,1]
	v_pk_fma_f32 v[108:109], v[108:109], v[168:169], v[100:101] op_sel_hi:[1,0,1]
	v_pk_fma_f32 v[106:107], v[106:107], v[168:169], v[98:99] op_sel_hi:[1,0,1]
	v_rcp_f32_e32 v130, v130
	v_rcp_f32_e32 v131, v131
	v_pk_mul_f32 v[106:107], v[110:111], v[106:107]
	v_pk_mul_f32 v[108:109], v[112:113], v[108:109]
	v_pk_mul_f32 v[110:111], v[96:97], v[118:119] op_sel_hi:[1,0]
	v_pk_mul_f32 v[112:113], v[94:95], v[118:119] op_sel_hi:[1,0]
	v_add_f32_e32 v110, v150, v110
	v_add_f32_e32 v112, v152, v112
	v_add_f32_e32 v113, v153, v113
	v_add_f32_e32 v111, v151, v111
	v_exp_f32_e32 v112, v112
	v_exp_f32_e32 v110, v110
	v_exp_f32_e32 v111, v111
	v_exp_f32_e32 v113, v113
	v_pk_mul_f32 v[124:125], v[124:125], v[130:131]
	s_mov_b32 s30, 0x2b000
	v_cvt_pk_bf16_f32 v115, v124, v125
	v_add_co_u32_e32 v124, vcc, s30, v146
	v_pk_add_f32 v[110:111], v[110:111], 1.0 op_sel_hi:[1,0]
	s_nop 0
	v_addc_co_u32_e32 v125, vcc, 0, v147, vcc
;     template <int QVV> __device__ __forceinline__ void run(f32x4 (&acc)[2][2][4][2], const Unit& u, int wr, int wc, int fr, int fq) const {
;     ...
;         for (int n = 0; n < 2; ++n) { sg[n] = *(const f32x4*)(swb + co + n * 16); su[n] = *(const f32x4*)(swb + co + HALF * 4 + n * 16); sgn[n] = sg[n] * (-LOG2E); }
; #pragma unroll
;         for (int ai = 0; ai < 2; ++ai)
; #pragma unroll
;             for (int m = 0; m < 4; ++m) { if (ai >= nai) continue;
;                 const float r = rs[ai][m], rn = r * (-LOG2E);
;                 f32x4 o[2];
; #pragma unroll
;                 for (int n = 0; n < 2; ++n) {
;                     const f32x4 gt = acc[ai][0][m][n] * r + sg[n], up = acc[ai][1][m][n] * r + su[n], ex = acc[ai][0][m][n] * rn + sgn[n];
;                     f32x4 den, rc;
; #pragma unroll
;                     for (int i = 0; i < 4; ++i) den[i] = __builtin_amdgcn_exp2f(ex[i]);
;                     den = den + 1.0f;
; #pragma unroll
;                     for (int i = 0; i < 4; ++i) rc[i] = __builtin_amdgcn_rcpf(den[i]);
;                     o[n] = (gt * up) * rc; }
;                 u32x4 w; w.x = pk2(o[0][0], o[0][1]); w.y = pk2(o[0][2], o[0][3]); w.z = pk2(o[1][0], o[1][1]); w.w = pk2(o[1][2], o[1][3]);
;                 *(u32x4*)(tb + lo + (unsigned)(ai * HALF + m * 16) * (DFF * 2)) = w; }
	v_pk_add_f32 v[112:113], v[112:113], 1.0 op_sel_hi:[1,0]
	global_store_dwordx4 v[124:125], v[114:117], off
	v_rcp_f32_e32 v112, v112
	v_rcp_f32_e32 v113, v113
	v_pk_add_f32 v[116:117], v[122:123], 1.0 op_sel_hi:[1,0]
	v_rcp_f32_e32 v110, v110
	v_rcp_f32_e32 v111, v111
	v_rcp_f32_e32 v116, v116
	v_rcp_f32_e32 v117, v117
	v_pk_fma_f32 v[96:97], v[96:97], v[168:169], v[88:89] op_sel_hi:[1,0,1]
	v_pk_fma_f32 v[94:95], v[94:95], v[168:169], v[86:87] op_sel_hi:[1,0,1]
	v_pk_fma_f32 v[92:93], v[92:93], v[168:169], v[84:85] op_sel_hi:[1,0,1]
	v_pk_fma_f32 v[90:91], v[90:91], v[168:169], v[82:83] op_sel_hi:[1,0,1]
	v_pk_mul_f32 v[92:93], v[96:97], v[92:93]
	v_pk_mul_f32 v[90:91], v[94:95], v[90:91]
	v_pk_mul_f32 v[94:95], v[92:93], v[110:111]
	v_pk_mul_f32 v[92:93], v[90:91], v[112:113]
	v_pk_mul_f32 v[106:107], v[106:107], v[116:117]
	v_cvt_pk_bf16_f32 v92, v92, v93
	v_cvt_pk_bf16_f32 v93, v94, v95
	v_mul_f32_e32 v94, 0xbfb8aa3b, v164
	v_exp_f32_e32 v121, v119
	v_cvt_pk_bf16_f32 v90, v106, v107
	v_pk_mul_f32 v[106:107], v[78:79], v[94:95] op_sel_hi:[1,0]
	v_pk_mul_f32 v[96:97], v[80:81], v[94:95] op_sel_hi:[1,0]
	v_add_f32_e32 v95, v156, v106
	v_exp_f32_e32 v106, v95
	v_add_f32_e32 v95, v157, v107
	v_exp_f32_e32 v107, v95
	v_add_f32_e32 v95, v154, v96
	v_pk_add_f32 v[114:115], v[120:121], 1.0 op_sel_hi:[1,0]
	v_exp_f32_e32 v96, v95
	v_add_f32_e32 v95, v155, v97
	v_pk_fma_f32 v[80:81], v[80:81], v[164:165], v[104:105] op_sel_hi:[1,0,1]
	v_pk_fma_f32 v[78:79], v[78:79], v[164:165], v[102:103] op_sel_hi:[1,0,1]
	v_pk_fma_f32 v[76:77], v[76:77], v[164:165], v[100:101] op_sel_hi:[1,0,1]
	v_pk_fma_f32 v[74:75], v[74:75], v[164:165], v[98:99] op_sel_hi:[1,0,1]
	v_rcp_f32_e32 v114, v114
	v_rcp_f32_e32 v115, v115
	v_pk_mul_f32 v[74:75], v[78:79], v[74:75]
	v_pk_mul_f32 v[76:77], v[80:81], v[76:77]
	v_pk_mul_f32 v[78:79], v[72:73], v[94:95] op_sel_hi:[1,0]
	v_pk_mul_f32 v[80:81], v[70:71], v[94:95] op_sel_hi:[1,0]
	v_add_f32_e32 v78, v150, v78
	v_add_f32_e32 v80, v152, v80
	v_add_f32_e32 v81, v153, v81
	v_add_f32_e32 v79, v151, v79
	v_exp_f32_e32 v80, v80
	v_exp_f32_e32 v78, v78
	v_exp_f32_e32 v79, v79
	v_exp_f32_e32 v81, v81
	v_pk_mul_f32 v[108:109], v[108:109], v[114:115]
	s_mov_b32 s30, 0x56000
	v_cvt_pk_bf16_f32 v91, v108, v109
	v_add_co_u32_e32 v108, vcc, s30, v146
	v_pk_add_f32 v[78:79], v[78:79], 1.0 op_sel_hi:[1,0]
	s_nop 0
	v_addc_co_u32_e32 v109, vcc, 0, v147, vcc
	v_pk_add_f32 v[80:81], v[80:81], 1.0 op_sel_hi:[1,0]
	global_store_dwordx4 v[108:109], v[90:93], off
	v_rcp_f32_e32 v80, v80
	v_rcp_f32_e32 v81, v81
	v_pk_add_f32 v[92:93], v[106:107], 1.0 op_sel_hi:[1,0]
	v_rcp_f32_e32 v78, v78
	v_rcp_f32_e32 v79, v79
	v_rcp_f32_e32 v92, v92
	v_rcp_f32_e32 v93, v93
	v_pk_fma_f32 v[72:73], v[72:73], v[164:165], v[88:89] op_sel_hi:[1,0,1]
	v_pk_fma_f32 v[70:71], v[70:71], v[164:165], v[86:87] op_sel_hi:[1,0,1]
	v_pk_fma_f32 v[68:69], v[68:69], v[164:165], v[84:85] op_sel_hi:[1,0,1]
	v_pk_fma_f32 v[66:67], v[66:67], v[164:165], v[82:83] op_sel_hi:[1,0,1]
	v_pk_mul_f32 v[68:69], v[72:73], v[68:69]
	v_pk_mul_f32 v[66:67], v[70:71], v[66:67]
	v_pk_mul_f32 v[70:71], v[68:69], v[78:79]
	v_pk_mul_f32 v[68:69], v[66:67], v[80:81]
	v_pk_mul_f32 v[74:75], v[74:75], v[92:93]
	v_cvt_pk_bf16_f32 v68, v68, v69
	v_cvt_pk_bf16_f32 v69, v70, v71
	v_mul_f32_e32 v70, 0xbfb8aa3b, v162
	v_exp_f32_e32 v97, v95
	v_cvt_pk_bf16_f32 v66, v74, v75
	v_pk_mul_f32 v[74:75], v[62:63], v[70:71] op_sel_hi:[1,0]
	v_pk_mul_f32 v[72:73], v[64:65], v[70:71] op_sel_hi:[1,0]
	v_add_f32_e32 v71, v156, v74
	v_exp_f32_e32 v74, v71
	v_add_f32_e32 v71, v157, v75
	v_exp_f32_e32 v75, v71
	v_add_f32_e32 v71, v154, v72
	v_pk_add_f32 v[90:91], v[96:97], 1.0 op_sel_hi:[1,0]
	v_exp_f32_e32 v72, v71
	v_add_f32_e32 v71, v155, v73
	v_pk_fma_f32 v[64:65], v[64:65], v[162:163], v[104:105] op_sel_hi:[1,0,1]
	v_pk_fma_f32 v[62:63], v[62:63], v[162:163], v[102:103] op_sel_hi:[1,0,1]
	v_pk_fma_f32 v[60:61], v[60:61], v[162:163], v[100:101] op_sel_hi:[1,0,1]
	v_pk_fma_f32 v[58:59], v[58:59], v[162:163], v[98:99] op_sel_hi:[1,0,1]
	v_rcp_f32_e32 v90, v90
	v_rcp_f32_e32 v91, v91
	v_pk_mul_f32 v[58:59], v[62:63], v[58:59]
	v_pk_mul_f32 v[60:61], v[64:65], v[60:61]
	v_pk_mul_f32 v[62:63], v[56:57], v[70:71] op_sel_hi:[1,0]
	v_pk_mul_f32 v[64:65], v[54:55], v[70:71] op_sel_hi:[1,0]
	v_add_f32_e32 v62, v150, v62
	v_add_f32_e32 v64, v152, v64
	v_add_f32_e32 v65, v153, v65
	v_add_f32_e32 v63, v151, v63
	v_exp_f32_e32 v64, v64
	v_exp_f32_e32 v62, v62
	v_exp_f32_e32 v63, v63
	v_exp_f32_e32 v65, v65
	v_pk_mul_f32 v[76:77], v[76:77], v[90:91]
	s_mov_b32 s30, 0x81000
	v_cvt_pk_bf16_f32 v67, v76, v77
	v_add_co_u32_e32 v76, vcc, s30, v146
	v_pk_add_f32 v[62:63], v[62:63], 1.0 op_sel_hi:[1,0]
	s_nop 0
	v_addc_co_u32_e32 v77, vcc, 0, v147, vcc
	v_pk_add_f32 v[64:65], v[64:65], 1.0 op_sel_hi:[1,0]
	global_store_dwordx4 v[76:77], v[66:69], off
	v_rcp_f32_e32 v64, v64
	v_rcp_f32_e32 v65, v65
	v_pk_add_f32 v[68:69], v[74:75], 1.0 op_sel_hi:[1,0]
	v_rcp_f32_e32 v62, v62
	v_rcp_f32_e32 v63, v63
	v_rcp_f32_e32 v68, v68
	v_rcp_f32_e32 v69, v69
	v_pk_fma_f32 v[56:57], v[56:57], v[162:163], v[88:89] op_sel_hi:[1,0,1]
	v_pk_fma_f32 v[54:55], v[54:55], v[162:163], v[86:87] op_sel_hi:[1,0,1]
	v_pk_fma_f32 v[52:53], v[52:53], v[162:163], v[84:85] op_sel_hi:[1,0,1]
	v_pk_fma_f32 v[50:51], v[50:51], v[162:163], v[82:83] op_sel_hi:[1,0,1]
	v_pk_mul_f32 v[52:53], v[56:57], v[52:53]
	v_pk_mul_f32 v[50:51], v[54:55], v[50:51]
	v_pk_mul_f32 v[54:55], v[52:53], v[62:63]
	v_pk_mul_f32 v[52:53], v[50:51], v[64:65]
	v_pk_mul_f32 v[58:59], v[58:59], v[68:69]
	v_cvt_pk_bf16_f32 v52, v52, v53
	v_cvt_pk_bf16_f32 v53, v54, v55
	v_mul_f32_e32 v54, 0xbfb8aa3b, v160
;     template <int QVV> __device__ __forceinline__ void run(f32x4 (&acc)[2][2][4][2], const Unit& u, int wr, int wc, int fr, int fq) const {
;     ...
;         for (int ai = 0; ai < 2; ++ai)
; #pragma unroll
;             for (int m = 0; m < 4; ++m) { if (ai >= nai) continue;
;                 const float r = rs[ai][m], rn = r * (-LOG2E);
;                 f32x4 o[2];
; #pragma unroll
;                 for (int n = 0; n < 2; ++n) {
;                     const f32x4 gt = acc[ai][0][m][n] * r + sg[n], up = acc[ai][1][m][n] * r + su[n], ex = acc[ai][0][m][n] * rn + sgn[n];
;                     f32x4 den, rc;
; #pragma unroll
;                     for (int i = 0; i < 4; ++i) den[i] = __builtin_amdgcn_exp2f(ex[i]);
;                     den = den + 1.0f;
; #pragma unroll
;                     for (int i = 0; i < 4; ++i) rc[i] = __builtin_amdgcn_rcpf(den[i]);
;                     o[n] = (gt * up) * rc; }
;                 u32x4 w; w.x = pk2(o[0][0], o[0][1]); w.y = pk2(o[0][2], o[0][3]); w.z = pk2(o[1][0], o[1][1]); w.w = pk2(o[1][2], o[1][3]);
;                 *(u32x4*)(tb + lo + (unsigned)(ai * HALF + m * 16) * (DFF * 2)) = w; }
	v_exp_f32_e32 v73, v71
	v_cvt_pk_bf16_f32 v50, v58, v59
	v_pk_mul_f32 v[58:59], v[46:47], v[54:55] op_sel_hi:[1,0]
	v_pk_mul_f32 v[56:57], v[48:49], v[54:55] op_sel_hi:[1,0]
	v_add_f32_e32 v55, v156, v58
	v_exp_f32_e32 v58, v55
	v_add_f32_e32 v55, v157, v59
	v_exp_f32_e32 v59, v55
	v_add_f32_e32 v55, v154, v56
	v_pk_add_f32 v[66:67], v[72:73], 1.0 op_sel_hi:[1,0]
	v_exp_f32_e32 v56, v55
	v_add_f32_e32 v55, v155, v57
	v_pk_fma_f32 v[48:49], v[48:49], v[160:161], v[104:105] op_sel_hi:[1,0,1]
	v_pk_fma_f32 v[46:47], v[46:47], v[160:161], v[102:103] op_sel_hi:[1,0,1]
	v_pk_fma_f32 v[44:45], v[44:45], v[160:161], v[100:101] op_sel_hi:[1,0,1]
	v_pk_fma_f32 v[42:43], v[42:43], v[160:161], v[98:99] op_sel_hi:[1,0,1]
	v_rcp_f32_e32 v66, v66
	v_rcp_f32_e32 v67, v67
	v_pk_mul_f32 v[42:43], v[46:47], v[42:43]
	v_pk_mul_f32 v[44:45], v[48:49], v[44:45]
	v_pk_mul_f32 v[46:47], v[40:41], v[54:55] op_sel_hi:[1,0]
	v_pk_mul_f32 v[48:49], v[38:39], v[54:55] op_sel_hi:[1,0]
	v_add_f32_e32 v46, v150, v46
	v_add_f32_e32 v48, v152, v48
	v_add_f32_e32 v49, v153, v49
	v_add_f32_e32 v47, v151, v47
	v_exp_f32_e32 v48, v48
	v_exp_f32_e32 v46, v46
	v_exp_f32_e32 v47, v47
	v_exp_f32_e32 v49, v49
	v_pk_mul_f32 v[60:61], v[60:61], v[66:67]
	s_mov_b32 s30, 0x158000
	v_cvt_pk_bf16_f32 v51, v60, v61
	v_add_co_u32_e32 v60, vcc, s30, v146
	v_pk_add_f32 v[46:47], v[46:47], 1.0 op_sel_hi:[1,0]
	s_nop 0
	v_addc_co_u32_e32 v61, vcc, 0, v147, vcc
	v_pk_add_f32 v[48:49], v[48:49], 1.0 op_sel_hi:[1,0]
	global_store_dwordx4 v[60:61], v[50:53], off
	v_rcp_f32_e32 v48, v48
	v_rcp_f32_e32 v49, v49
	v_pk_add_f32 v[52:53], v[58:59], 1.0 op_sel_hi:[1,0]
	v_rcp_f32_e32 v46, v46
	v_rcp_f32_e32 v47, v47
	v_rcp_f32_e32 v52, v52
	v_rcp_f32_e32 v53, v53
	v_pk_fma_f32 v[40:41], v[40:41], v[160:161], v[88:89] op_sel_hi:[1,0,1]
	v_pk_fma_f32 v[38:39], v[38:39], v[160:161], v[86:87] op_sel_hi:[1,0,1]
	v_pk_fma_f32 v[36:37], v[36:37], v[160:161], v[84:85] op_sel_hi:[1,0,1]
	v_pk_fma_f32 v[34:35], v[34:35], v[160:161], v[82:83] op_sel_hi:[1,0,1]
	v_pk_mul_f32 v[36:37], v[40:41], v[36:37]
	v_pk_mul_f32 v[34:35], v[38:39], v[34:35]
	v_pk_mul_f32 v[38:39], v[36:37], v[46:47]
	v_pk_mul_f32 v[36:37], v[34:35], v[48:49]
	v_pk_mul_f32 v[42:43], v[42:43], v[52:53]
	v_cvt_pk_bf16_f32 v36, v36, v37
	v_cvt_pk_bf16_f32 v37, v38, v39
	v_mul_f32_e32 v38, 0xbfb8aa3b, v158
	v_exp_f32_e32 v57, v55
	v_cvt_pk_bf16_f32 v34, v42, v43
	v_pk_mul_f32 v[42:43], v[30:31], v[38:39] op_sel_hi:[1,0]
	v_pk_mul_f32 v[40:41], v[32:33], v[38:39] op_sel_hi:[1,0]
	v_add_f32_e32 v39, v156, v42
	v_exp_f32_e32 v42, v39
	v_add_f32_e32 v39, v157, v43
	v_exp_f32_e32 v43, v39
	v_add_f32_e32 v39, v154, v40
	v_pk_add_f32 v[50:51], v[56:57], 1.0 op_sel_hi:[1,0]
	v_exp_f32_e32 v40, v39
	v_add_f32_e32 v39, v155, v41
	v_pk_fma_f32 v[32:33], v[32:33], v[158:159], v[104:105] op_sel_hi:[1,0,1]
	v_pk_fma_f32 v[30:31], v[30:31], v[158:159], v[102:103] op_sel_hi:[1,0,1]
	v_pk_fma_f32 v[28:29], v[28:29], v[158:159], v[100:101] op_sel_hi:[1,0,1]
	v_pk_fma_f32 v[26:27], v[26:27], v[158:159], v[98:99] op_sel_hi:[1,0,1]
	v_rcp_f32_e32 v50, v50
	v_rcp_f32_e32 v51, v51
	v_pk_mul_f32 v[26:27], v[30:31], v[26:27]
	v_pk_mul_f32 v[28:29], v[32:33], v[28:29]
	v_pk_mul_f32 v[30:31], v[24:25], v[38:39] op_sel_hi:[1,0]
	v_pk_mul_f32 v[32:33], v[22:23], v[38:39] op_sel_hi:[1,0]
	v_add_f32_e32 v30, v150, v30
	v_add_f32_e32 v32, v152, v32
	v_add_f32_e32 v33, v153, v33
	v_add_f32_e32 v31, v151, v31
	v_exp_f32_e32 v32, v32
	v_exp_f32_e32 v30, v30
	v_exp_f32_e32 v31, v31
	v_exp_f32_e32 v33, v33
	v_pk_mul_f32 v[44:45], v[44:45], v[50:51]
	s_mov_b32 s30, 0x183000
	v_cvt_pk_bf16_f32 v35, v44, v45
	v_add_co_u32_e32 v44, vcc, s30, v146
	v_pk_add_f32 v[30:31], v[30:31], 1.0 op_sel_hi:[1,0]
	s_nop 0
	v_addc_co_u32_e32 v45, vcc, 0, v147, vcc
; #define PG8_BAR __builtin_amdgcn_s_barrier()
;     ...
;         if (!has_next) break;
;         if (!cur.keep) {
; #pragma unroll
;             for (int a = 0; a < 2; ++a)
; #pragma unroll
;                 for (int b = 0; b < 2; ++b)
; #pragma unroll
;                     for (int m = 0; m < 4; ++m)
; #pragma unroll
;                         for (int n = 0; n < 2; ++n) { f32x2 z0, z1; asm("v_mov_b64 %0, 0\n\tv_mov_b64 %1, 0" : "=v"(z0), "=v"(z1));
;                     acc[a][b][m][n] = __builtin_shufflevector(z0, z1, 0, 1, 2, 3); }
;         }
;         cur = nxt; cA = nA; cB = nB; ++ui;
;         if (wr == 1) PG8_BAR;
;     template <int QVV> __device__ __forceinline__ void run(f32x4 (&acc)[2][2][4][2], const Unit& u, int wr, int wc, int fr, int fq) const {
;     ...
;         for (int ai = 0; ai < 2; ++ai)
; #pragma unroll
;             for (int m = 0; m < 4; ++m) { if (ai >= nai) continue;
;                 const float r = rs[ai][m], rn = r * (-LOG2E);
;                 f32x4 o[2];
; #pragma unroll
;                 for (int n = 0; n < 2; ++n) {
;                     const f32x4 gt = acc[ai][0][m][n] * r + sg[n], up = acc[ai][1][m][n] * r + su[n], ex = acc[ai][0][m][n] * rn + sgn[n];
;                     f32x4 den, rc;
; #pragma unroll
;                     for (int i = 0; i < 4; ++i) den[i] = __builtin_amdgcn_exp2f(ex[i]);
;                     den = den + 1.0f;
; #pragma unroll
;                     for (int i = 0; i < 4; ++i) rc[i] = __builtin_amdgcn_rcpf(den[i]);
;                     o[n] = (gt * up) * rc; }
;                 u32x4 w; w.x = pk2(o[0][0], o[0][1]); w.y = pk2(o[0][2], o[0][3]); w.z = pk2(o[1][0], o[1][1]); w.w = pk2(o[1][2], o[1][3]);
;                 *(u32x4*)(tb + lo + (unsigned)(ai * HALF + m * 16) * (DFF * 2)) = w; }
	v_pk_add_f32 v[32:33], v[32:33], 1.0 op_sel_hi:[1,0]
	v_fmamk_f32 v148, v188, 0x30000000, v231
	global_store_dwordx4 v[44:45], v[34:37], off
	v_rcp_f32_e32 v32, v32
	v_rcp_f32_e32 v33, v33
	v_pk_add_f32 v[36:37], v[42:43], 1.0 op_sel_hi:[1,0]
	v_rcp_f32_e32 v30, v30
	v_rcp_f32_e32 v31, v31
	v_rsq_f32_e32 v148, v148
	v_rcp_f32_e32 v36, v36
	v_rcp_f32_e32 v37, v37
	v_pk_fma_f32 v[24:25], v[24:25], v[158:159], v[88:89] op_sel_hi:[1,0,1]
	v_pk_fma_f32 v[22:23], v[22:23], v[158:159], v[86:87] op_sel_hi:[1,0,1]
	v_pk_fma_f32 v[20:21], v[20:21], v[158:159], v[84:85] op_sel_hi:[1,0,1]
	v_pk_fma_f32 v[18:19], v[18:19], v[158:159], v[82:83] op_sel_hi:[1,0,1]
	v_pk_mul_f32 v[20:21], v[24:25], v[20:21]
	v_pk_mul_f32 v[18:19], v[22:23], v[18:19]
	v_pk_mul_f32 v[22:23], v[20:21], v[30:31]
	v_pk_mul_f32 v[20:21], v[18:19], v[32:33]
	v_pk_mul_f32 v[26:27], v[26:27], v[36:37]
	v_cvt_pk_bf16_f32 v20, v20, v21
	v_cvt_pk_bf16_f32 v21, v22, v23
	v_mul_f32_e32 v22, 0xbfb8aa3b, v148
	v_cvt_pk_bf16_f32 v18, v26, v27
	v_pk_mul_f32 v[26:27], v[14:15], v[22:23] op_sel_hi:[1,0]
	v_exp_f32_e32 v41, v39
	v_pk_mul_f32 v[24:25], v[16:17], v[22:23] op_sel_hi:[1,0]
	v_add_f32_e32 v23, v156, v26
	v_exp_f32_e32 v26, v23
	v_add_f32_e32 v23, v157, v27
	v_exp_f32_e32 v27, v23
	v_add_f32_e32 v23, v154, v24
	v_exp_f32_e32 v24, v23
	v_add_f32_e32 v23, v155, v25
	v_pk_fma_f32 v[16:17], v[16:17], v[148:149], v[104:105] op_sel_hi:[1,0,1]
	v_pk_fma_f32 v[14:15], v[14:15], v[148:149], v[102:103] op_sel_hi:[1,0,1]
	v_pk_fma_f32 v[12:13], v[12:13], v[148:149], v[100:101] op_sel_hi:[1,0,1]
	v_pk_fma_f32 v[10:11], v[10:11], v[148:149], v[98:99] op_sel_hi:[1,0,1]
	v_pk_add_f32 v[34:35], v[40:41], 1.0 op_sel_hi:[1,0]
	v_pk_mul_f32 v[10:11], v[14:15], v[10:11]
	v_pk_mul_f32 v[12:13], v[16:17], v[12:13]
	v_pk_mul_f32 v[14:15], v[8:9], v[22:23] op_sel_hi:[1,0]
	v_pk_mul_f32 v[16:17], v[6:7], v[22:23] op_sel_hi:[1,0]
	v_rcp_f32_e32 v34, v34
	v_rcp_f32_e32 v35, v35
	v_add_f32_e32 v16, v152, v16
	v_add_f32_e32 v17, v153, v17
	v_add_f32_e32 v14, v150, v14
	v_add_f32_e32 v15, v151, v15
	v_exp_f32_e32 v16, v16
	v_exp_f32_e32 v14, v14
	v_exp_f32_e32 v15, v15
	v_exp_f32_e32 v17, v17
	v_exp_f32_e32 v25, v23
	v_pk_mul_f32 v[28:29], v[28:29], v[34:35]
	s_mov_b32 s30, 0x1ae000
	v_cvt_pk_bf16_f32 v19, v28, v29
	v_add_co_u32_e32 v28, vcc, s30, v146
	v_pk_add_f32 v[14:15], v[14:15], 1.0 op_sel_hi:[1,0]
	v_pk_add_f32 v[16:17], v[16:17], 1.0 op_sel_hi:[1,0]
	v_addc_co_u32_e32 v29, vcc, 0, v147, vcc
	v_rcp_f32_e32 v16, v16
	v_rcp_f32_e32 v17, v17
	v_rcp_f32_e32 v14, v14
	v_rcp_f32_e32 v15, v15
	global_store_dwordx4 v[28:29], v[18:21], off
	v_pk_fma_f32 v[8:9], v[8:9], v[148:149], v[88:89] op_sel_hi:[1,0,1]
	v_pk_fma_f32 v[6:7], v[6:7], v[148:149], v[86:87] op_sel_hi:[1,0,1]
	v_pk_add_f32 v[18:19], v[24:25], 1.0 op_sel_hi:[1,0]
	v_pk_add_f32 v[20:21], v[26:27], 1.0 op_sel_hi:[1,0]
	v_rcp_f32_e32 v18, v18
	v_rcp_f32_e32 v20, v20
	v_rcp_f32_e32 v21, v21
	v_rcp_f32_e32 v19, v19
	v_pk_fma_f32 v[4:5], v[4:5], v[148:149], v[84:85] op_sel_hi:[1,0,1]
	v_pk_fma_f32 v[2:3], v[2:3], v[148:149], v[82:83] op_sel_hi:[1,0,1]
	v_pk_mul_f32 v[4:5], v[8:9], v[4:5]
	v_pk_mul_f32 v[2:3], v[6:7], v[2:3]
	v_pk_mul_f32 v[6:7], v[4:5], v[14:15]
	v_pk_mul_f32 v[4:5], v[2:3], v[16:17]
	v_pk_mul_f32 v[12:13], v[12:13], v[18:19]
	v_cvt_pk_bf16_f32 v4, v4, v5
	v_cvt_pk_bf16_f32 v5, v6, v7
	v_add_co_u32_e32 v6, vcc, 0x1d9000, v146
	v_pk_mul_f32 v[10:11], v[10:11], v[20:21]
	s_nop 0
	v_addc_co_u32_e32 v7, vcc, 0, v147, vcc
	v_cvt_pk_bf16_f32 v2, v10, v11
	v_cvt_pk_bf16_f32 v3, v12, v13
	s_andn2_b64 vcc, exec, s[38:39]
	s_mov_b64 s[30:31], -1
	global_store_dwordx4 v[6:7], v[2:5], off
	s_cbranch_vccnz .LBB0_1643
	s_andn2_b64 vcc, exec, s[46:47]
	v_mov_b64 v[2:3], 0
	v_mov_b64 v[4:5], 0
	s_cbranch_vccnz .LBB0_1642
	s_branch .LBB0_1642
